# score R-merge via v_med3 insertion plus strict-order check; on ties the wave redoes the merge with exact compare-exchange chains (results identical to baseline)
# baseline (speedup 1.0000x reference)
; DEV int tidx() { int t = threadIdx.x; asm volatile("" : "+v"(t)); return t; }
; DEV f32x4 mfma16(bf16x8 a, bf16x8 b, f32x4 c) { return __builtin_amdgcn_mfma_f32_16x16x32_bf16(a, b, c, 0, 0, 0); }
; DEV void peer_top16(const bf16_t* __restrict__ pq, const bf16_t* sk  , float (&l)[16]) {
;   const int lane = tidx() & 63, l15 = lane & 15, quad = lane >> 4;
;   f32x4 acc[8];
; #pragma unroll
;   for (int nt = 0; nt < 8; nt++) acc[nt] = (f32x4){0.f, 0.f, 0.f, 0.f};
; #pragma unroll 1
;   for (int ks = 0; ks < 4; ks++) {
;     const bf16x8 bqk = *(const bf16x8*)(pq + ks * 32 + quad * 8);
; #pragma unroll
;     for (int nt = 0; nt < 8; nt++) {
;       bf16x8 ak = *(const bf16x8*)(sk + (nt * 16 + l15) * 144 + ks * 32 + quad * 8);
;       acc[nt] = mfma16(ak, bqk, acc[nt]);
;     }
;   }
.LBB0_170:
	v_add_u32_e32 v139, 0x10e00, v122
	ds_read_b128 v[164:167], v122 offset:36864
	ds_read_b128 v[168:171], v122 offset:41472
	ds_read_b128 v[172:175], v122 offset:46080
	ds_read_b128 v[176:179], v122 offset:50688
	ds_read_b128 v[180:183], v122 offset:55296
	ds_read_b128 v[184:187], v122 offset:59904
	ds_read_b128 v[188:191], v122 offset:64512
	ds_read_b128 v[128:131], v139
	s_waitcnt vmcnt(3) lgkmcnt(7)
	v_mfma_f32_16x16x32_bf16 v[30:33], v[164:167], v[148:151], v[30:33]
	ds_read_b128 v[164:167], v122 offset:36928
	s_waitcnt lgkmcnt(7)
	v_mfma_f32_16x16x32_bf16 v[22:25], v[168:171], v[148:151], v[22:25]
	ds_read_b128 v[168:171], v122 offset:41536
	s_waitcnt lgkmcnt(7)
	v_mfma_f32_16x16x32_bf16 v[14:17], v[172:175], v[148:151], v[14:17]
	ds_read_b128 v[172:175], v122 offset:46144
	s_waitcnt lgkmcnt(7)
	v_mfma_f32_16x16x32_bf16 v[6:9], v[176:179], v[148:151], v[6:9]
	ds_read_b128 v[176:179], v122 offset:50752
	s_waitcnt lgkmcnt(7)
	v_mfma_f32_16x16x32_bf16 v[26:29], v[180:183], v[148:151], v[26:29]
	ds_read_b128 v[180:183], v122 offset:55360
	s_waitcnt lgkmcnt(7)
	v_mfma_f32_16x16x32_bf16 v[18:21], v[184:187], v[148:151], v[18:21]
	ds_read_b128 v[184:187], v122 offset:59968
	s_waitcnt lgkmcnt(7)
	v_mfma_f32_16x16x32_bf16 v[10:13], v[188:191], v[148:151], v[10:13]
	ds_read_b128 v[188:191], v122 offset:64576
	s_waitcnt lgkmcnt(7)
	v_mfma_f32_16x16x32_bf16 v[2:5], v[128:131], v[148:151], v[2:5]
	ds_read_b128 v[128:131], v139 offset:64
	s_waitcnt vmcnt(2) lgkmcnt(7)
	v_mfma_f32_16x16x32_bf16 v[30:33], v[164:167], v[152:155], v[30:33]
	ds_read_b128 v[164:167], v122 offset:36992
	s_waitcnt lgkmcnt(7)
	v_mfma_f32_16x16x32_bf16 v[22:25], v[168:171], v[152:155], v[22:25]
	ds_read_b128 v[168:171], v122 offset:41600
	s_waitcnt lgkmcnt(7)
	v_mfma_f32_16x16x32_bf16 v[14:17], v[172:175], v[152:155], v[14:17]
	ds_read_b128 v[172:175], v122 offset:46208
	s_waitcnt lgkmcnt(7)
	v_mfma_f32_16x16x32_bf16 v[6:9], v[176:179], v[152:155], v[6:9]
	ds_read_b128 v[176:179], v122 offset:50816
	s_waitcnt lgkmcnt(7)
	v_mfma_f32_16x16x32_bf16 v[26:29], v[180:183], v[152:155], v[26:29]
	ds_read_b128 v[180:183], v122 offset:55424
	s_waitcnt lgkmcnt(7)
	v_mfma_f32_16x16x32_bf16 v[18:21], v[184:187], v[152:155], v[18:21]
	ds_read_b128 v[184:187], v122 offset:60032
	s_waitcnt lgkmcnt(7)
	v_mfma_f32_16x16x32_bf16 v[10:13], v[188:191], v[152:155], v[10:13]
	ds_read_b128 v[188:191], v122 offset:64640
	s_waitcnt lgkmcnt(7)
	v_mfma_f32_16x16x32_bf16 v[2:5], v[128:131], v[152:155], v[2:5]
	ds_read_b128 v[128:131], v139 offset:128
	s_waitcnt vmcnt(1) lgkmcnt(7)
	v_mfma_f32_16x16x32_bf16 v[30:33], v[164:167], v[156:159], v[30:33]
	ds_read_b128 v[164:167], v122 offset:37056
	s_waitcnt lgkmcnt(7)
	v_mfma_f32_16x16x32_bf16 v[22:25], v[168:171], v[156:159], v[22:25]
	ds_read_b128 v[168:171], v122 offset:41664
	s_waitcnt lgkmcnt(7)
	v_mfma_f32_16x16x32_bf16 v[14:17], v[172:175], v[156:159], v[14:17]
	ds_read_b128 v[172:175], v122 offset:46272
	s_waitcnt lgkmcnt(7)
	v_mfma_f32_16x16x32_bf16 v[6:9], v[176:179], v[156:159], v[6:9]
	ds_read_b128 v[176:179], v122 offset:50880
	s_waitcnt lgkmcnt(7)
	v_mfma_f32_16x16x32_bf16 v[26:29], v[180:183], v[156:159], v[26:29]
	ds_read_b128 v[180:183], v122 offset:55488
	s_waitcnt lgkmcnt(7)
	v_mfma_f32_16x16x32_bf16 v[18:21], v[184:187], v[156:159], v[18:21]
	ds_read_b128 v[184:187], v122 offset:60096
	s_waitcnt lgkmcnt(7)
	v_mfma_f32_16x16x32_bf16 v[10:13], v[188:191], v[156:159], v[10:13]
	ds_read_b128 v[188:191], v122 offset:64704
	s_waitcnt lgkmcnt(7)
	v_mfma_f32_16x16x32_bf16 v[2:5], v[128:131], v[156:159], v[2:5]
	ds_read_b128 v[128:131], v139 offset:192
	s_waitcnt vmcnt(0) lgkmcnt(7)
	v_mfma_f32_16x16x32_bf16 v[30:33], v[164:167], v[160:163], v[30:33]
	s_waitcnt lgkmcnt(6)
	v_mfma_f32_16x16x32_bf16 v[22:25], v[168:171], v[160:163], v[22:25]
	s_waitcnt lgkmcnt(5)
	v_mfma_f32_16x16x32_bf16 v[14:17], v[172:175], v[160:163], v[14:17]
	s_waitcnt lgkmcnt(4)
	v_mfma_f32_16x16x32_bf16 v[6:9], v[176:179], v[160:163], v[6:9]
	s_waitcnt lgkmcnt(3)
	v_mfma_f32_16x16x32_bf16 v[26:29], v[180:183], v[160:163], v[26:29]
	s_waitcnt lgkmcnt(2)
	v_mfma_f32_16x16x32_bf16 v[18:21], v[184:187], v[160:163], v[18:21]
	s_waitcnt lgkmcnt(1)
	v_mfma_f32_16x16x32_bf16 v[10:13], v[188:191], v[160:163], v[10:13]
	s_waitcnt lgkmcnt(0)
; DEV void merge_xor(float (&l)[16], int mask) {
;   float t[16];
; #pragma unroll
;   for (int i = 0; i < 16; i++) t[i] = __shfl_xor(l[15 - i], mask);
; #pragma unroll
;   for (int i = 0; i < 16; i++) l[i] = fmaxf(l[i], t[i]);
;   bitonic16(l);
; DEV void peer_top16(const bf16_t* __restrict__ pq, const bf16_t* sk  , float (&l)[16]) {
;     ...
;   float hi[16];
; #pragma unroll
;   for (int nt = 0; nt < 4; nt++)
; #pragma unroll
;     for (int r = 0; r < 4; r++) {
;       l[nt * 4 + r] = __uint_as_float((__float_as_uint(acc[nt][r]) & ~127u) | (unsigned)(nt * 16 + quad * 4 + r));
;       hi[nt * 4 + r] = __uint_as_float((__float_as_uint(acc[nt + 4][r]) & ~127u) | (unsigned)((nt + 4) * 16 + quad * 4 + r));
;     }
;   sort16_desc(l);
;   sort16_desc(hi);
	v_mfma_f32_16x16x32_bf16 v[2:5], v[128:131], v[160:163], v[2:5]
	s_movk_i32 s0, 0x100
	v_max_f32_e32 v0, v109, v121
	v_max_f32_e32 v100, v107, v120
	v_max_f32_e32 v101, v105, v119
	v_max_f32_e32 v103, v103, v118
	v_max_f32_e32 v87, v87, v116
	v_max_f32_e32 v79, v79, v115
	v_max_f32_e32 v75, v75, v114
	v_max_f32_e32 v71, v71, v113
	v_max_f32_e32 v67, v67, v112
	v_max_f32_e32 v63, v63, v111
	v_max_f32_e32 v59, v59, v110
	v_max_f32_e32 v55, v55, v108
	v_max_f32_e32 v51, v51, v106
	v_max_f32_e32 v47, v47, v104
	v_max_f32_e32 v43, v43, v91
	v_max_f32_e32 v39, v39, v83
	v_max_f32_e32 v83, v0, v67
	v_min_f32_e32 v0, v0, v67
	v_max_f32_e32 v67, v100, v63
	v_min_f32_e32 v63, v100, v63
	v_max_f32_e32 v91, v101, v59
	v_min_f32_e32 v59, v101, v59
	v_max_f32_e32 v100, v103, v55
	v_min_f32_e32 v55, v103, v55
	v_max_f32_e32 v101, v87, v51
	v_min_f32_e32 v51, v87, v51
	v_max_f32_e32 v87, v79, v47
	v_min_f32_e32 v47, v79, v47
	v_max_f32_e32 v79, v75, v43
	v_min_f32_e32 v43, v75, v43
	v_max_f32_e32 v75, v71, v39
	v_min_f32_e32 v39, v71, v39
	v_max_f32_e32 v71, v83, v101
	v_min_f32_e32 v101, v83, v101
	v_max_f32_e32 v103, v67, v87
	v_min_f32_e32 v67, v67, v87
	v_max_f32_e32 v87, v91, v79
	v_min_f32_e32 v79, v91, v79
	v_max_f32_e32 v91, v100, v75
	v_min_f32_e32 v75, v100, v75
	v_max_f32_e32 v100, v0, v51
	v_min_f32_e32 v0, v0, v51
	v_max_f32_e32 v51, v63, v47
	v_max_f32_e32 v105, v59, v43
	v_min_f32_e32 v43, v59, v43
	v_max_f32_e32 v59, v55, v39
	v_min_f32_e32 v107, v101, v79
	v_min_f32_e32 v108, v67, v75
	v_min_f32_e32 v110, v51, v59
	v_max_f32_e32 v79, v101, v79
	v_max_f32_e32 v67, v67, v75
	v_max_f32_e32 v101, v100, v105
	v_max_f32_e32 v51, v51, v59
	v_min_f32_e32 v75, v79, v67
	v_min_f32_e32 v59, v101, v51
	v_max_f32_e32 v79, v79, v67
	v_max_f32_e32 v67, v101, v51
	v_lshlrev_b32_e32 v101, 2, v102
	s_movk_i32 s0, 0xff80
	v_and_or_b32 v30, v30, s0, v101
	v_and_b32_e32 v27, 0xffffff80, v27
	s_movk_i32 s0, 0x41
	v_or3_b32 v27, v101, v27, s0
	v_and_b32_e32 v28, 0xffffff80, v28
	s_movk_i32 s0, 0x42
	v_or3_b32 v28, v101, v28, s0
	v_and_b32_e32 v29, 0xffffff80, v29
	s_movk_i32 s0, 0x43
	v_or3_b32 v29, v101, v29, s0
	v_and_b32_e32 v18, 0xffffff80, v18
	s_movk_i32 s0, 0x50
	v_or3_b32 v18, v101, v18, s0
	v_and_b32_e32 v19, 0xffffff80, v19
	s_movk_i32 s0, 0x51
	v_or3_b32 v19, v101, v19, s0
	v_and_b32_e32 v20, 0xffffff80, v20
	s_movk_i32 s0, 0x52
	v_or3_b32 v20, v101, v20, s0
	v_and_b32_e32 v21, 0xffffff80, v21
	s_movk_i32 s0, 0x53
	v_or3_b32 v21, v101, v21, s0
	v_and_b32_e32 v10, 0xffffff80, v10
	s_movk_i32 s0, 0x60
	v_or3_b32 v10, v101, v10, s0
	v_and_b32_e32 v11, 0xffffff80, v11
	s_movk_i32 s0, 0x61
	v_or3_b32 v11, v101, v11, s0
	v_and_b32_e32 v12, 0xffffff80, v12
	s_movk_i32 s0, 0x62
	v_or3_b32 v12, v101, v12, s0
	v_and_b32_e32 v13, 0xffffff80, v13
	s_movk_i32 s0, 0x63
	v_or3_b32 v13, v101, v13, s0
	v_and_b32_e32 v2, 0xffffff80, v2
	s_movk_i32 s0, 0x70
	v_and_b32_e32 v26, 0xffffff80, v26
	v_and_b32_e32 v31, 0xffffff80, v31
	v_or3_b32 v2, v101, v2, s0
	v_and_b32_e32 v3, 0xffffff80, v3
	s_movk_i32 s0, 0x71
	v_or3_b32 v26, v101, v26, 64
	v_or3_b32 v31, v101, v31, 1
	v_and_b32_e32 v32, 0xffffff80, v32
	v_and_b32_e32 v33, 0xffffff80, v33
	v_and_b32_e32 v22, 0xffffff80, v22
	v_and_b32_e32 v23, 0xffffff80, v23
	v_or3_b32 v3, v101, v3, s0
	v_and_b32_e32 v4, 0xffffff80, v4
	s_movk_i32 s0, 0x72
	v_min_f32_e32 v39, v55, v39
	v_min_f32_e32 v55, v71, v87
	v_min_f32_e32 v106, v103, v91
	v_min_f32_e32 v109, v100, v105
	v_max_f32_e32 v71, v71, v87
	v_max_f32_e32 v87, v103, v91
	v_or3_b32 v32, v101, v32, 2
	v_or3_b32 v33, v101, v33, 3
	v_or3_b32 v22, v101, v22, 16
	v_or3_b32 v23, v101, v23, 17
	v_and_b32_e32 v24, 0xffffff80, v24
	v_and_b32_e32 v25, 0xffffff80, v25
	v_and_b32_e32 v14, 0xffffff80, v14
	v_and_b32_e32 v15, 0xffffff80, v15
	v_and_b32_e32 v16, 0xffffff80, v16
	v_and_b32_e32 v17, 0xffffff80, v17
	v_and_b32_e32 v6, 0xffffff80, v6
	v_and_b32_e32 v7, 0xffffff80, v7
	v_and_b32_e32 v8, 0xffffff80, v8
	v_or3_b32 v4, v101, v4, s0
	v_and_b32_e32 v9, 0xffffff80, v9
	v_and_b32_e32 v5, 0xffffff80, v5
	s_movk_i32 s0, 0x73
	v_min_f32_e32 v104, v63, v47
	v_min_f32_e32 v83, v55, v106
	v_min_f32_e32 v47, v109, v110
	v_min_f32_e32 v91, v71, v87
	v_max_f32_e32 v100, v71, v87
	v_max_f32_e32 v87, v55, v106
	v_max_f32_e32 v55, v109, v110
	v_or3_b32 v24, v101, v24, 18
	v_or3_b32 v25, v101, v25, 19
	v_or3_b32 v14, v101, v14, 32
	v_or3_b32 v15, v101, v15, 33
	v_or3_b32 v16, v101, v16, 34
	v_or3_b32 v17, v101, v17, 35
	v_or3_b32 v6, v101, v6, 48
	v_or3_b32 v7, v101, v7, 49
	v_or3_b32 v8, v101, v8, 50
	v_or3_b32 v9, v101, v9, 51
	v_or3_b32 v5, v101, v5, s0
	v_max_f32_e32 v101, v30, v31
	v_min_f32_e32 v30, v30, v31
	v_max_f32_e32 v31, v32, v32
	v_max_f32_e32 v32, v33, v33
	v_max_f32_e32 v109, v26, v27
	v_min_f32_e32 v26, v26, v27
	v_max_f32_e32 v27, v28, v28
	v_max_f32_e32 v28, v29, v29
	v_max_f32_e32 v33, v32, v31
	v_min_f32_e32 v31, v32, v31
	v_max_f32_e32 v32, v22, v23
	v_min_f32_e32 v22, v22, v23
	v_max_f32_e32 v23, v24, v24
	v_max_f32_e32 v24, v25, v25
	v_max_f32_e32 v29, v28, v27
	v_min_f32_e32 v27, v28, v27
	v_max_f32_e32 v28, v18, v19
	v_min_f32_e32 v18, v18, v19
	v_max_f32_e32 v19, v20, v20
	v_max_f32_e32 v20, v21, v21
	v_max_f32_e32 v25, v24, v23
	v_min_f32_e32 v23, v24, v23
	v_max_f32_e32 v24, v14, v15
	v_min_f32_e32 v14, v14, v15
	v_max_f32_e32 v15, v16, v16
	v_max_f32_e32 v16, v17, v17
	v_max_f32_e32 v21, v20, v19
	v_min_f32_e32 v19, v20, v19
	v_max_f32_e32 v20, v10, v11
	v_min_f32_e32 v10, v10, v11
	v_max_f32_e32 v11, v12, v12
	v_max_f32_e32 v12, v13, v13
	v_max_f32_e32 v17, v16, v15
	v_min_f32_e32 v15, v16, v15
	v_max_f32_e32 v16, v6, v7
	v_min_f32_e32 v6, v6, v7
; DEV void ce(float& a, float& b) { float hi = fmaxf(a, b), lo = fminf(a, b); a = hi; b = lo; }
; DEV void sort16_desc(float (&a)[16]) {
; #pragma unroll
;   for (int k = 2; k <= 16; k <<= 1)
; #pragma unroll
;     for (int j = k >> 1; j > 0; j >>= 1)
; #pragma unroll
;       for (int i = 0; i < 16; i++) {
;         const int p = i ^ j;
;         if (p > i) { if ((i & k) == 0) ce(a[i], a[p]); else ce(a[p], a[i]); }
;       }
; }
	v_max_f32_e32 v7, v8, v8
	v_max_f32_e32 v8, v9, v9
	v_max_f32_e32 v13, v12, v11
	v_min_f32_e32 v11, v12, v11
	v_max_f32_e32 v12, v2, v3
	v_min_f32_e32 v2, v2, v3
	v_max_f32_e32 v3, v4, v4
	v_max_f32_e32 v4, v5, v5
	v_max_f32_e32 v9, v8, v7
	v_min_f32_e32 v7, v8, v7
	v_max_f32_e32 v5, v4, v3
	v_min_f32_e32 v3, v4, v3
	v_max_f32_e32 v8, v101, v31
	v_min_f32_e32 v31, v101, v31
	v_max_f32_e32 v101, v30, v33
	v_min_f32_e32 v30, v30, v33
	v_max_f32_e32 v33, v23, v32
	v_min_f32_e32 v23, v23, v32
	v_max_f32_e32 v32, v25, v22
	v_min_f32_e32 v22, v25, v22
	v_max_f32_e32 v25, v24, v15
	v_min_f32_e32 v15, v24, v15
	v_max_f32_e32 v24, v14, v17
	v_min_f32_e32 v14, v14, v17
	v_max_f32_e32 v17, v7, v16
	v_min_f32_e32 v7, v7, v16
	v_max_f32_e32 v16, v9, v6
	v_min_f32_e32 v6, v9, v6
	v_max_f32_e32 v4, v109, v27
	v_min_f32_e32 v27, v109, v27
	v_max_f32_e32 v109, v26, v29
	v_min_f32_e32 v26, v26, v29
	v_max_f32_e32 v29, v19, v28
	v_min_f32_e32 v19, v19, v28
	v_max_f32_e32 v28, v21, v18
	v_min_f32_e32 v18, v21, v18
	v_max_f32_e32 v21, v20, v11
	v_min_f32_e32 v11, v20, v11
	v_max_f32_e32 v20, v10, v13
	v_min_f32_e32 v10, v10, v13
	v_max_f32_e32 v13, v3, v12
	v_min_f32_e32 v3, v3, v12
	v_max_f32_e32 v12, v5, v2
	v_min_f32_e32 v2, v5, v2
	v_max_f32_e32 v9, v8, v101
	v_min_f32_e32 v8, v8, v101
	v_max_f32_e32 v101, v31, v30
	v_min_f32_e32 v30, v31, v30
	v_max_f32_e32 v31, v22, v23
	v_min_f32_e32 v22, v22, v23
	v_max_f32_e32 v23, v32, v33
	v_min_f32_e32 v32, v32, v33
	v_max_f32_e32 v33, v25, v24
	v_min_f32_e32 v24, v25, v24
	v_max_f32_e32 v25, v15, v14
	v_min_f32_e32 v14, v15, v14
	v_max_f32_e32 v15, v6, v7
	v_min_f32_e32 v6, v6, v7
	v_max_f32_e32 v7, v16, v17
	v_min_f32_e32 v16, v16, v17
	v_max_f32_e32 v5, v4, v109
	v_min_f32_e32 v4, v4, v109
	v_max_f32_e32 v109, v27, v26
	v_min_f32_e32 v26, v27, v26
	v_max_f32_e32 v27, v18, v19
	v_min_f32_e32 v18, v18, v19
	v_max_f32_e32 v19, v28, v29
	v_min_f32_e32 v28, v28, v29
	v_max_f32_e32 v29, v21, v20
	v_min_f32_e32 v20, v21, v20
	v_max_f32_e32 v21, v11, v10
	v_min_f32_e32 v10, v11, v10
	v_max_f32_e32 v11, v2, v3
	v_min_f32_e32 v2, v2, v3
	v_max_f32_e32 v3, v12, v13
	v_min_f32_e32 v12, v12, v13
	v_max_f32_e32 v17, v9, v22
	v_min_f32_e32 v9, v9, v22
	v_max_f32_e32 v22, v8, v31
	v_min_f32_e32 v8, v8, v31
	v_max_f32_e32 v31, v101, v32
	v_min_f32_e32 v32, v101, v32
	v_max_f32_e32 v101, v30, v23
	v_min_f32_e32 v23, v30, v23
	v_max_f32_e32 v30, v6, v33
	v_min_f32_e32 v6, v6, v33
	v_max_f32_e32 v33, v15, v24
	v_min_f32_e32 v15, v15, v24
	v_max_f32_e32 v24, v16, v25
	v_min_f32_e32 v16, v16, v25
	v_max_f32_e32 v25, v7, v14
	v_min_f32_e32 v7, v7, v14
	v_max_f32_e32 v13, v5, v18
	v_min_f32_e32 v5, v5, v18
	v_max_f32_e32 v18, v4, v27
	v_min_f32_e32 v4, v4, v27
	v_max_f32_e32 v27, v109, v28
	v_min_f32_e32 v28, v109, v28
	v_max_f32_e32 v109, v26, v19
	v_min_f32_e32 v19, v26, v19
	v_max_f32_e32 v26, v2, v29
	v_min_f32_e32 v2, v2, v29
	v_max_f32_e32 v29, v11, v20
	v_min_f32_e32 v11, v11, v20
	v_max_f32_e32 v20, v12, v21
	v_min_f32_e32 v12, v12, v21
	v_max_f32_e32 v21, v3, v10
	v_min_f32_e32 v3, v3, v10
	v_max_f32_e32 v14, v17, v31
	v_min_f32_e32 v17, v17, v31
	v_max_f32_e32 v31, v22, v101
	v_min_f32_e32 v22, v22, v101
	v_max_f32_e32 v101, v9, v32
	v_min_f32_e32 v9, v9, v32
	v_max_f32_e32 v32, v8, v23
	v_min_f32_e32 v8, v8, v23
	v_max_f32_e32 v23, v16, v6
	v_min_f32_e32 v6, v16, v6
	v_max_f32_e32 v16, v7, v15
	v_min_f32_e32 v7, v7, v15
	v_max_f32_e32 v15, v24, v30
	v_min_f32_e32 v24, v24, v30
	v_max_f32_e32 v30, v25, v33
	v_min_f32_e32 v25, v25, v33
	v_max_f32_e32 v10, v13, v27
	v_min_f32_e32 v13, v13, v27
	v_max_f32_e32 v27, v18, v109
	v_min_f32_e32 v18, v18, v109
	v_max_f32_e32 v109, v5, v28
	v_min_f32_e32 v5, v5, v28
	v_max_f32_e32 v28, v4, v19
	v_min_f32_e32 v4, v4, v19
	v_max_f32_e32 v19, v12, v2
	v_min_f32_e32 v2, v12, v2
	v_max_f32_e32 v12, v3, v11
	v_min_f32_e32 v3, v3, v11
	v_max_f32_e32 v11, v20, v26
	v_min_f32_e32 v20, v20, v26
	v_max_f32_e32 v26, v21, v29
	v_min_f32_e32 v21, v21, v29
	v_max_f32_e32 v33, v14, v31
	v_min_f32_e32 v14, v14, v31
	v_max_f32_e32 v31, v17, v22
	v_min_f32_e32 v17, v17, v22
	v_max_f32_e32 v22, v101, v32
	v_min_f32_e32 v32, v101, v32
	v_max_f32_e32 v101, v9, v8
	v_min_f32_e32 v8, v9, v8
	v_max_f32_e32 v9, v7, v6
	v_min_f32_e32 v6, v7, v6
	v_max_f32_e32 v7, v16, v23
	v_min_f32_e32 v16, v16, v23
	v_max_f32_e32 v23, v25, v24
	v_min_f32_e32 v24, v25, v24
	v_max_f32_e32 v25, v30, v15
	v_min_f32_e32 v15, v30, v15
	v_max_f32_e32 v29, v10, v27
	v_min_f32_e32 v10, v10, v27
	v_max_f32_e32 v27, v13, v18
	v_min_f32_e32 v13, v13, v18
	v_max_f32_e32 v18, v109, v28
	v_min_f32_e32 v28, v109, v28
	v_max_f32_e32 v109, v5, v4
	v_min_f32_e32 v4, v5, v4
	v_max_f32_e32 v5, v3, v2
	v_min_f32_e32 v2, v3, v2
	v_max_f32_e32 v3, v12, v19
	v_min_f32_e32 v12, v12, v19
	v_max_f32_e32 v19, v21, v20
	v_min_f32_e32 v20, v21, v20
	v_max_f32_e32 v21, v26, v11
	v_min_f32_e32 v11, v26, v11
	v_max_f32_e32 v30, v33, v6
	v_min_f32_e32 v6, v33, v6
	v_max_f32_e32 v33, v14, v9
	v_min_f32_e32 v9, v14, v9
	v_max_f32_e32 v14, v31, v16
	v_min_f32_e32 v16, v31, v16
	v_max_f32_e32 v31, v17, v7
	v_min_f32_e32 v7, v17, v7
	v_max_f32_e32 v17, v22, v24
	v_min_f32_e32 v22, v22, v24
	v_max_f32_e32 v24, v32, v23
	v_min_f32_e32 v23, v32, v23
	v_max_f32_e32 v32, v101, v15
	v_min_f32_e32 v15, v101, v15
	v_max_f32_e32 v101, v8, v25
	v_min_f32_e32 v8, v8, v25
	v_max_f32_e32 v26, v29, v2
	v_min_f32_e32 v2, v29, v2
	v_max_f32_e32 v29, v10, v5
	v_min_f32_e32 v5, v10, v5
	v_max_f32_e32 v10, v27, v12
	v_min_f32_e32 v12, v27, v12
	v_max_f32_e32 v27, v13, v3
	v_min_f32_e32 v3, v13, v3
	v_max_f32_e32 v13, v18, v20
	v_min_f32_e32 v18, v18, v20
	v_max_f32_e32 v20, v28, v19
; DEV void ce(float& a, float& b) { float hi = fmaxf(a, b), lo = fminf(a, b); a = hi; b = lo; }
; DEV void bitonic16(float (&l)[16]) {
; #pragma unroll
;   for (int s = 8; s > 0; s >>= 1)
; #pragma unroll
;     for (int i = 0; i < 16; i++)
;       if (!(i & s)) ce(l[i], l[i + s]);
; }
; DEV void sort16_desc(float (&a)[16]) {
; #pragma unroll
;   for (int k = 2; k <= 16; k <<= 1)
; #pragma unroll
;     for (int j = k >> 1; j > 0; j >>= 1)
; #pragma unroll
;       for (int i = 0; i < 16; i++) {
;         const int p = i ^ j;
;         if (p > i) { if ((i & k) == 0) ce(a[i], a[p]); else ce(a[p], a[i]); }
;       }
; }
; DEV void merge_xor(float (&l)[16], int mask) {
;   float t[16];
; #pragma unroll
;   for (int i = 0; i < 16; i++) t[i] = __shfl_xor(l[15 - i], mask);
; #pragma unroll
;   for (int i = 0; i < 16; i++) l[i] = fmaxf(l[i], t[i]);
;   bitonic16(l);
; DEV void peer_top16(const bf16_t* __restrict__ pq, const bf16_t* sk  , float (&l)[16]) {
;     ...
;   sort16_desc(l);
;   sort16_desc(hi);
; #pragma unroll
;   for (int i = 0; i < 16; i++) l[i] = fmaxf(l[i], hi[15 - i]);
;   bitonic16(l);
;   merge_xor(l, 16);
;   merge_xor(l, 32);
; }
	v_min_f32_e32 v19, v28, v19
	v_max_f32_e32 v28, v109, v11
	v_min_f32_e32 v11, v109, v11
	v_max_f32_e32 v109, v4, v21
	v_min_f32_e32 v4, v4, v21
	v_max_f32_e32 v25, v30, v17
	v_min_f32_e32 v17, v30, v17
	v_max_f32_e32 v30, v33, v24
	v_min_f32_e32 v24, v33, v24
	v_max_f32_e32 v33, v14, v32
	v_min_f32_e32 v14, v14, v32
	v_max_f32_e32 v32, v31, v101
	v_min_f32_e32 v31, v31, v101
	v_max_f32_e32 v101, v6, v22
	v_min_f32_e32 v6, v6, v22
	v_max_f32_e32 v22, v9, v23
	v_min_f32_e32 v9, v9, v23
	v_max_f32_e32 v23, v16, v15
	v_min_f32_e32 v15, v16, v15
	v_max_f32_e32 v16, v7, v8
	v_min_f32_e32 v7, v7, v8
	v_max_f32_e32 v21, v26, v13
	v_min_f32_e32 v13, v26, v13
	v_max_f32_e32 v26, v29, v20
	v_min_f32_e32 v20, v29, v20
	v_max_f32_e32 v29, v10, v28
	v_min_f32_e32 v10, v10, v28
	v_max_f32_e32 v28, v27, v109
	v_min_f32_e32 v27, v27, v109
	v_max_f32_e32 v109, v2, v18
	v_min_f32_e32 v2, v2, v18
	v_max_f32_e32 v18, v5, v19
	v_min_f32_e32 v5, v5, v19
	v_max_f32_e32 v19, v12, v11
	v_min_f32_e32 v11, v12, v11
	v_max_f32_e32 v12, v3, v4
	v_min_f32_e32 v3, v3, v4
	v_max_f32_e32 v111, v0, v43
	v_min_f32_e32 v112, v104, v39
	v_max_f32_e32 v103, v104, v39
	v_min_f32_e32 v0, v0, v43
	v_max_f32_e32 v8, v25, v33
	v_min_f32_e32 v25, v25, v33
	v_max_f32_e32 v33, v30, v32
	v_min_f32_e32 v30, v30, v32
	v_max_f32_e32 v32, v17, v14
	v_min_f32_e32 v14, v17, v14
	v_max_f32_e32 v17, v24, v31
	v_min_f32_e32 v24, v24, v31
	v_max_f32_e32 v31, v101, v23
	v_min_f32_e32 v23, v101, v23
	v_max_f32_e32 v101, v22, v16
	v_min_f32_e32 v16, v22, v16
	v_max_f32_e32 v22, v6, v15
	v_min_f32_e32 v6, v6, v15
	v_max_f32_e32 v15, v9, v7
	v_min_f32_e32 v7, v9, v7
	v_max_f32_e32 v4, v21, v29
	v_min_f32_e32 v21, v21, v29
	v_max_f32_e32 v29, v26, v28
	v_min_f32_e32 v26, v26, v28
	v_max_f32_e32 v28, v13, v10
	v_min_f32_e32 v10, v13, v10
	v_max_f32_e32 v13, v20, v27
	v_min_f32_e32 v20, v20, v27
	v_max_f32_e32 v27, v109, v19
	v_min_f32_e32 v19, v109, v19
	v_max_f32_e32 v109, v18, v12
	v_min_f32_e32 v12, v18, v12
	v_max_f32_e32 v18, v2, v11
	v_min_f32_e32 v2, v2, v11
	v_max_f32_e32 v11, v5, v3
	v_min_f32_e32 v3, v5, v3
	v_min_f32_e32 v63, v107, v108
	v_min_f32_e32 v39, v111, v103
	v_max_f32_e32 v71, v107, v108
	v_max_f32_e32 v51, v111, v103
	v_max_f32_e32 v43, v0, v112
	v_min_f32_e32 v0, v0, v112
	v_min_f32_e32 v9, v8, v33
	v_min_f32_e32 v102, v25, v30
	v_min_f32_e32 v103, v32, v17
	v_min_f32_e32 v104, v14, v24
	v_min_f32_e32 v105, v31, v101
	v_min_f32_e32 v106, v23, v16
	v_min_f32_e32 v107, v22, v15
	v_min_f32_e32 v108, v6, v7
	v_min_f32_e32 v5, v4, v29
	v_min_f32_e32 v110, v21, v26
	v_min_f32_e32 v111, v28, v13
	v_min_f32_e32 v112, v10, v20
	v_min_f32_e32 v113, v27, v109
	v_min_f32_e32 v114, v19, v12
	v_min_f32_e32 v115, v18, v11
	v_min_f32_e32 v116, v2, v3
	v_max3_f32 v8, v8, v33, v116
	v_max3_f32 v2, v9, v2, v3
	v_max3_f32 v3, v25, v30, v115
	v_max3_f32 v9, v102, v18, v11
	v_max3_f32 v11, v32, v17, v114
	v_max3_f32 v12, v103, v19, v12
	v_max3_f32 v14, v14, v24, v113
	v_max3_f32 v17, v104, v27, v109
	v_max3_f32 v18, v31, v101, v112
	v_max3_f32 v10, v105, v10, v20
	v_max3_f32 v16, v23, v16, v111
	v_max3_f32 v13, v106, v28, v13
	v_max3_f32 v15, v22, v15, v110
	v_max3_f32 v19, v107, v21, v26
	v_max3_f32 v5, v6, v7, v5
	v_max3_f32 v4, v108, v4, v29
	v_max_f32_e32 v6, v8, v18
	v_min_f32_e32 v7, v8, v18
	v_max_f32_e32 v8, v2, v10
	v_min_f32_e32 v2, v2, v10
	v_max_f32_e32 v10, v3, v16
	v_min_f32_e32 v3, v3, v16
	v_max_f32_e32 v16, v9, v13
	v_min_f32_e32 v9, v9, v13
	v_max_f32_e32 v13, v11, v15
	v_min_f32_e32 v11, v11, v15
	v_max_f32_e32 v15, v12, v19
	v_min_f32_e32 v12, v12, v19
	v_max_f32_e32 v18, v14, v5
	v_min_f32_e32 v5, v14, v5
	v_max_f32_e32 v14, v17, v4
	v_min_f32_e32 v4, v17, v4
	v_max_f32_e32 v17, v6, v13
	v_min_f32_e32 v6, v6, v13
	v_max_f32_e32 v13, v8, v15
	v_min_f32_e32 v8, v8, v15
	v_max_f32_e32 v15, v10, v18
	v_min_f32_e32 v10, v10, v18
	v_max_f32_e32 v18, v16, v14
	v_min_f32_e32 v14, v16, v14
	v_max_f32_e32 v16, v7, v11
	v_min_f32_e32 v7, v7, v11
	v_max_f32_e32 v11, v2, v12
	v_min_f32_e32 v2, v2, v12
	v_max_f32_e32 v12, v3, v5
	v_min_f32_e32 v3, v3, v5
	v_max_f32_e32 v5, v9, v4
	v_min_f32_e32 v4, v9, v4
	v_max_f32_e32 v9, v17, v15
	v_min_f32_e32 v15, v17, v15
	v_max_f32_e32 v17, v13, v18
	v_min_f32_e32 v13, v13, v18
	v_max_f32_e32 v18, v6, v10
	v_min_f32_e32 v6, v6, v10
	v_max_f32_e32 v10, v8, v14
	v_min_f32_e32 v8, v8, v14
	v_max_f32_e32 v14, v16, v12
	v_min_f32_e32 v12, v16, v12
	v_max_f32_e32 v16, v11, v5
	v_min_f32_e32 v5, v11, v5
	v_max_f32_e32 v11, v7, v3
	v_min_f32_e32 v3, v7, v3
	v_max_f32_e32 v7, v2, v4
	v_min_f32_e32 v2, v2, v4
	v_max_f32_e32 v4, v9, v17
	v_min_f32_e32 v9, v9, v17
	v_max_f32_e32 v17, v15, v13
	v_min_f32_e32 v13, v15, v13
	v_max_f32_e32 v15, v18, v10
	v_min_f32_e32 v10, v18, v10
	v_max_f32_e32 v18, v6, v8
	v_min_f32_e32 v6, v6, v8
	v_max_f32_e32 v8, v14, v16
	v_min_f32_e32 v14, v14, v16
	v_max_f32_e32 v16, v12, v5
	v_min_f32_e32 v5, v12, v5
	v_max_f32_e32 v12, v11, v7
	v_min_f32_e32 v7, v11, v7
	v_max_f32_e32 v11, v3, v2
	v_min_f32_e32 v2, v3, v2
	ds_bpermute_b32 v3, v95, v2
	ds_bpermute_b32 v19, v95, v11
	ds_bpermute_b32 v20, v95, v7
	ds_bpermute_b32 v21, v95, v12
	ds_bpermute_b32 v22, v95, v5
	ds_bpermute_b32 v23, v95, v16
	s_waitcnt lgkmcnt(5)
	ds_bpermute_b32 v24, v95, v14
	ds_bpermute_b32 v33, v95, v4
	v_max_f32_e32 v3, v4, v3
	s_waitcnt lgkmcnt(6)
	ds_bpermute_b32 v25, v95, v8
	ds_bpermute_b32 v32, v95, v9
	v_max_f32_e32 v4, v9, v19
	s_waitcnt lgkmcnt(7)
	ds_bpermute_b32 v26, v95, v6
	ds_bpermute_b32 v31, v95, v17
	v_max_f32_e32 v9, v17, v20
	s_waitcnt lgkmcnt(8)
	ds_bpermute_b32 v27, v95, v18
	ds_bpermute_b32 v30, v95, v13
	v_max_f32_e32 v13, v13, v21
	s_waitcnt lgkmcnt(9)
; DEV void merge_xor(float (&l)[16], int mask) {
;   float t[16];
; #pragma unroll
;   for (int i = 0; i < 16; i++) t[i] = __shfl_xor(l[15 - i], mask);
; #pragma unroll
;   for (int i = 0; i < 16; i++) l[i] = fmaxf(l[i], t[i]);
;   bitonic16(l);
; }
; DEV void phase_peer_score(const Params& p, int layer, int M, char* smem) {
;     ...
;     unsigned char* tab = (unsigned char*)smem + 73728 + (w * 16 + l15) * 32;
; #pragma unroll
;     for (int i = 0; i < 16; i++) { tab[i] = (unsigned char)(__float_as_uint(L0[i]) & 127u); tab[16 + i] = (unsigned char)(__float_as_uint(L1[i]) & 127u); }
	ds_bpermute_b32 v28, v95, v10
	ds_bpermute_b32 v29, v95, v15
	v_max_f32_e32 v15, v15, v22
	s_waitcnt lgkmcnt(10)
	v_max_f32_e32 v10, v10, v23
	s_waitcnt lgkmcnt(9)
	v_max_f32_e32 v17, v18, v24
	s_waitcnt lgkmcnt(7)
	v_max_f32_e32 v6, v6, v25
	s_waitcnt lgkmcnt(5)
	v_max_f32_e32 v8, v8, v26
	s_waitcnt lgkmcnt(3)
	v_max_f32_e32 v14, v14, v27
	s_waitcnt lgkmcnt(1)
	v_max_f32_e32 v16, v16, v28
	s_waitcnt lgkmcnt(0)
	v_max_f32_e32 v5, v5, v29
	v_max_f32_e32 v12, v12, v30
	v_max_f32_e32 v7, v7, v31
	v_max_f32_e32 v11, v11, v32
	v_max_f32_e32 v2, v2, v33
	v_max_f32_e32 v18, v3, v8
	v_min_f32_e32 v3, v3, v8
	v_max_f32_e32 v8, v4, v14
	v_min_f32_e32 v4, v4, v14
	v_max_f32_e32 v14, v9, v16
	v_min_f32_e32 v9, v9, v16
	v_max_f32_e32 v16, v13, v5
	v_min_f32_e32 v5, v13, v5
	v_max_f32_e32 v13, v15, v12
	v_min_f32_e32 v12, v15, v12
	v_max_f32_e32 v15, v10, v7
	v_min_f32_e32 v7, v10, v7
	v_max_f32_e32 v10, v17, v11
	v_min_f32_e32 v11, v17, v11
	v_max_f32_e32 v17, v6, v2
	v_min_f32_e32 v2, v6, v2
	v_max_f32_e32 v6, v18, v13
	v_min_f32_e32 v13, v18, v13
	v_max_f32_e32 v18, v8, v15
	v_min_f32_e32 v8, v8, v15
	v_max_f32_e32 v15, v14, v10
	v_min_f32_e32 v10, v14, v10
	v_max_f32_e32 v14, v16, v17
	v_min_f32_e32 v16, v16, v17
	v_max_f32_e32 v17, v3, v12
	v_min_f32_e32 v3, v3, v12
	v_max_f32_e32 v12, v4, v7
	v_min_f32_e32 v4, v4, v7
	v_max_f32_e32 v7, v9, v11
	v_min_f32_e32 v9, v9, v11
	v_max_f32_e32 v11, v5, v2
	v_min_f32_e32 v2, v5, v2
	v_max_f32_e32 v5, v6, v15
	v_min_f32_e32 v6, v6, v15
	v_max_f32_e32 v15, v18, v14
	v_min_f32_e32 v14, v18, v14
	v_max_f32_e32 v18, v13, v10
	v_min_f32_e32 v10, v13, v10
	v_max_f32_e32 v13, v8, v16
	v_min_f32_e32 v8, v8, v16
	v_max_f32_e32 v16, v17, v7
	v_min_f32_e32 v7, v17, v7
	v_max_f32_e32 v17, v12, v11
	v_min_f32_e32 v11, v12, v11
	v_max_f32_e32 v12, v3, v9
	v_min_f32_e32 v3, v3, v9
	v_max_f32_e32 v9, v4, v2
	v_min_f32_e32 v2, v4, v2
	v_max_f32_e32 v4, v5, v15
	v_min_f32_e32 v5, v5, v15
	v_max_f32_e32 v15, v6, v14
	v_min_f32_e32 v6, v6, v14
	v_max_f32_e32 v14, v18, v13
	v_min_f32_e32 v13, v18, v13
	v_max_f32_e32 v18, v10, v8
	v_min_f32_e32 v8, v10, v8
	v_max_f32_e32 v10, v16, v17
	v_min_f32_e32 v16, v16, v17
	v_max_f32_e32 v17, v7, v11
	v_min_f32_e32 v7, v7, v11
	v_max_f32_e32 v11, v12, v9
	v_min_f32_e32 v9, v12, v9
	v_max_f32_e32 v12, v3, v2
	v_min_f32_e32 v2, v3, v2
	ds_bpermute_b32 v3, v99, v2
	ds_bpermute_b32 v19, v99, v12
	ds_bpermute_b32 v20, v99, v9
	ds_bpermute_b32 v21, v99, v11
	ds_bpermute_b32 v22, v99, v7
	ds_bpermute_b32 v23, v99, v17
	s_waitcnt lgkmcnt(5)
	ds_bpermute_b32 v24, v99, v16
	ds_bpermute_b32 v33, v99, v4
	v_max_f32_e32 v3, v4, v3
	s_waitcnt lgkmcnt(6)
	ds_bpermute_b32 v25, v99, v10
	ds_bpermute_b32 v32, v99, v5
	v_max_f32_e32 v4, v5, v19
	s_waitcnt lgkmcnt(7)
	ds_bpermute_b32 v26, v99, v8
	ds_bpermute_b32 v31, v99, v15
	v_max_f32_e32 v5, v15, v20
	s_waitcnt lgkmcnt(8)
	ds_bpermute_b32 v27, v99, v18
	ds_bpermute_b32 v30, v99, v6
	v_max_f32_e32 v6, v6, v21
	s_waitcnt lgkmcnt(9)
	ds_bpermute_b32 v28, v99, v13
	ds_bpermute_b32 v29, v99, v14
	v_max_f32_e32 v14, v14, v22
	s_waitcnt lgkmcnt(10)
	v_max_f32_e32 v13, v13, v23
	s_waitcnt lgkmcnt(9)
	v_max_f32_e32 v15, v18, v24
	s_waitcnt lgkmcnt(7)
	v_max_f32_e32 v8, v8, v25
	s_waitcnt lgkmcnt(5)
	v_max_f32_e32 v10, v10, v26
	s_waitcnt lgkmcnt(3)
	v_max_f32_e32 v16, v16, v27
	s_waitcnt lgkmcnt(1)
	v_max_f32_e32 v17, v17, v28
	s_waitcnt lgkmcnt(0)
	v_max_f32_e32 v7, v7, v29
	v_max_f32_e32 v11, v11, v30
	v_max_f32_e32 v9, v9, v31
	v_max_f32_e32 v12, v12, v32
	v_max_f32_e32 v2, v2, v33
	v_max_f32_e32 v18, v3, v10
	v_min_f32_e32 v3, v3, v10
	v_max_f32_e32 v10, v4, v16
	v_min_f32_e32 v4, v4, v16
	v_max_f32_e32 v16, v5, v17
	v_min_f32_e32 v5, v5, v17
	v_max_f32_e32 v17, v6, v7
	v_min_f32_e32 v6, v6, v7
	v_max_f32_e32 v7, v14, v11
	v_min_f32_e32 v11, v14, v11
	v_max_f32_e32 v14, v13, v9
	v_min_f32_e32 v9, v13, v9
	v_max_f32_e32 v13, v15, v12
	v_min_f32_e32 v12, v15, v12
	v_max_f32_e32 v15, v8, v2
	v_min_f32_e32 v2, v8, v2
	v_max_f32_e32 v8, v18, v7
	v_min_f32_e32 v7, v18, v7
	v_max_f32_e32 v18, v10, v14
	v_min_f32_e32 v10, v10, v14
	v_max_f32_e32 v14, v16, v13
	v_min_f32_e32 v13, v16, v13
	v_max_f32_e32 v16, v17, v15
	v_min_f32_e32 v15, v17, v15
	v_max_f32_e32 v17, v3, v11
	v_min_f32_e32 v3, v3, v11
	v_max_f32_e32 v11, v4, v9
	v_min_f32_e32 v4, v4, v9
	v_max_f32_e32 v9, v5, v12
	v_min_f32_e32 v5, v5, v12
	v_max_f32_e32 v12, v6, v2
	v_min_f32_e32 v2, v6, v2
	v_max_f32_e32 v6, v8, v14
	v_min_f32_e32 v8, v8, v14
	v_max_f32_e32 v14, v18, v16
	v_min_f32_e32 v16, v18, v16
	v_max_f32_e32 v18, v7, v13
	v_max_f32_e32 v19, v10, v15
	s_movk_i32 s0, 0x7f
	v_min_f32_e32 v13, v7, v13
	v_min_f32_e32 v10, v10, v15
	v_max_f32_e32 v15, v17, v9
	v_min_f32_e32 v21, v17, v9
	v_max_f32_e32 v17, v11, v12
	v_min_f32_e32 v22, v11, v12
	v_max_f32_e32 v23, v3, v5
	v_min_f32_e32 v3, v3, v5
	v_max_f32_e32 v5, v4, v2
	v_min_f32_e32 v24, v4, v2
	v_max_f32_e32 v9, v18, v19
	v_min_f32_e32 v12, v18, v19
	v_and_b32_sdwa v18, v63, s0 dst_sel:BYTE_1 dst_unused:UNUSED_PAD src0_sel:DWORD src1_sel:DWORD
	v_max_f32_e32 v2, v6, v14
	v_min_f32_e32 v4, v6, v14
	v_max_f32_e32 v11, v13, v10
	v_min_f32_e32 v10, v13, v10
	v_max_f32_e32 v14, v23, v5
	v_min_f32_e32 v13, v23, v5
	v_max_f32_e32 v6, v3, v24
	v_min_f32_e32 v5, v3, v24
	v_and_b32_sdwa v3, v75, s0 dst_sel:BYTE_1 dst_unused:UNUSED_PAD src0_sel:DWORD src1_sel:DWORD
	v_bitop3_b16 v18, v71, v18, s0 bitop3:0xec
	v_bitop3_b16 v3, v79, v3, s0 bitop3:0xec
	v_lshlrev_b32_e32 v18, 16, v18
	v_or_b32_sdwa v23, v3, v18 dst_sel:DWORD dst_unused:UNUSED_PAD src0_sel:WORD_0 src1_sel:DWORD
	v_and_b32_sdwa v18, v83, s0 dst_sel:BYTE_1 dst_unused:UNUSED_PAD src0_sel:DWORD src1_sel:DWORD
; DEV void ce(float& a, float& b) { float hi = fmaxf(a, b), lo = fminf(a, b); a = hi; b = lo; }
; DEV void phase_peer_score(const Params& p, int layer, int M, char* smem) {
;     ...
;     float R[16];
; #pragma unroll
;     for (int i = 0; i < 16; i++) R[i] = -3.0e38f;
; #pragma unroll
;     for (int i = 0; i < 16; i++)
; #pragma unroll
;       for (int j = 0; j < 16; j++)
;         if ((i + 1) * (j + 1) <= 16) {
;           float v = L0[i] + L1[j];
;           v = __uint_as_float((__float_as_uint(v) & ~255u) | (unsigned)(i * 16 + j));
; #pragma unroll
;           for (int t = 0; t < 16; t++)
;             if (t >= (i + 1) * (j + 1) - 1) ce(R[t], v);
;         }
;     unsigned char* tab = (unsigned char*)smem + 73728 + (w * 16 + l15) * 32;
; #pragma unroll
;     for (int i = 0; i < 16; i++) { tab[i] = (unsigned char)(__float_as_uint(L0[i]) & 127u); tab[16 + i] = (unsigned char)(__float_as_uint(L1[i]) & 127u); }
	v_and_b32_sdwa v3, v91, s0 dst_sel:BYTE_1 dst_unused:UNUSED_PAD src0_sel:DWORD src1_sel:DWORD
	v_bitop3_b16 v18, v87, v18, s0 bitop3:0xec
	v_bitop3_b16 v3, v100, v3, s0 bitop3:0xec
	v_lshlrev_b32_e32 v18, 16, v18
	v_max_f32_e32 v7, v8, v16
	v_min_f32_e32 v8, v8, v16
	v_max_f32_e32 v20, v15, v17
	v_min_f32_e32 v17, v15, v17
	v_max_f32_e32 v16, v21, v22
	v_min_f32_e32 v15, v21, v22
	v_or_b32_sdwa v22, v3, v18 dst_sel:DWORD dst_unused:UNUSED_PAD src0_sel:WORD_0 src1_sel:DWORD
	v_and_b32_sdwa v18, v10, s0 dst_sel:BYTE_1 dst_unused:UNUSED_PAD src0_sel:DWORD src1_sel:DWORD
	v_and_b32_sdwa v3, v12, s0 dst_sel:BYTE_1 dst_unused:UNUSED_PAD src0_sel:DWORD src1_sel:DWORD
	v_bitop3_b16 v18, v11, v18, s0 bitop3:0xec
	v_bitop3_b16 v3, v9, v3, s0 bitop3:0xec
	v_lshlrev_b32_e32 v18, 16, v18
	v_or_b32_sdwa v27, v3, v18 dst_sel:DWORD dst_unused:UNUSED_PAD src0_sel:WORD_0 src1_sel:DWORD
	v_and_b32_sdwa v18, v8, s0 dst_sel:BYTE_1 dst_unused:UNUSED_PAD src0_sel:DWORD src1_sel:DWORD
	v_and_b32_sdwa v3, v4, s0 dst_sel:BYTE_1 dst_unused:UNUSED_PAD src0_sel:DWORD src1_sel:DWORD
	v_bitop3_b16 v18, v7, v18, s0 bitop3:0xec
	v_bitop3_b16 v3, v2, v3, s0 bitop3:0xec
	v_lshlrev_b32_e32 v18, 16, v18
	v_or_b32_sdwa v26, v3, v18 dst_sel:DWORD dst_unused:UNUSED_PAD src0_sel:WORD_0 src1_sel:DWORD
	v_and_b32_sdwa v18, v0, s0 dst_sel:BYTE_1 dst_unused:UNUSED_PAD src0_sel:DWORD src1_sel:DWORD
	v_and_b32_sdwa v3, v39, s0 dst_sel:BYTE_1 dst_unused:UNUSED_PAD src0_sel:DWORD src1_sel:DWORD
	v_bitop3_b16 v18, v43, v18, s0 bitop3:0xec
	v_bitop3_b16 v3, v51, v3, s0 bitop3:0xec
	v_lshlrev_b32_e32 v18, 16, v18
	v_or_b32_sdwa v25, v3, v18 dst_sel:DWORD dst_unused:UNUSED_PAD src0_sel:WORD_0 src1_sel:DWORD
	v_and_b32_sdwa v18, v47, s0 dst_sel:BYTE_1 dst_unused:UNUSED_PAD src0_sel:DWORD src1_sel:DWORD
	v_and_b32_sdwa v3, v59, s0 dst_sel:BYTE_1 dst_unused:UNUSED_PAD src0_sel:DWORD src1_sel:DWORD
	v_bitop3_b16 v18, v55, v18, s0 bitop3:0xec
	v_bitop3_b16 v3, v67, v3, s0 bitop3:0xec
	v_lshlrev_b32_e32 v18, 16, v18
	v_or_b32_sdwa v24, v3, v18 dst_sel:DWORD dst_unused:UNUSED_PAD src0_sel:WORD_0 src1_sel:DWORD
	v_and_b32_sdwa v18, v5, s0 dst_sel:BYTE_1 dst_unused:UNUSED_PAD src0_sel:DWORD src1_sel:DWORD
	v_and_b32_sdwa v3, v13, s0 dst_sel:BYTE_1 dst_unused:UNUSED_PAD src0_sel:DWORD src1_sel:DWORD
	v_bitop3_b16 v18, v6, v18, s0 bitop3:0xec
	v_bitop3_b16 v3, v14, v3, s0 bitop3:0xec
	v_lshlrev_b32_e32 v18, 16, v18
	v_or_b32_sdwa v29, v3, v18 dst_sel:DWORD dst_unused:UNUSED_PAD src0_sel:WORD_0 src1_sel:DWORD
	v_and_b32_sdwa v18, v15, s0 dst_sel:BYTE_1 dst_unused:UNUSED_PAD src0_sel:DWORD src1_sel:DWORD
	v_and_b32_sdwa v3, v17, s0 dst_sel:BYTE_1 dst_unused:UNUSED_PAD src0_sel:DWORD src1_sel:DWORD
	v_bitop3_b16 v18, v16, v18, s0 bitop3:0xec
	v_bitop3_b16 v3, v20, v3, s0 bitop3:0xec
	v_lshlrev_b32_e32 v18, 16, v18
	v_or_b32_sdwa v28, v3, v18 dst_sel:DWORD dst_unused:UNUSED_PAD src0_sel:WORD_0 src1_sel:DWORD
	ds_write_b128 v138, v[22:25]
	ds_write_b128 v138, v[26:29] offset:16
	s_and_saveexec_b64 s[14:15], s[38:39]
	s_cbranch_execz .LBB0_162
	s_movk_i32 s0, 0xff00
	v_add_f32_e32 v164, v100, v2
	v_and_or_b32 v164, v164, s0, 0
	v_max_f32_e32 v148, 0xff61b1e6, v164
	v_add_f32_e32 v164, v100, v4
	v_and_or_b32 v164, v164, s0, 1
	v_max_f32_e32 v149, 0xff61b1e6, v164
	v_add_f32_e32 v164, v100, v7
	v_and_or_b32 v164, v164, s0, 2
	v_max_f32_e32 v150, 0xff61b1e6, v164
	v_add_f32_e32 v164, v100, v8
	v_and_or_b32 v164, v164, s0, 3
	v_max_f32_e32 v151, 0xff61b1e6, v164
	v_add_f32_e32 v164, v100, v9
	v_and_or_b32 v164, v164, s0, 4
	v_max_f32_e32 v152, 0xff61b1e6, v164
	v_add_f32_e32 v164, v100, v12
	v_and_or_b32 v164, v164, s0, 5
	v_max_f32_e32 v153, 0xff61b1e6, v164
	v_add_f32_e32 v164, v100, v11
	v_and_or_b32 v164, v164, s0, 6
	v_max_f32_e32 v154, 0xff61b1e6, v164
	v_add_f32_e32 v164, v100, v10
	v_and_or_b32 v164, v164, s0, 7
	v_max_f32_e32 v155, 0xff61b1e6, v164
	v_add_f32_e32 v164, v100, v20
	v_and_or_b32 v164, v164, s0, 8
	v_max_f32_e32 v156, 0xff61b1e6, v164
	v_add_f32_e32 v164, v100, v17
	v_and_or_b32 v164, v164, s0, 9
	v_max_f32_e32 v157, 0xff61b1e6, v164
	v_add_f32_e32 v164, v100, v16
	v_and_or_b32 v164, v164, s0, 10
	v_max_f32_e32 v158, 0xff61b1e6, v164
	v_add_f32_e32 v164, v100, v15
	v_and_or_b32 v164, v164, s0, 11
	v_max_f32_e32 v159, 0xff61b1e6, v164
	v_add_f32_e32 v164, v100, v14
	v_and_or_b32 v164, v164, s0, 12
	v_max_f32_e32 v160, 0xff61b1e6, v164
	v_add_f32_e32 v164, v100, v13
	v_and_or_b32 v164, v164, s0, 13
	v_max_f32_e32 v161, 0xff61b1e6, v164
	v_add_f32_e32 v164, v100, v6
	v_and_or_b32 v164, v164, s0, 14
	v_max_f32_e32 v162, 0xff61b1e6, v164
	v_add_f32_e32 v164, v100, v5
	v_and_or_b32 v164, v164, s0, 15
	v_max_f32_e32 v163, 0xff61b1e6, v164
	v_add_f32_e32 v164, v91, v2
	v_and_or_b32 v164, v164, s0, 16
	v_med3_f32 v163, v162, v163, v164
	v_med3_f32 v162, v161, v162, v164
	v_med3_f32 v161, v160, v161, v164
	v_med3_f32 v160, v159, v160, v164
	v_med3_f32 v159, v158, v159, v164
	v_med3_f32 v158, v157, v158, v164
	v_med3_f32 v157, v156, v157, v164
	v_med3_f32 v156, v155, v156, v164
	v_med3_f32 v155, v154, v155, v164
	v_med3_f32 v154, v153, v154, v164
	v_med3_f32 v153, v152, v153, v164
	v_med3_f32 v152, v151, v152, v164
	v_med3_f32 v151, v150, v151, v164
	v_med3_f32 v150, v149, v150, v164
	v_max_f32_e32 v149, v149, v164
	v_add_f32_e32 v164, v91, v4
	v_and_or_b32 v164, v164, s0, 17
	v_med3_f32 v163, v162, v163, v164
	v_med3_f32 v162, v161, v162, v164
	v_med3_f32 v161, v160, v161, v164
	v_med3_f32 v160, v159, v160, v164
	v_med3_f32 v159, v158, v159, v164
	v_med3_f32 v158, v157, v158, v164
	v_med3_f32 v157, v156, v157, v164
	v_med3_f32 v156, v155, v156, v164
	v_med3_f32 v155, v154, v155, v164
; DEV void ce(float& a, float& b) { float hi = fmaxf(a, b), lo = fminf(a, b); a = hi; b = lo; }
; DEV void phase_peer_score(const Params& p, int layer, int M, char* smem) {
;     ...
;     float R[16];
; #pragma unroll
;     for (int i = 0; i < 16; i++) R[i] = -3.0e38f;
; #pragma unroll
;     for (int i = 0; i < 16; i++)
; #pragma unroll
;       for (int j = 0; j < 16; j++)
;         if ((i + 1) * (j + 1) <= 16) {
;           float v = L0[i] + L1[j];
;           v = __uint_as_float((__float_as_uint(v) & ~255u) | (unsigned)(i * 16 + j));
; #pragma unroll
;           for (int t = 0; t < 16; t++)
;             if (t >= (i + 1) * (j + 1) - 1) ce(R[t], v);
;         }
	v_med3_f32 v154, v153, v154, v164
	v_med3_f32 v153, v152, v153, v164
	v_med3_f32 v152, v151, v152, v164
	v_max_f32_e32 v151, v151, v164
	v_add_f32_e32 v164, v91, v7
	v_and_or_b32 v164, v164, s0, 18
	v_med3_f32 v163, v162, v163, v164
	v_med3_f32 v162, v161, v162, v164
	v_med3_f32 v161, v160, v161, v164
	v_med3_f32 v160, v159, v160, v164
	v_med3_f32 v159, v158, v159, v164
	v_med3_f32 v158, v157, v158, v164
	v_med3_f32 v157, v156, v157, v164
	v_med3_f32 v156, v155, v156, v164
	v_med3_f32 v155, v154, v155, v164
	v_med3_f32 v154, v153, v154, v164
	v_max_f32_e32 v153, v153, v164
	v_add_f32_e32 v164, v91, v8
	v_and_or_b32 v164, v164, s0, 19
	v_med3_f32 v163, v162, v163, v164
	v_med3_f32 v162, v161, v162, v164
	v_med3_f32 v161, v160, v161, v164
	v_med3_f32 v160, v159, v160, v164
	v_med3_f32 v159, v158, v159, v164
	v_med3_f32 v158, v157, v158, v164
	v_med3_f32 v157, v156, v157, v164
	v_med3_f32 v156, v155, v156, v164
	v_max_f32_e32 v155, v155, v164
	v_add_f32_e32 v164, v91, v9
	v_and_or_b32 v164, v164, s0, 20
	v_med3_f32 v163, v162, v163, v164
	v_med3_f32 v162, v161, v162, v164
	v_med3_f32 v161, v160, v161, v164
	v_med3_f32 v160, v159, v160, v164
	v_med3_f32 v159, v158, v159, v164
	v_med3_f32 v158, v157, v158, v164
	v_max_f32_e32 v157, v157, v164
	v_add_f32_e32 v164, v91, v12
	v_and_or_b32 v164, v164, s0, 21
	v_med3_f32 v163, v162, v163, v164
	v_med3_f32 v162, v161, v162, v164
	v_med3_f32 v161, v160, v161, v164
	v_med3_f32 v160, v159, v160, v164
	v_max_f32_e32 v159, v159, v164
	v_add_f32_e32 v164, v91, v11
	v_and_or_b32 v164, v164, s0, 22
	v_med3_f32 v163, v162, v163, v164
	v_med3_f32 v162, v161, v162, v164
	v_max_f32_e32 v161, v161, v164
	v_add_f32_e32 v164, v91, v10
	v_and_or_b32 v164, v164, s0, 23
	v_max_f32_e32 v163, v163, v164
	v_add_f32_e32 v164, v87, v2
	v_and_or_b32 v164, v164, s0, 32
	v_med3_f32 v163, v162, v163, v164
	v_med3_f32 v162, v161, v162, v164
	v_med3_f32 v161, v160, v161, v164
	v_med3_f32 v160, v159, v160, v164
	v_med3_f32 v159, v158, v159, v164
	v_med3_f32 v158, v157, v158, v164
	v_med3_f32 v157, v156, v157, v164
	v_med3_f32 v156, v155, v156, v164
	v_med3_f32 v155, v154, v155, v164
	v_med3_f32 v154, v153, v154, v164
	v_med3_f32 v153, v152, v153, v164
	v_med3_f32 v152, v151, v152, v164
	v_med3_f32 v151, v150, v151, v164
	v_max_f32_e32 v150, v150, v164
	v_add_f32_e32 v164, v87, v4
	v_and_or_b32 v164, v164, s0, 33
	v_med3_f32 v163, v162, v163, v164
	v_med3_f32 v162, v161, v162, v164
	v_med3_f32 v161, v160, v161, v164
	v_med3_f32 v160, v159, v160, v164
	v_med3_f32 v159, v158, v159, v164
	v_med3_f32 v158, v157, v158, v164
	v_med3_f32 v157, v156, v157, v164
	v_med3_f32 v156, v155, v156, v164
	v_med3_f32 v155, v154, v155, v164
	v_med3_f32 v154, v153, v154, v164
	v_max_f32_e32 v153, v153, v164
	v_add_f32_e32 v164, v87, v7
	v_and_or_b32 v164, v164, s0, 34
	v_med3_f32 v163, v162, v163, v164
	v_med3_f32 v162, v161, v162, v164
	v_med3_f32 v161, v160, v161, v164
	v_med3_f32 v160, v159, v160, v164
	v_med3_f32 v159, v158, v159, v164
	v_med3_f32 v158, v157, v158, v164
	v_med3_f32 v157, v156, v157, v164
	v_max_f32_e32 v156, v156, v164
	v_add_f32_e32 v164, v87, v8
	v_and_or_b32 v164, v164, s0, 35
	v_med3_f32 v163, v162, v163, v164
	v_med3_f32 v162, v161, v162, v164
	v_med3_f32 v161, v160, v161, v164
	v_med3_f32 v160, v159, v160, v164
	v_max_f32_e32 v159, v159, v164
	v_add_f32_e32 v164, v87, v9
	v_and_or_b32 v164, v164, s0, 36
	v_med3_f32 v163, v162, v163, v164
	v_max_f32_e32 v162, v162, v164
	v_add_f32_e32 v164, v83, v2
	v_and_or_b32 v164, v164, s0, 48
	v_med3_f32 v163, v162, v163, v164
	v_med3_f32 v162, v161, v162, v164
	v_med3_f32 v161, v160, v161, v164
	v_med3_f32 v160, v159, v160, v164
	v_med3_f32 v159, v158, v159, v164
	v_med3_f32 v158, v157, v158, v164
	v_med3_f32 v157, v156, v157, v164
	v_med3_f32 v156, v155, v156, v164
	v_med3_f32 v155, v154, v155, v164
	v_med3_f32 v154, v153, v154, v164
	v_med3_f32 v153, v152, v153, v164
	v_med3_f32 v152, v151, v152, v164
	v_max_f32_e32 v151, v151, v164
	v_add_f32_e32 v164, v83, v4
	v_and_or_b32 v164, v164, s0, 49
	v_med3_f32 v163, v162, v163, v164
	v_med3_f32 v162, v161, v162, v164
	v_med3_f32 v161, v160, v161, v164
	v_med3_f32 v160, v159, v160, v164
	v_med3_f32 v159, v158, v159, v164
	v_med3_f32 v158, v157, v158, v164
	v_med3_f32 v157, v156, v157, v164
	v_med3_f32 v156, v155, v156, v164
	v_max_f32_e32 v155, v155, v164
	v_add_f32_e32 v164, v83, v7
	v_and_or_b32 v164, v164, s0, 50
	v_med3_f32 v163, v162, v163, v164
	v_med3_f32 v162, v161, v162, v164
	v_med3_f32 v161, v160, v161, v164
	v_med3_f32 v160, v159, v160, v164
	v_max_f32_e32 v159, v159, v164
	v_add_f32_e32 v164, v83, v8
	v_and_or_b32 v164, v164, s0, 51
	v_max_f32_e32 v163, v163, v164
	v_add_f32_e32 v164, v79, v2
	v_and_or_b32 v164, v164, s0, 64
	v_med3_f32 v163, v162, v163, v164
	v_med3_f32 v162, v161, v162, v164
	v_med3_f32 v161, v160, v161, v164
	v_med3_f32 v160, v159, v160, v164
	v_med3_f32 v159, v158, v159, v164
	v_med3_f32 v158, v157, v158, v164
	v_med3_f32 v157, v156, v157, v164
	v_med3_f32 v156, v155, v156, v164
	v_med3_f32 v155, v154, v155, v164
	v_med3_f32 v154, v153, v154, v164
	v_med3_f32 v153, v152, v153, v164
	v_max_f32_e32 v152, v152, v164
	v_add_f32_e32 v164, v79, v4
	v_and_b32_e32 v164, 0xffffff00, v164
	v_or_b32_e32 v164, 0x41, v164
	v_med3_f32 v163, v162, v163, v164
	v_med3_f32 v162, v161, v162, v164
	v_med3_f32 v161, v160, v161, v164
	v_med3_f32 v160, v159, v160, v164
	v_med3_f32 v159, v158, v159, v164
	v_med3_f32 v158, v157, v158, v164
	v_max_f32_e32 v157, v157, v164
	v_add_f32_e32 v164, v79, v7
	v_and_b32_e32 v164, 0xffffff00, v164
	v_or_b32_e32 v164, 0x42, v164
	v_med3_f32 v163, v162, v163, v164
	v_max_f32_e32 v162, v162, v164
; DEV void ce(float& a, float& b) { float hi = fmaxf(a, b), lo = fminf(a, b); a = hi; b = lo; }
; DEV void phase_peer_score(const Params& p, int layer, int M, char* smem) {
;     ...
;     float R[16];
; #pragma unroll
;     for (int i = 0; i < 16; i++) R[i] = -3.0e38f;
; #pragma unroll
;     for (int i = 0; i < 16; i++)
; #pragma unroll
;       for (int j = 0; j < 16; j++)
;         if ((i + 1) * (j + 1) <= 16) {
;           float v = L0[i] + L1[j];
;           v = __uint_as_float((__float_as_uint(v) & ~255u) | (unsigned)(i * 16 + j));
; #pragma unroll
;           for (int t = 0; t < 16; t++)
;             if (t >= (i + 1) * (j + 1) - 1) ce(R[t], v);
;         }
	v_add_f32_e32 v164, v75, v2
	v_and_b32_e32 v164, 0xffffff00, v164
	v_or_b32_e32 v164, 0x50, v164
	v_med3_f32 v163, v162, v163, v164
	v_med3_f32 v162, v161, v162, v164
	v_med3_f32 v161, v160, v161, v164
	v_med3_f32 v160, v159, v160, v164
	v_med3_f32 v159, v158, v159, v164
	v_med3_f32 v158, v157, v158, v164
	v_med3_f32 v157, v156, v157, v164
	v_med3_f32 v156, v155, v156, v164
	v_med3_f32 v155, v154, v155, v164
	v_med3_f32 v154, v153, v154, v164
	v_max_f32_e32 v153, v153, v164
	v_add_f32_e32 v164, v75, v4
	v_and_b32_e32 v164, 0xffffff00, v164
	v_or_b32_e32 v164, 0x51, v164
	v_med3_f32 v163, v162, v163, v164
	v_med3_f32 v162, v161, v162, v164
	v_med3_f32 v161, v160, v161, v164
	v_med3_f32 v160, v159, v160, v164
	v_max_f32_e32 v159, v159, v164
	v_add_f32_e32 v164, v71, v2
	v_and_b32_e32 v164, 0xffffff00, v164
	v_or_b32_e32 v164, 0x60, v164
	v_med3_f32 v163, v162, v163, v164
	v_med3_f32 v162, v161, v162, v164
	v_med3_f32 v161, v160, v161, v164
	v_med3_f32 v160, v159, v160, v164
	v_med3_f32 v159, v158, v159, v164
	v_med3_f32 v158, v157, v158, v164
	v_med3_f32 v157, v156, v157, v164
	v_med3_f32 v156, v155, v156, v164
	v_med3_f32 v155, v154, v155, v164
	v_max_f32_e32 v154, v154, v164
	v_add_f32_e32 v164, v71, v4
	v_and_b32_e32 v164, 0xffffff00, v164
	v_or_b32_e32 v164, 0x61, v164
	v_med3_f32 v163, v162, v163, v164
	v_med3_f32 v162, v161, v162, v164
	v_max_f32_e32 v161, v161, v164
	v_add_f32_e32 v164, v63, v2
	v_and_b32_e32 v164, 0xffffff00, v164
	v_or_b32_e32 v164, 0x70, v164
	v_med3_f32 v163, v162, v163, v164
	v_med3_f32 v162, v161, v162, v164
	v_med3_f32 v161, v160, v161, v164
	v_med3_f32 v160, v159, v160, v164
	v_med3_f32 v159, v158, v159, v164
	v_med3_f32 v158, v157, v158, v164
	v_med3_f32 v157, v156, v157, v164
	v_med3_f32 v156, v155, v156, v164
	v_max_f32_e32 v155, v155, v164
	v_add_f32_e32 v164, v63, v4
	v_and_b32_e32 v164, 0xffffff00, v164
	v_or_b32_e32 v164, 0x71, v164
	v_max_f32_e32 v163, v163, v164
	v_add_f32_e32 v164, v67, v2
	v_and_b32_e32 v164, 0xffffff00, v164
	v_or_b32_e32 v164, 0x80, v164
	v_med3_f32 v163, v162, v163, v164
	v_med3_f32 v162, v161, v162, v164
	v_med3_f32 v161, v160, v161, v164
	v_med3_f32 v160, v159, v160, v164
	v_med3_f32 v159, v158, v159, v164
	v_med3_f32 v158, v157, v158, v164
	v_med3_f32 v157, v156, v157, v164
	v_max_f32_e32 v156, v156, v164
	v_add_f32_e32 v164, v59, v2
	v_and_b32_e32 v164, 0xffffff00, v164
	v_or_b32_e32 v164, 0x90, v164
	v_med3_f32 v163, v162, v163, v164
	v_med3_f32 v162, v161, v162, v164
	v_med3_f32 v161, v160, v161, v164
	v_med3_f32 v160, v159, v160, v164
	v_med3_f32 v159, v158, v159, v164
	v_med3_f32 v158, v157, v158, v164
	v_max_f32_e32 v157, v157, v164
	v_add_f32_e32 v164, v55, v2
	v_and_b32_e32 v164, 0xffffff00, v164
	v_or_b32_e32 v164, 0xa0, v164
	v_med3_f32 v163, v162, v163, v164
	v_med3_f32 v162, v161, v162, v164
	v_med3_f32 v161, v160, v161, v164
	v_med3_f32 v160, v159, v160, v164
	v_med3_f32 v159, v158, v159, v164
	v_max_f32_e32 v158, v158, v164
	v_add_f32_e32 v164, v47, v2
	v_and_b32_e32 v164, 0xffffff00, v164
	v_or_b32_e32 v164, 0xb0, v164
	v_med3_f32 v163, v162, v163, v164
	v_med3_f32 v162, v161, v162, v164
	v_med3_f32 v161, v160, v161, v164
	v_med3_f32 v160, v159, v160, v164
	v_max_f32_e32 v159, v159, v164
	v_add_f32_e32 v164, v51, v2
	v_and_b32_e32 v164, 0xffffff00, v164
	v_or_b32_e32 v164, 0xc0, v164
	v_med3_f32 v163, v162, v163, v164
	v_med3_f32 v162, v161, v162, v164
	v_med3_f32 v161, v160, v161, v164
	v_max_f32_e32 v160, v160, v164
	v_add_f32_e32 v164, v39, v2
	v_and_b32_e32 v164, 0xffffff00, v164
	v_or_b32_e32 v164, 0xd0, v164
	v_med3_f32 v163, v162, v163, v164
	v_med3_f32 v162, v161, v162, v164
	v_max_f32_e32 v161, v161, v164
	v_add_f32_e32 v164, v43, v2
	v_and_b32_e32 v164, 0xffffff00, v164
	v_or_b32_e32 v164, 0xe0, v164
	v_med3_f32 v163, v162, v163, v164
	v_max_f32_e32 v162, v162, v164
	v_add_f32_e32 v164, v0, v2
	v_and_b32_e32 v164, 0xffffff00, v164
	v_or_b32_e32 v164, 0xf0, v164
	v_max_f32_e32 v163, v163, v164
	v_cmp_le_f32_e64 s[40:41], v148, v149
	v_cmp_le_f32_e32 vcc, v149, v150
	s_or_b64 s[40:41], s[40:41], vcc
	v_cmp_le_f32_e32 vcc, v150, v151
	s_or_b64 s[40:41], s[40:41], vcc
	v_cmp_le_f32_e32 vcc, v151, v152
	s_or_b64 s[40:41], s[40:41], vcc
	v_cmp_le_f32_e32 vcc, v152, v153
	s_or_b64 s[40:41], s[40:41], vcc
	v_cmp_le_f32_e32 vcc, v153, v154
	s_or_b64 s[40:41], s[40:41], vcc
	v_cmp_le_f32_e32 vcc, v154, v155
	s_or_b64 s[40:41], s[40:41], vcc
	v_cmp_le_f32_e32 vcc, v155, v156
	s_or_b64 s[40:41], s[40:41], vcc
	v_cmp_le_f32_e32 vcc, v156, v157
	s_or_b64 s[40:41], s[40:41], vcc
	v_cmp_le_f32_e32 vcc, v157, v158
	s_or_b64 s[40:41], s[40:41], vcc
	v_cmp_le_f32_e32 vcc, v158, v159
	s_or_b64 s[40:41], s[40:41], vcc
	v_cmp_le_f32_e32 vcc, v159, v160
	s_or_b64 s[40:41], s[40:41], vcc
	v_cmp_le_f32_e32 vcc, v160, v161
	s_or_b64 s[40:41], s[40:41], vcc
	v_cmp_le_f32_e32 vcc, v161, v162
	s_or_b64 s[40:41], s[40:41], vcc
	v_cmp_le_f32_e32 vcc, v162, v163
	s_or_b64 s[40:41], s[40:41], vcc
	s_and_b64 s[40:41], s[40:41], exec
	s_cbranch_scc0 .Lmed3_ok_bb_172
; DEV void ce(float& a, float& b) { float hi = fmaxf(a, b), lo = fminf(a, b); a = hi; b = lo; }
; DEV void phase_peer_score(const Params& p, int layer, int M, char* smem) {
;     ...
;     float R[16];
; #pragma unroll
;     for (int i = 0; i < 16; i++) R[i] = -3.0e38f;
; #pragma unroll
;     for (int i = 0; i < 16; i++)
; #pragma unroll
;       for (int j = 0; j < 16; j++)
;         if ((i + 1) * (j + 1) <= 16) {
;           float v = L0[i] + L1[j];
;           v = __uint_as_float((__float_as_uint(v) & ~255u) | (unsigned)(i * 16 + j));
; #pragma unroll
;           for (int t = 0; t < 16; t++)
;             if (t >= (i + 1) * (j + 1) - 1) ce(R[t], v);
;         }
	v_mov_b32_e32 v148, 0xff61b1e6
	v_mov_b32_e32 v149, 0xff61b1e6
	v_mov_b32_e32 v150, 0xff61b1e6
	v_mov_b32_e32 v151, 0xff61b1e6
	v_mov_b32_e32 v152, 0xff61b1e6
	v_mov_b32_e32 v153, 0xff61b1e6
	v_mov_b32_e32 v154, 0xff61b1e6
	v_mov_b32_e32 v155, 0xff61b1e6
	v_mov_b32_e32 v156, 0xff61b1e6
	v_mov_b32_e32 v157, 0xff61b1e6
	v_mov_b32_e32 v158, 0xff61b1e6
	v_mov_b32_e32 v159, 0xff61b1e6
	v_mov_b32_e32 v160, 0xff61b1e6
	v_mov_b32_e32 v161, 0xff61b1e6
	v_mov_b32_e32 v162, 0xff61b1e6
	v_mov_b32_e32 v163, 0xff61b1e6
	v_add_f32_e32 v164, v100, v2
	v_and_or_b32 v164, v164, s0, 0
	v_min_f32_e32 v165, v148, v164
	v_max_f32_e32 v148, v148, v164
	v_min_f32_e32 v164, v149, v165
	v_max_f32_e32 v149, v149, v165
	v_min_f32_e32 v165, v150, v164
	v_max_f32_e32 v150, v150, v164
	v_min_f32_e32 v164, v151, v165
	v_max_f32_e32 v151, v151, v165
	v_min_f32_e32 v165, v152, v164
	v_max_f32_e32 v152, v152, v164
	v_min_f32_e32 v164, v153, v165
	v_max_f32_e32 v153, v153, v165
	v_min_f32_e32 v165, v154, v164
	v_max_f32_e32 v154, v154, v164
	v_min_f32_e32 v164, v155, v165
	v_max_f32_e32 v155, v155, v165
	v_min_f32_e32 v165, v156, v164
	v_max_f32_e32 v156, v156, v164
	v_min_f32_e32 v164, v157, v165
	v_max_f32_e32 v157, v157, v165
	v_min_f32_e32 v165, v158, v164
	v_max_f32_e32 v158, v158, v164
	v_min_f32_e32 v164, v159, v165
	v_max_f32_e32 v159, v159, v165
	v_min_f32_e32 v165, v160, v164
	v_max_f32_e32 v160, v160, v164
	v_min_f32_e32 v164, v161, v165
	v_max_f32_e32 v161, v161, v165
	v_min_f32_e32 v165, v162, v164
	v_max_f32_e32 v162, v162, v164
	v_max_f32_e32 v163, v163, v165
	v_add_f32_e32 v164, v100, v4
	v_and_or_b32 v164, v164, s0, 1
	v_min_f32_e32 v165, v149, v164
	v_max_f32_e32 v149, v149, v164
	v_min_f32_e32 v164, v150, v165
	v_max_f32_e32 v150, v150, v165
	v_min_f32_e32 v165, v151, v164
	v_max_f32_e32 v151, v151, v164
	v_min_f32_e32 v164, v152, v165
	v_max_f32_e32 v152, v152, v165
	v_min_f32_e32 v165, v153, v164
	v_max_f32_e32 v153, v153, v164
	v_min_f32_e32 v164, v154, v165
	v_max_f32_e32 v154, v154, v165
	v_min_f32_e32 v165, v155, v164
	v_max_f32_e32 v155, v155, v164
	v_min_f32_e32 v164, v156, v165
	v_max_f32_e32 v156, v156, v165
	v_min_f32_e32 v165, v157, v164
	v_max_f32_e32 v157, v157, v164
	v_min_f32_e32 v164, v158, v165
	v_max_f32_e32 v158, v158, v165
	v_min_f32_e32 v165, v159, v164
	v_max_f32_e32 v159, v159, v164
	v_min_f32_e32 v164, v160, v165
	v_max_f32_e32 v160, v160, v165
	v_min_f32_e32 v165, v161, v164
	v_max_f32_e32 v161, v161, v164
	v_min_f32_e32 v164, v162, v165
	v_max_f32_e32 v162, v162, v165
	v_max_f32_e32 v163, v163, v164
	v_add_f32_e32 v164, v100, v7
	v_and_or_b32 v164, v164, s0, 2
	v_min_f32_e32 v165, v150, v164
	v_max_f32_e32 v150, v150, v164
	v_min_f32_e32 v164, v151, v165
	v_max_f32_e32 v151, v151, v165
	v_min_f32_e32 v165, v152, v164
	v_max_f32_e32 v152, v152, v164
	v_min_f32_e32 v164, v153, v165
	v_max_f32_e32 v153, v153, v165
	v_min_f32_e32 v165, v154, v164
	v_max_f32_e32 v154, v154, v164
	v_min_f32_e32 v164, v155, v165
	v_max_f32_e32 v155, v155, v165
	v_min_f32_e32 v165, v156, v164
	v_max_f32_e32 v156, v156, v164
	v_min_f32_e32 v164, v157, v165
	v_max_f32_e32 v157, v157, v165
	v_min_f32_e32 v165, v158, v164
	v_max_f32_e32 v158, v158, v164
	v_min_f32_e32 v164, v159, v165
	v_max_f32_e32 v159, v159, v165
	v_min_f32_e32 v165, v160, v164
	v_max_f32_e32 v160, v160, v164
	v_min_f32_e32 v164, v161, v165
	v_max_f32_e32 v161, v161, v165
	v_min_f32_e32 v165, v162, v164
	v_max_f32_e32 v162, v162, v164
	v_max_f32_e32 v163, v163, v165
	v_add_f32_e32 v164, v100, v8
	v_and_or_b32 v164, v164, s0, 3
	v_min_f32_e32 v165, v151, v164
	v_max_f32_e32 v151, v151, v164
	v_min_f32_e32 v164, v152, v165
	v_max_f32_e32 v152, v152, v165
	v_min_f32_e32 v165, v153, v164
	v_max_f32_e32 v153, v153, v164
	v_min_f32_e32 v164, v154, v165
	v_max_f32_e32 v154, v154, v165
	v_min_f32_e32 v165, v155, v164
	v_max_f32_e32 v155, v155, v164
	v_min_f32_e32 v164, v156, v165
	v_max_f32_e32 v156, v156, v165
	v_min_f32_e32 v165, v157, v164
	v_max_f32_e32 v157, v157, v164
	v_min_f32_e32 v164, v158, v165
	v_max_f32_e32 v158, v158, v165
	v_min_f32_e32 v165, v159, v164
	v_max_f32_e32 v159, v159, v164
	v_min_f32_e32 v164, v160, v165
	v_max_f32_e32 v160, v160, v165
	v_min_f32_e32 v165, v161, v164
	v_max_f32_e32 v161, v161, v164
	v_min_f32_e32 v164, v162, v165
	v_max_f32_e32 v162, v162, v165
	v_max_f32_e32 v163, v163, v164
	v_add_f32_e32 v164, v100, v9
	v_and_or_b32 v164, v164, s0, 4
	v_min_f32_e32 v165, v152, v164
	v_max_f32_e32 v152, v152, v164
	v_min_f32_e32 v164, v153, v165
	v_max_f32_e32 v153, v153, v165
	v_min_f32_e32 v165, v154, v164
	v_max_f32_e32 v154, v154, v164
	v_min_f32_e32 v164, v155, v165
	v_max_f32_e32 v155, v155, v165
	v_min_f32_e32 v165, v156, v164
	v_max_f32_e32 v156, v156, v164
	v_min_f32_e32 v164, v157, v165
	v_max_f32_e32 v157, v157, v165
	v_min_f32_e32 v165, v158, v164
	v_max_f32_e32 v158, v158, v164
	v_min_f32_e32 v164, v159, v165
	v_max_f32_e32 v159, v159, v165
	v_min_f32_e32 v165, v160, v164
	v_max_f32_e32 v160, v160, v164
	v_min_f32_e32 v164, v161, v165
	v_max_f32_e32 v161, v161, v165
	v_min_f32_e32 v165, v162, v164
	v_max_f32_e32 v162, v162, v164
	v_max_f32_e32 v163, v163, v165
	v_add_f32_e32 v164, v100, v12
	v_and_or_b32 v164, v164, s0, 5
	v_min_f32_e32 v165, v153, v164
	v_max_f32_e32 v153, v153, v164
	v_min_f32_e32 v164, v154, v165
	v_max_f32_e32 v154, v154, v165
	v_min_f32_e32 v165, v155, v164
	v_max_f32_e32 v155, v155, v164
	v_min_f32_e32 v164, v156, v165
	v_max_f32_e32 v156, v156, v165
	v_min_f32_e32 v165, v157, v164
	v_max_f32_e32 v157, v157, v164
	v_min_f32_e32 v164, v158, v165
	v_max_f32_e32 v158, v158, v165
	v_min_f32_e32 v165, v159, v164
	v_max_f32_e32 v159, v159, v164
; DEV void ce(float& a, float& b) { float hi = fmaxf(a, b), lo = fminf(a, b); a = hi; b = lo; }
; DEV void phase_peer_score(const Params& p, int layer, int M, char* smem) {
;     ...
;     float R[16];
; #pragma unroll
;     for (int i = 0; i < 16; i++) R[i] = -3.0e38f;
; #pragma unroll
;     for (int i = 0; i < 16; i++)
; #pragma unroll
;       for (int j = 0; j < 16; j++)
;         if ((i + 1) * (j + 1) <= 16) {
;           float v = L0[i] + L1[j];
;           v = __uint_as_float((__float_as_uint(v) & ~255u) | (unsigned)(i * 16 + j));
; #pragma unroll
;           for (int t = 0; t < 16; t++)
;             if (t >= (i + 1) * (j + 1) - 1) ce(R[t], v);
;         }
	v_min_f32_e32 v164, v160, v165
	v_max_f32_e32 v160, v160, v165
	v_min_f32_e32 v165, v161, v164
	v_max_f32_e32 v161, v161, v164
	v_min_f32_e32 v164, v162, v165
	v_max_f32_e32 v162, v162, v165
	v_max_f32_e32 v163, v163, v164
	v_add_f32_e32 v164, v100, v11
	v_and_or_b32 v164, v164, s0, 6
	v_min_f32_e32 v165, v154, v164
	v_max_f32_e32 v154, v154, v164
	v_min_f32_e32 v164, v155, v165
	v_max_f32_e32 v155, v155, v165
	v_min_f32_e32 v165, v156, v164
	v_max_f32_e32 v156, v156, v164
	v_min_f32_e32 v164, v157, v165
	v_max_f32_e32 v157, v157, v165
	v_min_f32_e32 v165, v158, v164
	v_max_f32_e32 v158, v158, v164
	v_min_f32_e32 v164, v159, v165
	v_max_f32_e32 v159, v159, v165
	v_min_f32_e32 v165, v160, v164
	v_max_f32_e32 v160, v160, v164
	v_min_f32_e32 v164, v161, v165
	v_max_f32_e32 v161, v161, v165
	v_min_f32_e32 v165, v162, v164
	v_max_f32_e32 v162, v162, v164
	v_max_f32_e32 v163, v163, v165
	v_add_f32_e32 v164, v100, v10
	v_and_or_b32 v164, v164, s0, 7
	v_min_f32_e32 v165, v155, v164
	v_max_f32_e32 v155, v155, v164
	v_min_f32_e32 v164, v156, v165
	v_max_f32_e32 v156, v156, v165
	v_min_f32_e32 v165, v157, v164
	v_max_f32_e32 v157, v157, v164
	v_min_f32_e32 v164, v158, v165
	v_max_f32_e32 v158, v158, v165
	v_min_f32_e32 v165, v159, v164
	v_max_f32_e32 v159, v159, v164
	v_min_f32_e32 v164, v160, v165
	v_max_f32_e32 v160, v160, v165
	v_min_f32_e32 v165, v161, v164
	v_max_f32_e32 v161, v161, v164
	v_min_f32_e32 v164, v162, v165
	v_max_f32_e32 v162, v162, v165
	v_max_f32_e32 v163, v163, v164
	v_add_f32_e32 v164, v100, v20
	v_and_or_b32 v164, v164, s0, 8
	v_min_f32_e32 v165, v156, v164
	v_max_f32_e32 v156, v156, v164
	v_min_f32_e32 v164, v157, v165
	v_max_f32_e32 v157, v157, v165
	v_min_f32_e32 v165, v158, v164
	v_max_f32_e32 v158, v158, v164
	v_min_f32_e32 v164, v159, v165
	v_max_f32_e32 v159, v159, v165
	v_min_f32_e32 v165, v160, v164
	v_max_f32_e32 v160, v160, v164
	v_min_f32_e32 v164, v161, v165
	v_max_f32_e32 v161, v161, v165
	v_min_f32_e32 v165, v162, v164
	v_max_f32_e32 v162, v162, v164
	v_max_f32_e32 v163, v163, v165
	v_add_f32_e32 v164, v100, v17
	v_and_or_b32 v164, v164, s0, 9
	v_min_f32_e32 v165, v157, v164
	v_max_f32_e32 v157, v157, v164
	v_min_f32_e32 v164, v158, v165
	v_max_f32_e32 v158, v158, v165
	v_min_f32_e32 v165, v159, v164
	v_max_f32_e32 v159, v159, v164
	v_min_f32_e32 v164, v160, v165
	v_max_f32_e32 v160, v160, v165
	v_min_f32_e32 v165, v161, v164
	v_max_f32_e32 v161, v161, v164
	v_min_f32_e32 v164, v162, v165
	v_max_f32_e32 v162, v162, v165
	v_max_f32_e32 v163, v163, v164
	v_add_f32_e32 v164, v100, v16
	v_and_or_b32 v164, v164, s0, 10
	v_min_f32_e32 v165, v158, v164
	v_max_f32_e32 v158, v158, v164
	v_min_f32_e32 v164, v159, v165
	v_max_f32_e32 v159, v159, v165
	v_min_f32_e32 v165, v160, v164
	v_max_f32_e32 v160, v160, v164
	v_min_f32_e32 v164, v161, v165
	v_max_f32_e32 v161, v161, v165
	v_min_f32_e32 v165, v162, v164
	v_max_f32_e32 v162, v162, v164
	v_max_f32_e32 v163, v163, v165
	v_add_f32_e32 v164, v100, v15
	v_and_or_b32 v164, v164, s0, 11
	v_min_f32_e32 v165, v159, v164
	v_max_f32_e32 v159, v159, v164
	v_min_f32_e32 v164, v160, v165
	v_max_f32_e32 v160, v160, v165
	v_min_f32_e32 v165, v161, v164
	v_max_f32_e32 v161, v161, v164
	v_min_f32_e32 v164, v162, v165
	v_max_f32_e32 v162, v162, v165
	v_max_f32_e32 v163, v163, v164
	v_add_f32_e32 v164, v100, v14
	v_and_or_b32 v164, v164, s0, 12
	v_min_f32_e32 v165, v160, v164
	v_max_f32_e32 v160, v160, v164
	v_min_f32_e32 v164, v161, v165
	v_max_f32_e32 v161, v161, v165
	v_min_f32_e32 v165, v162, v164
	v_max_f32_e32 v162, v162, v164
	v_max_f32_e32 v163, v163, v165
	v_add_f32_e32 v164, v100, v13
	v_and_or_b32 v164, v164, s0, 13
	v_min_f32_e32 v165, v161, v164
	v_max_f32_e32 v161, v161, v164
	v_min_f32_e32 v164, v162, v165
	v_max_f32_e32 v162, v162, v165
	v_max_f32_e32 v163, v163, v164
	v_add_f32_e32 v164, v100, v6
	v_and_or_b32 v164, v164, s0, 14
	v_min_f32_e32 v165, v162, v164
	v_max_f32_e32 v162, v162, v164
	v_max_f32_e32 v163, v163, v165
	v_add_f32_e32 v164, v100, v5
	v_and_or_b32 v164, v164, s0, 15
	v_max_f32_e32 v163, v163, v164
	v_add_f32_e32 v164, v91, v2
	v_and_or_b32 v164, v164, s0, 16
	v_min_f32_e32 v165, v149, v164
	v_max_f32_e32 v149, v149, v164
	v_min_f32_e32 v164, v150, v165
	v_max_f32_e32 v150, v150, v165
	v_min_f32_e32 v165, v151, v164
	v_max_f32_e32 v151, v151, v164
	v_min_f32_e32 v164, v152, v165
	v_max_f32_e32 v152, v152, v165
	v_min_f32_e32 v165, v153, v164
	v_max_f32_e32 v153, v153, v164
	v_min_f32_e32 v164, v154, v165
	v_max_f32_e32 v154, v154, v165
	v_min_f32_e32 v165, v155, v164
	v_max_f32_e32 v155, v155, v164
	v_min_f32_e32 v164, v156, v165
	v_max_f32_e32 v156, v156, v165
	v_min_f32_e32 v165, v157, v164
	v_max_f32_e32 v157, v157, v164
	v_min_f32_e32 v164, v158, v165
	v_max_f32_e32 v158, v158, v165
	v_min_f32_e32 v165, v159, v164
	v_max_f32_e32 v159, v159, v164
	v_min_f32_e32 v164, v160, v165
	v_max_f32_e32 v160, v160, v165
	v_min_f32_e32 v165, v161, v164
	v_max_f32_e32 v161, v161, v164
	v_min_f32_e32 v164, v162, v165
	v_max_f32_e32 v162, v162, v165
	v_max_f32_e32 v163, v163, v164
	v_add_f32_e32 v164, v91, v4
	v_and_or_b32 v164, v164, s0, 17
	v_min_f32_e32 v165, v151, v164
	v_max_f32_e32 v151, v151, v164
	v_min_f32_e32 v164, v152, v165
	v_max_f32_e32 v152, v152, v165
	v_min_f32_e32 v165, v153, v164
	v_max_f32_e32 v153, v153, v164
	v_min_f32_e32 v164, v154, v165
	v_max_f32_e32 v154, v154, v165
	v_min_f32_e32 v165, v155, v164
	v_max_f32_e32 v155, v155, v164
	v_min_f32_e32 v164, v156, v165
	v_max_f32_e32 v156, v156, v165
	v_min_f32_e32 v165, v157, v164
	v_max_f32_e32 v157, v157, v164
	v_min_f32_e32 v164, v158, v165
	v_max_f32_e32 v158, v158, v165
	v_min_f32_e32 v165, v159, v164
; DEV void ce(float& a, float& b) { float hi = fmaxf(a, b), lo = fminf(a, b); a = hi; b = lo; }
; DEV void phase_peer_score(const Params& p, int layer, int M, char* smem) {
;     ...
;     float R[16];
; #pragma unroll
;     for (int i = 0; i < 16; i++) R[i] = -3.0e38f;
; #pragma unroll
;     for (int i = 0; i < 16; i++)
; #pragma unroll
;       for (int j = 0; j < 16; j++)
;         if ((i + 1) * (j + 1) <= 16) {
;           float v = L0[i] + L1[j];
;           v = __uint_as_float((__float_as_uint(v) & ~255u) | (unsigned)(i * 16 + j));
; #pragma unroll
;           for (int t = 0; t < 16; t++)
;             if (t >= (i + 1) * (j + 1) - 1) ce(R[t], v);
;         }
	v_max_f32_e32 v159, v159, v164
	v_min_f32_e32 v164, v160, v165
	v_max_f32_e32 v160, v160, v165
	v_min_f32_e32 v165, v161, v164
	v_max_f32_e32 v161, v161, v164
	v_min_f32_e32 v164, v162, v165
	v_max_f32_e32 v162, v162, v165
	v_max_f32_e32 v163, v163, v164
	v_add_f32_e32 v164, v91, v7
	v_and_or_b32 v164, v164, s0, 18
	v_min_f32_e32 v165, v153, v164
	v_max_f32_e32 v153, v153, v164
	v_min_f32_e32 v164, v154, v165
	v_max_f32_e32 v154, v154, v165
	v_min_f32_e32 v165, v155, v164
	v_max_f32_e32 v155, v155, v164
	v_min_f32_e32 v164, v156, v165
	v_max_f32_e32 v156, v156, v165
	v_min_f32_e32 v165, v157, v164
	v_max_f32_e32 v157, v157, v164
	v_min_f32_e32 v164, v158, v165
	v_max_f32_e32 v158, v158, v165
	v_min_f32_e32 v165, v159, v164
	v_max_f32_e32 v159, v159, v164
	v_min_f32_e32 v164, v160, v165
	v_max_f32_e32 v160, v160, v165
	v_min_f32_e32 v165, v161, v164
	v_max_f32_e32 v161, v161, v164
	v_min_f32_e32 v164, v162, v165
	v_max_f32_e32 v162, v162, v165
	v_max_f32_e32 v163, v163, v164
	v_add_f32_e32 v164, v91, v8
	v_and_or_b32 v164, v164, s0, 19
	v_min_f32_e32 v165, v155, v164
	v_max_f32_e32 v155, v155, v164
	v_min_f32_e32 v164, v156, v165
	v_max_f32_e32 v156, v156, v165
	v_min_f32_e32 v165, v157, v164
	v_max_f32_e32 v157, v157, v164
	v_min_f32_e32 v164, v158, v165
	v_max_f32_e32 v158, v158, v165
	v_min_f32_e32 v165, v159, v164
	v_max_f32_e32 v159, v159, v164
	v_min_f32_e32 v164, v160, v165
	v_max_f32_e32 v160, v160, v165
	v_min_f32_e32 v165, v161, v164
	v_max_f32_e32 v161, v161, v164
	v_min_f32_e32 v164, v162, v165
	v_max_f32_e32 v162, v162, v165
	v_max_f32_e32 v163, v163, v164
	v_add_f32_e32 v164, v91, v9
	v_and_or_b32 v164, v164, s0, 20
	v_min_f32_e32 v165, v157, v164
	v_max_f32_e32 v157, v157, v164
	v_min_f32_e32 v164, v158, v165
	v_max_f32_e32 v158, v158, v165
	v_min_f32_e32 v165, v159, v164
	v_max_f32_e32 v159, v159, v164
	v_min_f32_e32 v164, v160, v165
	v_max_f32_e32 v160, v160, v165
	v_min_f32_e32 v165, v161, v164
	v_max_f32_e32 v161, v161, v164
	v_min_f32_e32 v164, v162, v165
	v_max_f32_e32 v162, v162, v165
	v_max_f32_e32 v163, v163, v164
	v_add_f32_e32 v164, v91, v12
	v_and_or_b32 v164, v164, s0, 21
	v_min_f32_e32 v165, v159, v164
	v_max_f32_e32 v159, v159, v164
	v_min_f32_e32 v164, v160, v165
	v_max_f32_e32 v160, v160, v165
	v_min_f32_e32 v165, v161, v164
	v_max_f32_e32 v161, v161, v164
	v_min_f32_e32 v164, v162, v165
	v_max_f32_e32 v162, v162, v165
	v_max_f32_e32 v163, v163, v164
	v_add_f32_e32 v164, v91, v11
	v_and_or_b32 v164, v164, s0, 22
	v_min_f32_e32 v165, v161, v164
	v_max_f32_e32 v161, v161, v164
	v_min_f32_e32 v164, v162, v165
	v_max_f32_e32 v162, v162, v165
	v_max_f32_e32 v163, v163, v164
	v_add_f32_e32 v164, v91, v10
	v_and_or_b32 v164, v164, s0, 23
	v_max_f32_e32 v163, v163, v164
	v_add_f32_e32 v164, v87, v2
	v_and_or_b32 v164, v164, s0, 32
	v_min_f32_e32 v165, v150, v164
	v_max_f32_e32 v150, v150, v164
	v_min_f32_e32 v164, v151, v165
	v_max_f32_e32 v151, v151, v165
	v_min_f32_e32 v165, v152, v164
	v_max_f32_e32 v152, v152, v164
	v_min_f32_e32 v164, v153, v165
	v_max_f32_e32 v153, v153, v165
	v_min_f32_e32 v165, v154, v164
	v_max_f32_e32 v154, v154, v164
	v_min_f32_e32 v164, v155, v165
	v_max_f32_e32 v155, v155, v165
	v_min_f32_e32 v165, v156, v164
	v_max_f32_e32 v156, v156, v164
	v_min_f32_e32 v164, v157, v165
	v_max_f32_e32 v157, v157, v165
	v_min_f32_e32 v165, v158, v164
	v_max_f32_e32 v158, v158, v164
	v_min_f32_e32 v164, v159, v165
	v_max_f32_e32 v159, v159, v165
	v_min_f32_e32 v165, v160, v164
	v_max_f32_e32 v160, v160, v164
	v_min_f32_e32 v164, v161, v165
	v_max_f32_e32 v161, v161, v165
	v_min_f32_e32 v165, v162, v164
	v_max_f32_e32 v162, v162, v164
	v_max_f32_e32 v163, v163, v165
	v_add_f32_e32 v164, v87, v4
	v_and_or_b32 v164, v164, s0, 33
	v_min_f32_e32 v165, v153, v164
	v_max_f32_e32 v153, v153, v164
	v_min_f32_e32 v164, v154, v165
	v_max_f32_e32 v154, v154, v165
	v_min_f32_e32 v165, v155, v164
	v_max_f32_e32 v155, v155, v164
	v_min_f32_e32 v164, v156, v165
	v_max_f32_e32 v156, v156, v165
	v_min_f32_e32 v165, v157, v164
	v_max_f32_e32 v157, v157, v164
	v_min_f32_e32 v164, v158, v165
	v_max_f32_e32 v158, v158, v165
	v_min_f32_e32 v165, v159, v164
	v_max_f32_e32 v159, v159, v164
	v_min_f32_e32 v164, v160, v165
	v_max_f32_e32 v160, v160, v165
	v_min_f32_e32 v165, v161, v164
	v_max_f32_e32 v161, v161, v164
	v_min_f32_e32 v164, v162, v165
	v_max_f32_e32 v162, v162, v165
	v_max_f32_e32 v163, v163, v164
	v_add_f32_e32 v164, v87, v7
	v_and_or_b32 v164, v164, s0, 34
	v_min_f32_e32 v165, v156, v164
	v_max_f32_e32 v156, v156, v164
	v_min_f32_e32 v164, v157, v165
	v_max_f32_e32 v157, v157, v165
	v_min_f32_e32 v165, v158, v164
	v_max_f32_e32 v158, v158, v164
	v_min_f32_e32 v164, v159, v165
	v_max_f32_e32 v159, v159, v165
	v_min_f32_e32 v165, v160, v164
	v_max_f32_e32 v160, v160, v164
	v_min_f32_e32 v164, v161, v165
	v_max_f32_e32 v161, v161, v165
	v_min_f32_e32 v165, v162, v164
	v_max_f32_e32 v162, v162, v164
	v_max_f32_e32 v163, v163, v165
	v_add_f32_e32 v164, v87, v8
	v_and_or_b32 v164, v164, s0, 35
	v_min_f32_e32 v165, v159, v164
	v_max_f32_e32 v159, v159, v164
	v_min_f32_e32 v164, v160, v165
	v_max_f32_e32 v160, v160, v165
	v_min_f32_e32 v165, v161, v164
	v_max_f32_e32 v161, v161, v164
	v_min_f32_e32 v164, v162, v165
	v_max_f32_e32 v162, v162, v165
	v_max_f32_e32 v163, v163, v164
	v_add_f32_e32 v164, v87, v9
	v_and_or_b32 v164, v164, s0, 36
	v_min_f32_e32 v165, v162, v164
	v_max_f32_e32 v162, v162, v164
	v_max_f32_e32 v163, v163, v165
	v_add_f32_e32 v164, v83, v2
	v_and_or_b32 v164, v164, s0, 48
	v_min_f32_e32 v165, v151, v164
	v_max_f32_e32 v151, v151, v164
	v_min_f32_e32 v164, v152, v165
	v_max_f32_e32 v152, v152, v165
; DEV void ce(float& a, float& b) { float hi = fmaxf(a, b), lo = fminf(a, b); a = hi; b = lo; }
; DEV void phase_peer_score(const Params& p, int layer, int M, char* smem) {
;     ...
;     float R[16];
; #pragma unroll
;     for (int i = 0; i < 16; i++) R[i] = -3.0e38f;
; #pragma unroll
;     for (int i = 0; i < 16; i++)
; #pragma unroll
;       for (int j = 0; j < 16; j++)
;         if ((i + 1) * (j + 1) <= 16) {
;           float v = L0[i] + L1[j];
;           v = __uint_as_float((__float_as_uint(v) & ~255u) | (unsigned)(i * 16 + j));
; #pragma unroll
;           for (int t = 0; t < 16; t++)
;             if (t >= (i + 1) * (j + 1) - 1) ce(R[t], v);
;         }
	v_min_f32_e32 v165, v153, v164
	v_max_f32_e32 v153, v153, v164
	v_min_f32_e32 v164, v154, v165
	v_max_f32_e32 v154, v154, v165
	v_min_f32_e32 v165, v155, v164
	v_max_f32_e32 v155, v155, v164
	v_min_f32_e32 v164, v156, v165
	v_max_f32_e32 v156, v156, v165
	v_min_f32_e32 v165, v157, v164
	v_max_f32_e32 v157, v157, v164
	v_min_f32_e32 v164, v158, v165
	v_max_f32_e32 v158, v158, v165
	v_min_f32_e32 v165, v159, v164
	v_max_f32_e32 v159, v159, v164
	v_min_f32_e32 v164, v160, v165
	v_max_f32_e32 v160, v160, v165
	v_min_f32_e32 v165, v161, v164
	v_max_f32_e32 v161, v161, v164
	v_min_f32_e32 v164, v162, v165
	v_max_f32_e32 v162, v162, v165
	v_max_f32_e32 v163, v163, v164
	v_add_f32_e32 v164, v83, v4
	v_and_or_b32 v164, v164, s0, 49
	v_min_f32_e32 v165, v155, v164
	v_max_f32_e32 v155, v155, v164
	v_min_f32_e32 v164, v156, v165
	v_max_f32_e32 v156, v156, v165
	v_min_f32_e32 v165, v157, v164
	v_max_f32_e32 v157, v157, v164
	v_min_f32_e32 v164, v158, v165
	v_max_f32_e32 v158, v158, v165
	v_min_f32_e32 v165, v159, v164
	v_max_f32_e32 v159, v159, v164
	v_min_f32_e32 v164, v160, v165
	v_max_f32_e32 v160, v160, v165
	v_min_f32_e32 v165, v161, v164
	v_max_f32_e32 v161, v161, v164
	v_min_f32_e32 v164, v162, v165
	v_max_f32_e32 v162, v162, v165
	v_max_f32_e32 v163, v163, v164
	v_add_f32_e32 v164, v83, v7
	v_and_or_b32 v164, v164, s0, 50
	v_min_f32_e32 v165, v159, v164
	v_max_f32_e32 v159, v159, v164
	v_min_f32_e32 v164, v160, v165
	v_max_f32_e32 v160, v160, v165
	v_min_f32_e32 v165, v161, v164
	v_max_f32_e32 v161, v161, v164
	v_min_f32_e32 v164, v162, v165
	v_max_f32_e32 v162, v162, v165
	v_max_f32_e32 v163, v163, v164
	v_add_f32_e32 v164, v83, v8
	v_and_or_b32 v164, v164, s0, 51
	v_max_f32_e32 v163, v163, v164
	v_add_f32_e32 v164, v79, v2
	v_and_or_b32 v164, v164, s0, 64
	v_min_f32_e32 v165, v152, v164
	v_max_f32_e32 v152, v152, v164
	v_min_f32_e32 v164, v153, v165
	v_max_f32_e32 v153, v153, v165
	v_min_f32_e32 v165, v154, v164
	v_max_f32_e32 v154, v154, v164
	v_min_f32_e32 v164, v155, v165
	v_max_f32_e32 v155, v155, v165
	v_min_f32_e32 v165, v156, v164
	v_max_f32_e32 v156, v156, v164
	v_min_f32_e32 v164, v157, v165
	v_max_f32_e32 v157, v157, v165
	v_min_f32_e32 v165, v158, v164
	v_max_f32_e32 v158, v158, v164
	v_min_f32_e32 v164, v159, v165
	v_max_f32_e32 v159, v159, v165
	v_min_f32_e32 v165, v160, v164
	v_max_f32_e32 v160, v160, v164
	v_min_f32_e32 v164, v161, v165
	v_max_f32_e32 v161, v161, v165
	v_min_f32_e32 v165, v162, v164
	v_max_f32_e32 v162, v162, v164
	v_max_f32_e32 v163, v163, v165
	v_add_f32_e32 v164, v79, v4
	v_and_b32_e32 v164, 0xffffff00, v164
	v_or_b32_e32 v164, 0x41, v164
	v_min_f32_e32 v165, v157, v164
	v_max_f32_e32 v157, v157, v164
	v_min_f32_e32 v164, v158, v165
	v_max_f32_e32 v158, v158, v165
	v_min_f32_e32 v165, v159, v164
	v_max_f32_e32 v159, v159, v164
	v_min_f32_e32 v164, v160, v165
	v_max_f32_e32 v160, v160, v165
	v_min_f32_e32 v165, v161, v164
	v_max_f32_e32 v161, v161, v164
	v_min_f32_e32 v164, v162, v165
	v_max_f32_e32 v162, v162, v165
	v_max_f32_e32 v163, v163, v164
	v_add_f32_e32 v164, v79, v7
	v_and_b32_e32 v164, 0xffffff00, v164
	v_or_b32_e32 v164, 0x42, v164
	v_min_f32_e32 v165, v162, v164
	v_max_f32_e32 v162, v162, v164
	v_max_f32_e32 v163, v163, v165
	v_add_f32_e32 v164, v75, v2
	v_and_b32_e32 v164, 0xffffff00, v164
	v_or_b32_e32 v164, 0x50, v164
	v_min_f32_e32 v165, v153, v164
	v_max_f32_e32 v153, v153, v164
	v_min_f32_e32 v164, v154, v165
	v_max_f32_e32 v154, v154, v165
	v_min_f32_e32 v165, v155, v164
	v_max_f32_e32 v155, v155, v164
	v_min_f32_e32 v164, v156, v165
	v_max_f32_e32 v156, v156, v165
	v_min_f32_e32 v165, v157, v164
	v_max_f32_e32 v157, v157, v164
	v_min_f32_e32 v164, v158, v165
	v_max_f32_e32 v158, v158, v165
	v_min_f32_e32 v165, v159, v164
	v_max_f32_e32 v159, v159, v164
	v_min_f32_e32 v164, v160, v165
	v_max_f32_e32 v160, v160, v165
	v_min_f32_e32 v165, v161, v164
	v_max_f32_e32 v161, v161, v164
	v_min_f32_e32 v164, v162, v165
	v_max_f32_e32 v162, v162, v165
	v_max_f32_e32 v163, v163, v164
	v_add_f32_e32 v164, v75, v4
	v_and_b32_e32 v164, 0xffffff00, v164
	v_or_b32_e32 v164, 0x51, v164
	v_min_f32_e32 v165, v159, v164
	v_max_f32_e32 v159, v159, v164
	v_min_f32_e32 v164, v160, v165
	v_max_f32_e32 v160, v160, v165
	v_min_f32_e32 v165, v161, v164
	v_max_f32_e32 v161, v161, v164
	v_min_f32_e32 v164, v162, v165
	v_max_f32_e32 v162, v162, v165
	v_max_f32_e32 v163, v163, v164
	v_add_f32_e32 v164, v71, v2
	v_and_b32_e32 v164, 0xffffff00, v164
	v_or_b32_e32 v164, 0x60, v164
	v_min_f32_e32 v165, v154, v164
	v_max_f32_e32 v154, v154, v164
	v_min_f32_e32 v164, v155, v165
	v_max_f32_e32 v155, v155, v165
	v_min_f32_e32 v165, v156, v164
	v_max_f32_e32 v156, v156, v164
	v_min_f32_e32 v164, v157, v165
	v_max_f32_e32 v157, v157, v165
	v_min_f32_e32 v165, v158, v164
	v_max_f32_e32 v158, v158, v164
	v_min_f32_e32 v164, v159, v165
	v_max_f32_e32 v159, v159, v165
	v_min_f32_e32 v165, v160, v164
	v_max_f32_e32 v160, v160, v164
	v_min_f32_e32 v164, v161, v165
	v_max_f32_e32 v161, v161, v165
	v_min_f32_e32 v165, v162, v164
	v_max_f32_e32 v162, v162, v164
	v_max_f32_e32 v163, v163, v165
	v_add_f32_e32 v164, v71, v4
	v_and_b32_e32 v164, 0xffffff00, v164
	v_or_b32_e32 v164, 0x61, v164
	v_min_f32_e32 v165, v161, v164
	v_max_f32_e32 v161, v161, v164
	v_min_f32_e32 v164, v162, v165
	v_max_f32_e32 v162, v162, v165
	v_max_f32_e32 v163, v163, v164
	v_add_f32_e32 v164, v63, v2
	v_and_b32_e32 v164, 0xffffff00, v164
	v_or_b32_e32 v164, 0x70, v164
	v_min_f32_e32 v165, v155, v164
	v_max_f32_e32 v155, v155, v164
	v_min_f32_e32 v164, v156, v165
	v_max_f32_e32 v156, v156, v165
	v_min_f32_e32 v165, v157, v164
	v_max_f32_e32 v157, v157, v164
; DEV void ce(float& a, float& b) { float hi = fmaxf(a, b), lo = fminf(a, b); a = hi; b = lo; }
; DEV void phase_peer_score(const Params& p, int layer, int M, char* smem) {
;     ...
;     float R[16];
; #pragma unroll
;     for (int i = 0; i < 16; i++) R[i] = -3.0e38f;
; #pragma unroll
;     for (int i = 0; i < 16; i++)
; #pragma unroll
;       for (int j = 0; j < 16; j++)
;         if ((i + 1) * (j + 1) <= 16) {
;           float v = L0[i] + L1[j];
;           v = __uint_as_float((__float_as_uint(v) & ~255u) | (unsigned)(i * 16 + j));
; #pragma unroll
;           for (int t = 0; t < 16; t++)
;             if (t >= (i + 1) * (j + 1) - 1) ce(R[t], v);
;         }
;     unsigned char* tab = (unsigned char*)smem + 73728 + (w * 16 + l15) * 32;
; #pragma unroll
;     for (int i = 0; i < 16; i++) { tab[i] = (unsigned char)(__float_as_uint(L0[i]) & 127u); tab[16 + i] = (unsigned char)(__float_as_uint(L1[i]) & 127u); }
;     float ev[16]; float sum = 0.f;
; #pragma unroll
;     for (int t = 0; t < 16; t++) { ev[t] = __expf(R[t] - R[0]); sum += ev[t]; }
;     const float inv = 1.f / sum;
;     int eid[16];
; #pragma unroll
;     for (int t = 0; t < 16; t++) {
;       unsigned code = __float_as_uint(R[t]) & 255u;
;       eid[t] = (int)tab[code >> 4] * 128 + (int)tab[16 + (code & 15u)];
	v_min_f32_e32 v164, v158, v165
	v_max_f32_e32 v158, v158, v165
	v_min_f32_e32 v165, v159, v164
	v_max_f32_e32 v159, v159, v164
	v_min_f32_e32 v164, v160, v165
	v_max_f32_e32 v160, v160, v165
	v_min_f32_e32 v165, v161, v164
	v_max_f32_e32 v161, v161, v164
	v_min_f32_e32 v164, v162, v165
	v_max_f32_e32 v162, v162, v165
	v_max_f32_e32 v163, v163, v164
	v_add_f32_e32 v164, v63, v4
	v_and_b32_e32 v164, 0xffffff00, v164
	v_or_b32_e32 v164, 0x71, v164
	v_max_f32_e32 v163, v163, v164
	v_add_f32_e32 v164, v67, v2
	v_and_b32_e32 v164, 0xffffff00, v164
	v_or_b32_e32 v164, 0x80, v164
	v_min_f32_e32 v165, v156, v164
	v_max_f32_e32 v156, v156, v164
	v_min_f32_e32 v164, v157, v165
	v_max_f32_e32 v157, v157, v165
	v_min_f32_e32 v165, v158, v164
	v_max_f32_e32 v158, v158, v164
	v_min_f32_e32 v164, v159, v165
	v_max_f32_e32 v159, v159, v165
	v_min_f32_e32 v165, v160, v164
	v_max_f32_e32 v160, v160, v164
	v_min_f32_e32 v164, v161, v165
	v_max_f32_e32 v161, v161, v165
	v_min_f32_e32 v165, v162, v164
	v_max_f32_e32 v162, v162, v164
	v_max_f32_e32 v163, v163, v165
	v_add_f32_e32 v164, v59, v2
	v_and_b32_e32 v164, 0xffffff00, v164
	v_or_b32_e32 v164, 0x90, v164
	v_min_f32_e32 v165, v157, v164
	v_max_f32_e32 v157, v157, v164
	v_min_f32_e32 v164, v158, v165
	v_max_f32_e32 v158, v158, v165
	v_min_f32_e32 v165, v159, v164
	v_max_f32_e32 v159, v159, v164
	v_min_f32_e32 v164, v160, v165
	v_max_f32_e32 v160, v160, v165
	v_min_f32_e32 v165, v161, v164
	v_max_f32_e32 v161, v161, v164
	v_min_f32_e32 v164, v162, v165
	v_max_f32_e32 v162, v162, v165
	v_max_f32_e32 v163, v163, v164
	v_add_f32_e32 v164, v55, v2
	v_and_b32_e32 v164, 0xffffff00, v164
	v_or_b32_e32 v164, 0xa0, v164
	v_min_f32_e32 v165, v158, v164
	v_max_f32_e32 v158, v158, v164
	v_min_f32_e32 v164, v159, v165
	v_max_f32_e32 v159, v159, v165
	v_min_f32_e32 v165, v160, v164
	v_max_f32_e32 v160, v160, v164
	v_min_f32_e32 v164, v161, v165
	v_max_f32_e32 v161, v161, v165
	v_min_f32_e32 v165, v162, v164
	v_max_f32_e32 v162, v162, v164
	v_max_f32_e32 v163, v163, v165
	v_add_f32_e32 v164, v47, v2
	v_and_b32_e32 v164, 0xffffff00, v164
	v_or_b32_e32 v164, 0xb0, v164
	v_min_f32_e32 v165, v159, v164
	v_max_f32_e32 v159, v159, v164
	v_min_f32_e32 v164, v160, v165
	v_max_f32_e32 v160, v160, v165
	v_min_f32_e32 v165, v161, v164
	v_max_f32_e32 v161, v161, v164
	v_min_f32_e32 v164, v162, v165
	v_max_f32_e32 v162, v162, v165
	v_max_f32_e32 v163, v163, v164
	v_add_f32_e32 v164, v51, v2
	v_and_b32_e32 v164, 0xffffff00, v164
	v_or_b32_e32 v164, 0xc0, v164
	v_min_f32_e32 v165, v160, v164
	v_max_f32_e32 v160, v160, v164
	v_min_f32_e32 v164, v161, v165
	v_max_f32_e32 v161, v161, v165
	v_min_f32_e32 v165, v162, v164
	v_max_f32_e32 v162, v162, v164
	v_max_f32_e32 v163, v163, v165
	v_add_f32_e32 v164, v39, v2
	v_and_b32_e32 v164, 0xffffff00, v164
	v_or_b32_e32 v164, 0xd0, v164
	v_min_f32_e32 v165, v161, v164
	v_max_f32_e32 v161, v161, v164
	v_min_f32_e32 v164, v162, v165
	v_max_f32_e32 v162, v162, v165
	v_max_f32_e32 v163, v163, v164
	v_add_f32_e32 v164, v43, v2
	v_and_b32_e32 v164, 0xffffff00, v164
	v_or_b32_e32 v164, 0xe0, v164
	v_min_f32_e32 v165, v162, v164
	v_max_f32_e32 v162, v162, v164
	v_max_f32_e32 v163, v163, v165
	v_add_f32_e32 v164, v0, v2
	v_and_b32_e32 v164, 0xffffff00, v164
	v_or_b32_e32 v164, 0xf0, v164
	v_max_f32_e32 v163, v163, v164
.Lmed3_ok_bb_172:
	s_lshl_b32 s0, s18, 3
	s_andn2_b32 s0, s0, 63
	v_add_u32_e32 v18, s0, v117
	s_movk_i32 s0, 0xff00
	v_sub_f32_e32 v5, v149, v148
	v_mul_f32_e32 v5, 0x3fb8aa3b, v5
	v_exp_f32_e32 v101, v5
	v_sub_f32_e32 v5, v150, v148
	v_mul_f32_e32 v5, 0x3fb8aa3b, v5
	v_exp_f32_e32 v104, v5
	v_sub_f32_e32 v5, v151, v148
	v_mul_f32_e32 v5, 0x3fb8aa3b, v5
	v_exp_f32_e32 v105, v5
	v_sub_f32_e32 v5, v152, v148
	v_mul_f32_e32 v5, 0x3fb8aa3b, v5
	v_exp_f32_e32 v102, v5
	v_sub_f32_e32 v5, v153, v148
	v_mul_f32_e32 v5, 0x3fb8aa3b, v5
	v_exp_f32_e32 v103, v5
	v_sub_f32_e32 v5, v154, v148
	v_mul_f32_e32 v5, 0x3fb8aa3b, v5
	v_exp_f32_e32 v110, v5
	v_sub_f32_e32 v5, v155, v148
	v_sub_f32_e32 v3, v148, v148
	v_mul_f32_e32 v5, 0x3fb8aa3b, v5
	v_mul_f32_e32 v3, 0x3fb8aa3b, v3
	v_exp_f32_e32 v111, v5
	v_sub_f32_e32 v5, v156, v148
	v_exp_f32_e32 v100, v3
	v_mul_f32_e32 v5, 0x3fb8aa3b, v5
	v_exp_f32_e32 v112, v5
	v_sub_f32_e32 v5, v157, v148
	v_mul_f32_e32 v5, 0x3fb8aa3b, v5
	v_exp_f32_e32 v113, v5
	v_sub_f32_e32 v5, v158, v148
	v_add_f32_e32 v3, 0, v100
	v_mul_f32_e32 v5, 0x3fb8aa3b, v5
	v_add_f32_e32 v3, v3, v101
	v_exp_f32_e32 v114, v5
	v_sub_f32_e32 v5, v159, v148
	v_add_f32_e32 v3, v3, v104
	v_mul_f32_e32 v5, 0x3fb8aa3b, v5
	v_add_f32_e32 v3, v3, v105
	v_exp_f32_e32 v115, v5
	v_sub_f32_e32 v5, v160, v148
	v_add_f32_e32 v3, v3, v102
	v_mul_f32_e32 v5, 0x3fb8aa3b, v5
	v_add_f32_e32 v3, v3, v103
	v_exp_f32_e32 v106, v5
	v_sub_f32_e32 v5, v161, v148
	v_add_f32_e32 v3, v3, v110
	v_mul_f32_e32 v5, 0x3fb8aa3b, v5
	v_add_f32_e32 v3, v3, v111
	v_exp_f32_e32 v107, v5
	v_sub_f32_e32 v5, v162, v148
	v_add_f32_e32 v3, v3, v112
	v_mul_f32_e32 v5, 0x3fb8aa3b, v5
	v_add_f32_e32 v3, v3, v113
	v_exp_f32_e32 v108, v5
	v_sub_f32_e32 v5, v163, v148
	v_add_f32_e32 v3, v3, v114
	v_mul_f32_e32 v5, 0x3fb8aa3b, v5
	v_add_f32_e32 v3, v3, v115
	v_exp_f32_e32 v109, v5
	v_add_f32_e32 v3, v3, v106
	v_add_f32_e32 v3, v3, v107
	v_add_f32_e32 v3, v3, v108
	v_add_f32_e32 v3, v3, v109
	v_div_scale_f32 v5, s[0:1], v3, v3, 1.0
	v_rcp_f32_e32 v6, v5
	v_ashrrev_i32_e32 v19, 31, v18
	s_mov_b32 s0, 0x10000
	v_lshlrev_b64 v[120:121], 9, v[18:19]
	v_fma_f32 v17, -v5, v6, 1.0
	v_fmac_f32_e32 v6, v17, v6
	v_div_scale_f32 v17, vcc, 1.0, v3, 1.0
	v_mul_f32_e32 v20, v17, v6
	v_fma_f32 v21, -v5, v20, v17
	v_fmac_f32_e32 v20, v21, v6
	v_fma_f32 v5, -v5, v20, v17
	v_div_fmas_f32 v5, v5, v6, v20
	v_div_fixup_f32 v116, v5, v3, 1.0
	v_bfe_u32 v3, v163, 4, 4
	v_and_b32_e32 v2, 15, v163
	v_and_b32_e32 v17, 15, v155
	v_add_u32_e32 v3, v138, v3
	v_add_u32_e32 v2, v138, v2
	v_add_u32_e32 v17, v138, v17
	ds_read_u8 v3, v3
	ds_read_u8 v17, v17 offset:16
	ds_read_u8 v2, v2 offset:16
	v_and_b32_e32 v6, 15, v160
	v_add_u32_e32 v6, v138, v6
	ds_read_u8 v6, v6 offset:16
	v_lshl_add_u64 v[18:19], s[8:9], 0, v[120:121]
	s_waitcnt lgkmcnt(1)
; DEV void phase_peer_score(const Params& p, int layer, int M, char* smem) {
;     ...
;     int eid[16];
; #pragma unroll
;     for (int t = 0; t < 16; t++) {
;       unsigned code = __float_as_uint(R[t]) & 255u;
;       eid[t] = (int)tab[code >> 4] * 128 + (int)tab[16 + (code & 15u)];
;     }
;     if (quad == 0) {
;       int* eo = EIDX + (size_t)m * 128 + h * 16;
;       float* go = GATE + (size_t)m * 128 + h * 16;
;       float* uo = go + (size_t)MT * 128;
	v_lshl_add_u32 v5, v3, 7, v2
	v_bfe_u32 v2, v162, 4, 4
	v_and_b32_e32 v3, 15, v162
	v_add_u32_e32 v2, v138, v2
	v_add_u32_e32 v3, v138, v3
	ds_read_u8 v2, v2
	ds_read_u8 v3, v3 offset:16
	s_lshl_b32 s52, s19, 6
	v_lshl_add_u64 v[118:119], v[18:19], 0, s[52:53]
	v_lshl_add_u64 v[120:121], s[6:7], 0, v[120:121]
	v_lshl_add_u64 v[120:121], v[120:121], 0, s[52:53]
	s_waitcnt lgkmcnt(0)
	v_lshl_add_u32 v4, v2, 7, v3
	v_bfe_u32 v2, v161, 4, 4
	v_and_b32_e32 v3, 15, v161
	v_add_u32_e32 v2, v138, v2
	v_add_u32_e32 v3, v138, v3
	ds_read_u8 v2, v2
	ds_read_u8 v3, v3 offset:16
	v_and_b32_e32 v7, 15, v159
	v_add_u32_e32 v7, v138, v7
	ds_read_u8 v7, v7 offset:16
	s_waitcnt lgkmcnt(1)
	v_lshl_add_u32 v3, v2, 7, v3
	v_bfe_u32 v2, v160, 4, 4
	v_add_u32_e32 v2, v138, v2
	ds_read_u8 v2, v2
	s_waitcnt lgkmcnt(0)
	v_lshl_add_u32 v2, v2, 7, v6
	v_bfe_u32 v6, v159, 4, 4
	v_add_u32_e32 v6, v138, v6
	ds_read_u8 v6, v6
	s_waitcnt lgkmcnt(0)
	v_lshl_add_u32 v9, v6, 7, v7
	v_bfe_u32 v6, v158, 4, 4
	v_and_b32_e32 v7, 15, v158
	v_add_u32_e32 v6, v138, v6
	v_add_u32_e32 v7, v138, v7
	ds_read_u8 v6, v6
	ds_read_u8 v7, v7 offset:16
	s_waitcnt lgkmcnt(0)
	v_lshl_add_u32 v8, v6, 7, v7
	v_bfe_u32 v6, v157, 4, 4
	v_and_b32_e32 v7, 15, v157
	v_add_u32_e32 v6, v138, v6
	v_add_u32_e32 v7, v138, v7
	ds_read_u8 v6, v6
	ds_read_u8 v7, v7 offset:16
	s_waitcnt lgkmcnt(0)
	v_lshl_add_u32 v7, v6, 7, v7
	v_bfe_u32 v6, v156, 4, 4
	v_and_b32_e32 v13, 15, v156
	v_add_u32_e32 v6, v138, v6
	v_add_u32_e32 v13, v138, v13
	ds_read_u8 v6, v6
	ds_read_u8 v13, v13 offset:16
	s_waitcnt lgkmcnt(0)
	v_lshl_add_u32 v6, v6, 7, v13
	v_bfe_u32 v13, v155, 4, 4
	v_add_u32_e32 v13, v138, v13
	ds_read_u8 v13, v13
	s_waitcnt lgkmcnt(0)
	v_lshl_add_u32 v13, v13, 7, v17
	v_bfe_u32 v17, v154, 4, 4
	v_and_b32_e32 v12, 15, v154
	v_add_u32_e32 v17, v138, v17
	v_add_u32_e32 v12, v138, v12
	ds_read_u8 v17, v17
	ds_read_u8 v12, v12 offset:16
	s_waitcnt lgkmcnt(0)
	v_lshl_add_u32 v12, v17, 7, v12
	v_bfe_u32 v17, v153, 4, 4
	v_and_b32_e32 v11, 15, v153
	v_add_u32_e32 v17, v138, v17
	v_add_u32_e32 v11, v138, v11
	ds_read_u8 v17, v17
	ds_read_u8 v11, v11 offset:16
	s_waitcnt lgkmcnt(0)
	v_lshl_add_u32 v11, v17, 7, v11
	v_bfe_u32 v17, v152, 4, 4
	v_and_b32_e32 v10, 15, v152
	v_add_u32_e32 v17, v138, v17
	v_add_u32_e32 v10, v138, v10
	ds_read_u8 v17, v17
	ds_read_u8 v10, v10 offset:16
	s_waitcnt lgkmcnt(0)
	v_lshl_add_u32 v10, v17, 7, v10
	v_bfe_u32 v17, v151, 4, 4
	v_and_b32_e32 v16, 15, v151
	v_add_u32_e32 v17, v138, v17
	v_add_u32_e32 v16, v138, v16
	ds_read_u8 v17, v17
	ds_read_u8 v16, v16 offset:16
	s_waitcnt lgkmcnt(0)
	v_lshl_add_u32 v17, v17, 7, v16
	v_bfe_u32 v16, v150, 4, 4
	v_and_b32_e32 v15, 15, v150
	v_add_u32_e32 v16, v138, v16
	v_add_u32_e32 v15, v138, v15
	ds_read_u8 v16, v16
	ds_read_u8 v15, v15 offset:16
	s_waitcnt lgkmcnt(0)
	v_lshl_add_u32 v16, v16, 7, v15
	v_bfe_u32 v15, v149, 4, 4
	v_and_b32_e32 v14, 15, v149
	v_add_u32_e32 v15, v138, v15
	v_add_u32_e32 v14, v138, v14
	ds_read_u8 v15, v15
	ds_read_u8 v14, v14 offset:16
	s_waitcnt lgkmcnt(0)
	v_lshl_add_u32 v15, v15, 7, v14
	v_bfe_u32 v14, v148, 4, 4
	v_and_b32_e32 v0, 15, v148
	v_add_u32_e32 v14, v138, v14
	v_add_u32_e32 v0, v138, v0
	ds_read_u8 v14, v14
	ds_read_u8 v0, v0 offset:16
	s_waitcnt lgkmcnt(0)
; DEV void phase_peer_score(const Params& p, int layer, int M, char* smem) {
;     ...
;     if (quad == 0) {
;       int* eo = EIDX + (size_t)m * 128 + h * 16;
;       float* go = GATE + (size_t)m * 128 + h * 16;
;       float* uo = go + (size_t)MT * 128;
;       float us[16], vs[16];
; #pragma unroll
;       for (int t = 0; t < 16; t++) { us[t] = USC[eid[t]]; vs[t] = USC[16384 + eid[t]]; }
; #pragma unroll
;       for (int t = 0; t < 16; t += 4) {
;         *(int4*)(eo + t) = make_int4(eid[t], eid[t + 1], eid[t + 2], eid[t + 3]);
;         *(float4*)(go + t) = make_float4(ev[t] * inv * vs[t], ev[t + 1] * inv * vs[t + 1], ev[t + 2] * inv * vs[t + 2], ev[t + 3] * inv * vs[t + 3]);
;         *(float4*)(uo + t) = make_float4(us[t], us[t + 1], us[t + 2], us[t + 3]);
;       }
;     }
	v_lshl_add_u32 v14, v14, 7, v0
	v_lshlrev_b32_e32 v0, 2, v14
	v_lshl_add_u64 v[20:21], s[10:11], 0, v[0:1]
	v_add_co_u32_e32 v20, vcc, s0, v20
	global_load_dword v18, v0, s[10:11]
	s_nop 0
	v_addc_co_u32_e32 v21, vcc, 0, v21, vcc
	global_load_dword v122, v[20:21], off
	v_lshlrev_b32_e32 v0, 2, v15
	v_lshl_add_u64 v[20:21], s[10:11], 0, v[0:1]
	v_add_co_u32_e32 v20, vcc, s0, v20
	global_load_dword v19, v0, s[10:11]
	s_nop 0
	v_addc_co_u32_e32 v21, vcc, 0, v21, vcc
	global_load_dword v123, v[20:21], off
	v_lshlrev_b32_e32 v0, 2, v16
	v_lshl_add_u64 v[22:23], s[10:11], 0, v[0:1]
	v_add_co_u32_e32 v22, vcc, s0, v22
	global_load_dword v20, v0, s[10:11]
	s_nop 0
	v_addc_co_u32_e32 v23, vcc, 0, v23, vcc
	global_load_dword v126, v[22:23], off
	v_lshlrev_b32_e32 v0, 2, v17
	v_lshl_add_u64 v[22:23], s[10:11], 0, v[0:1]
	v_add_co_u32_e32 v22, vcc, s0, v22
	global_load_dword v21, v0, s[10:11]
	s_nop 0
	v_addc_co_u32_e32 v23, vcc, 0, v23, vcc
	global_load_dword v127, v[22:23], off
	v_lshlrev_b32_e32 v0, 2, v10
	v_lshl_add_u64 v[24:25], s[10:11], 0, v[0:1]
	v_add_co_u32_e32 v24, vcc, s0, v24
	global_load_dword v22, v0, s[10:11]
	s_nop 0
	v_addc_co_u32_e32 v25, vcc, 0, v25, vcc
	global_load_dword v124, v[24:25], off
	v_lshlrev_b32_e32 v0, 2, v11
	v_lshl_add_u64 v[24:25], s[10:11], 0, v[0:1]
	v_add_co_u32_e32 v24, vcc, s0, v24
	global_load_dword v23, v0, s[10:11]
	s_nop 0
	v_addc_co_u32_e32 v25, vcc, 0, v25, vcc
	global_load_dword v125, v[24:25], off
	v_lshlrev_b32_e32 v0, 2, v12
	v_lshl_add_u64 v[26:27], s[10:11], 0, v[0:1]
	v_add_co_u32_e32 v26, vcc, s0, v26
	global_load_dword v24, v0, s[10:11]
	s_nop 0
	v_addc_co_u32_e32 v27, vcc, 0, v27, vcc
	global_load_dword v128, v[26:27], off
	v_lshlrev_b32_e32 v0, 2, v13
	v_lshl_add_u64 v[26:27], s[10:11], 0, v[0:1]
	v_add_co_u32_e32 v26, vcc, s0, v26
	global_load_dword v25, v0, s[10:11]
	s_nop 0
	v_addc_co_u32_e32 v27, vcc, 0, v27, vcc
	global_load_dword v129, v[26:27], off
	v_lshlrev_b32_e32 v0, 2, v6
	v_lshl_add_u64 v[28:29], s[10:11], 0, v[0:1]
	v_add_co_u32_e32 v28, vcc, s0, v28
	global_load_dword v26, v0, s[10:11]
	s_nop 0
	v_addc_co_u32_e32 v29, vcc, 0, v29, vcc
	global_load_dword v130, v[28:29], off
	v_lshlrev_b32_e32 v0, 2, v7
	v_lshl_add_u64 v[28:29], s[10:11], 0, v[0:1]
	v_add_co_u32_e32 v28, vcc, s0, v28
	global_load_dword v27, v0, s[10:11]
	s_nop 0
	v_addc_co_u32_e32 v29, vcc, 0, v29, vcc
	global_load_dword v131, v[28:29], off
	v_lshlrev_b32_e32 v0, 2, v8
	v_lshl_add_u64 v[30:31], s[10:11], 0, v[0:1]
	v_add_co_u32_e32 v30, vcc, s0, v30
	global_load_dword v28, v0, s[10:11]
	s_nop 0
	v_addc_co_u32_e32 v31, vcc, 0, v31, vcc
	global_load_dword v132, v[30:31], off
	v_lshlrev_b32_e32 v0, 2, v9
	v_lshl_add_u64 v[30:31], s[10:11], 0, v[0:1]
	v_add_co_u32_e32 v30, vcc, s0, v30
	global_load_dword v29, v0, s[10:11]
	s_nop 0
	v_addc_co_u32_e32 v31, vcc, 0, v31, vcc
	global_load_dword v133, v[30:31], off
	v_lshlrev_b32_e32 v0, 2, v2
	v_lshl_add_u64 v[32:33], s[10:11], 0, v[0:1]
	v_add_co_u32_e32 v32, vcc, s0, v32
	global_load_dword v30, v0, s[10:11]
	s_nop 0
	v_addc_co_u32_e32 v33, vcc, 0, v33, vcc
	global_load_dword v134, v[32:33], off
	v_lshlrev_b32_e32 v0, 2, v3
	v_lshl_add_u64 v[32:33], s[10:11], 0, v[0:1]
	v_add_co_u32_e32 v32, vcc, s0, v32
	global_load_dword v31, v0, s[10:11]
	s_nop 0
	v_addc_co_u32_e32 v33, vcc, 0, v33, vcc
	global_load_dword v135, v[32:33], off
	v_lshlrev_b32_e32 v0, 2, v4
	v_lshl_add_u64 v[136:137], s[10:11], 0, v[0:1]
	v_add_co_u32_e32 v136, vcc, s0, v136
	global_load_dword v32, v0, s[10:11]
	s_nop 0
	v_addc_co_u32_e32 v137, vcc, 0, v137, vcc
	global_load_dword v136, v[136:137], off
	v_lshlrev_b32_e32 v0, 2, v5
	v_lshl_add_u64 v[140:141], s[10:11], 0, v[0:1]
	v_add_co_u32_e32 v140, vcc, s0, v140
	global_load_dword v33, v0, s[10:11]
	s_nop 0
	v_addc_co_u32_e32 v141, vcc, 0, v141, vcc
	global_load_dword v137, v[140:141], off
	s_mov_b32 s0, 0x840000
	global_store_dwordx4 v[120:121], v[14:17], off
	s_nop 1
	v_pk_mul_f32 v[14:15], v[100:101], v[116:117] op_sel_hi:[1,0]
	v_pk_mul_f32 v[16:17], v[104:105], v[116:117] op_sel_hi:[1,0]
	s_waitcnt vmcnt(29)
	v_pk_mul_f32 v[14:15], v[14:15], v[122:123]
	s_waitcnt vmcnt(25)
	v_pk_mul_f32 v[16:17], v[16:17], v[126:127]
	global_store_dwordx4 v[118:119], v[14:17], off
	s_nop 1
	v_add_co_u32_e32 v14, vcc, s0, v118
	s_nop 1
	v_addc_co_u32_e32 v15, vcc, 0, v119, vcc
	global_store_dwordx4 v[14:15], v[18:21], off
	global_store_dwordx4 v[120:121], v[10:13], off offset:16
	s_nop 1
	v_pk_mul_f32 v[10:11], v[102:103], v[116:117] op_sel_hi:[1,0]
	v_pk_mul_f32 v[12:13], v[110:111], v[116:117] op_sel_hi:[1,0]
	s_waitcnt vmcnt(24)
	v_pk_mul_f32 v[10:11], v[10:11], v[124:125]
	s_waitcnt vmcnt(20)
	v_pk_mul_f32 v[12:13], v[12:13], v[128:129]
	global_store_dwordx4 v[118:119], v[10:13], off offset:16
	global_store_dwordx4 v[14:15], v[22:25], off offset:16
	global_store_dwordx4 v[120:121], v[6:9], off offset:32
	s_nop 1
	v_pk_mul_f32 v[6:7], v[112:113], v[116:117] op_sel_hi:[1,0]
	v_pk_mul_f32 v[8:9], v[114:115], v[116:117] op_sel_hi:[1,0]
	s_waitcnt vmcnt(19)
	v_pk_mul_f32 v[6:7], v[6:7], v[130:131]
	s_waitcnt vmcnt(15)
	v_pk_mul_f32 v[8:9], v[8:9], v[132:133]
	global_store_dwordx4 v[118:119], v[6:9], off offset:32
	global_store_dwordx4 v[14:15], v[26:29], off offset:32
	global_store_dwordx4 v[120:121], v[2:5], off offset:48
	s_nop 1
	v_pk_mul_f32 v[2:3], v[106:107], v[116:117] op_sel_hi:[1,0]
	v_pk_mul_f32 v[4:5], v[108:109], v[116:117] op_sel_hi:[1,0]
	s_waitcnt vmcnt(14)
	v_pk_mul_f32 v[2:3], v[2:3], v[134:135]
	s_waitcnt vmcnt(10)
	v_pk_mul_f32 v[4:5], v[4:5], v[136:137]
	global_store_dwordx4 v[118:119], v[2:5], off offset:48
	global_store_dwordx4 v[14:15], v[30:33], off offset:48
	s_branch .LBB0_162

; DEV int tidx() { int t = threadIdx.x; asm volatile("" : "+v"(t)); return t; }
; DEV f32x4 mfma16(bf16x8 a, bf16x8 b, f32x4 c) { return __builtin_amdgcn_mfma_f32_16x16x32_bf16(a, b, c, 0, 0, 0); }
; DEV void peer_top16(const bf16_t* __restrict__ pq, const bf16_t* sk  , float (&l)[16]) {
;   const int lane = tidx() & 63, l15 = lane & 15, quad = lane >> 4;
;   f32x4 acc[8];
; #pragma unroll
;   for (int nt = 0; nt < 8; nt++) acc[nt] = (f32x4){0.f, 0.f, 0.f, 0.f};
; #pragma unroll 1
;   for (int ks = 0; ks < 4; ks++) {
;     const bf16x8 bqk = *(const bf16x8*)(pq + ks * 32 + quad * 8);
; #pragma unroll
;     for (int nt = 0; nt < 8; nt++) {
;       bf16x8 ak = *(const bf16x8*)(sk + (nt * 16 + l15) * 144 + ks * 32 + quad * 8);
;       acc[nt] = mfma16(ak, bqk, acc[nt]);
;     }
;   }
.LBB0_635:
	v_add_u32_e32 v139, 0x10e00, v122
	ds_read_b128 v[164:167], v122 offset:36864
	ds_read_b128 v[168:171], v122 offset:41472
	ds_read_b128 v[172:175], v122 offset:46080
	ds_read_b128 v[176:179], v122 offset:50688
	ds_read_b128 v[180:183], v122 offset:55296
	ds_read_b128 v[184:187], v122 offset:59904
	ds_read_b128 v[188:191], v122 offset:64512
	ds_read_b128 v[128:131], v139
	s_waitcnt vmcnt(3) lgkmcnt(7)
	v_mfma_f32_16x16x32_bf16 v[30:33], v[164:167], v[148:151], v[30:33]
	ds_read_b128 v[164:167], v122 offset:36928
	s_waitcnt lgkmcnt(7)
	v_mfma_f32_16x16x32_bf16 v[22:25], v[168:171], v[148:151], v[22:25]
	ds_read_b128 v[168:171], v122 offset:41536
	s_waitcnt lgkmcnt(7)
	v_mfma_f32_16x16x32_bf16 v[14:17], v[172:175], v[148:151], v[14:17]
	ds_read_b128 v[172:175], v122 offset:46144
	s_waitcnt lgkmcnt(7)
	v_mfma_f32_16x16x32_bf16 v[6:9], v[176:179], v[148:151], v[6:9]
	ds_read_b128 v[176:179], v122 offset:50752
	s_waitcnt lgkmcnt(7)
	v_mfma_f32_16x16x32_bf16 v[26:29], v[180:183], v[148:151], v[26:29]
	ds_read_b128 v[180:183], v122 offset:55360
	s_waitcnt lgkmcnt(7)
	v_mfma_f32_16x16x32_bf16 v[18:21], v[184:187], v[148:151], v[18:21]
	ds_read_b128 v[184:187], v122 offset:59968
	s_waitcnt lgkmcnt(7)
	v_mfma_f32_16x16x32_bf16 v[10:13], v[188:191], v[148:151], v[10:13]
	ds_read_b128 v[188:191], v122 offset:64576
	s_waitcnt lgkmcnt(7)
	v_mfma_f32_16x16x32_bf16 v[2:5], v[128:131], v[148:151], v[2:5]
	ds_read_b128 v[128:131], v139 offset:64
	s_waitcnt vmcnt(2) lgkmcnt(7)
	v_mfma_f32_16x16x32_bf16 v[30:33], v[164:167], v[152:155], v[30:33]
	ds_read_b128 v[164:167], v122 offset:36992
	s_waitcnt lgkmcnt(7)
	v_mfma_f32_16x16x32_bf16 v[22:25], v[168:171], v[152:155], v[22:25]
	ds_read_b128 v[168:171], v122 offset:41600
	s_waitcnt lgkmcnt(7)
	v_mfma_f32_16x16x32_bf16 v[14:17], v[172:175], v[152:155], v[14:17]
	ds_read_b128 v[172:175], v122 offset:46208
	s_waitcnt lgkmcnt(7)
	v_mfma_f32_16x16x32_bf16 v[6:9], v[176:179], v[152:155], v[6:9]
	ds_read_b128 v[176:179], v122 offset:50816
	s_waitcnt lgkmcnt(7)
	v_mfma_f32_16x16x32_bf16 v[26:29], v[180:183], v[152:155], v[26:29]
	ds_read_b128 v[180:183], v122 offset:55424
	s_waitcnt lgkmcnt(7)
	v_mfma_f32_16x16x32_bf16 v[18:21], v[184:187], v[152:155], v[18:21]
	ds_read_b128 v[184:187], v122 offset:60032
	s_waitcnt lgkmcnt(7)
	v_mfma_f32_16x16x32_bf16 v[10:13], v[188:191], v[152:155], v[10:13]
	ds_read_b128 v[188:191], v122 offset:64640
	s_waitcnt lgkmcnt(7)
	v_mfma_f32_16x16x32_bf16 v[2:5], v[128:131], v[152:155], v[2:5]
	ds_read_b128 v[128:131], v139 offset:128
	s_waitcnt vmcnt(1) lgkmcnt(7)
	v_mfma_f32_16x16x32_bf16 v[30:33], v[164:167], v[156:159], v[30:33]
	ds_read_b128 v[164:167], v122 offset:37056
	s_waitcnt lgkmcnt(7)
	v_mfma_f32_16x16x32_bf16 v[22:25], v[168:171], v[156:159], v[22:25]
	ds_read_b128 v[168:171], v122 offset:41664
	s_waitcnt lgkmcnt(7)
	v_mfma_f32_16x16x32_bf16 v[14:17], v[172:175], v[156:159], v[14:17]
	ds_read_b128 v[172:175], v122 offset:46272
	s_waitcnt lgkmcnt(7)
	v_mfma_f32_16x16x32_bf16 v[6:9], v[176:179], v[156:159], v[6:9]
	ds_read_b128 v[176:179], v122 offset:50880
	s_waitcnt lgkmcnt(7)
	v_mfma_f32_16x16x32_bf16 v[26:29], v[180:183], v[156:159], v[26:29]
	ds_read_b128 v[180:183], v122 offset:55488
	s_waitcnt lgkmcnt(7)
	v_mfma_f32_16x16x32_bf16 v[18:21], v[184:187], v[156:159], v[18:21]
	ds_read_b128 v[184:187], v122 offset:60096
	s_waitcnt lgkmcnt(7)
	v_mfma_f32_16x16x32_bf16 v[10:13], v[188:191], v[156:159], v[10:13]
	ds_read_b128 v[188:191], v122 offset:64704
	s_waitcnt lgkmcnt(7)
	v_mfma_f32_16x16x32_bf16 v[2:5], v[128:131], v[156:159], v[2:5]
	ds_read_b128 v[128:131], v139 offset:192
	s_waitcnt vmcnt(0) lgkmcnt(7)
	v_mfma_f32_16x16x32_bf16 v[30:33], v[164:167], v[160:163], v[30:33]
	s_waitcnt lgkmcnt(6)
	v_mfma_f32_16x16x32_bf16 v[22:25], v[168:171], v[160:163], v[22:25]
	s_waitcnt lgkmcnt(5)
	v_mfma_f32_16x16x32_bf16 v[14:17], v[172:175], v[160:163], v[14:17]
	s_waitcnt lgkmcnt(4)
	v_mfma_f32_16x16x32_bf16 v[6:9], v[176:179], v[160:163], v[6:9]
	s_waitcnt lgkmcnt(3)
	v_mfma_f32_16x16x32_bf16 v[26:29], v[180:183], v[160:163], v[26:29]
	s_waitcnt lgkmcnt(2)
	v_mfma_f32_16x16x32_bf16 v[18:21], v[184:187], v[160:163], v[18:21]
	s_waitcnt lgkmcnt(1)
	v_mfma_f32_16x16x32_bf16 v[10:13], v[188:191], v[160:163], v[10:13]
	s_waitcnt lgkmcnt(0)
; DEV void merge_xor(float (&l)[16], int mask) {
;   float t[16];
; #pragma unroll
;   for (int i = 0; i < 16; i++) t[i] = __shfl_xor(l[15 - i], mask);
; #pragma unroll
;   for (int i = 0; i < 16; i++) l[i] = fmaxf(l[i], t[i]);
;   bitonic16(l);
; DEV void peer_top16(const bf16_t* __restrict__ pq, const bf16_t* sk  , float (&l)[16]) {
;     ...
;   float hi[16];
; #pragma unroll
;   for (int nt = 0; nt < 4; nt++)
; #pragma unroll
;     for (int r = 0; r < 4; r++) {
;       l[nt * 4 + r] = __uint_as_float((__float_as_uint(acc[nt][r]) & ~127u) | (unsigned)(nt * 16 + quad * 4 + r));
;       hi[nt * 4 + r] = __uint_as_float((__float_as_uint(acc[nt + 4][r]) & ~127u) | (unsigned)((nt + 4) * 16 + quad * 4 + r));
;     }
;   sort16_desc(l);
;   sort16_desc(hi);
	v_mfma_f32_16x16x32_bf16 v[2:5], v[128:131], v[160:163], v[2:5]
	s_movk_i32 s18, 0x100
	v_max_f32_e32 v0, v109, v121
	v_max_f32_e32 v100, v107, v120
	v_max_f32_e32 v101, v105, v119
	v_max_f32_e32 v103, v103, v118
	v_max_f32_e32 v87, v87, v116
	v_max_f32_e32 v79, v79, v115
	v_max_f32_e32 v75, v75, v114
	v_max_f32_e32 v71, v71, v113
	v_max_f32_e32 v67, v67, v112
	v_max_f32_e32 v63, v63, v111
	v_max_f32_e32 v59, v59, v110
	v_max_f32_e32 v55, v55, v108
	v_max_f32_e32 v51, v51, v106
	v_max_f32_e32 v47, v47, v104
	v_max_f32_e32 v43, v43, v91
	v_max_f32_e32 v39, v39, v83
	v_max_f32_e32 v83, v0, v67
	v_min_f32_e32 v0, v0, v67
	v_max_f32_e32 v67, v100, v63
	v_min_f32_e32 v63, v100, v63
	v_max_f32_e32 v91, v101, v59
	v_min_f32_e32 v59, v101, v59
	v_max_f32_e32 v100, v103, v55
	v_min_f32_e32 v55, v103, v55
	v_max_f32_e32 v101, v87, v51
	v_min_f32_e32 v51, v87, v51
	v_max_f32_e32 v87, v79, v47
	v_min_f32_e32 v47, v79, v47
	v_max_f32_e32 v79, v75, v43
	v_min_f32_e32 v43, v75, v43
	v_max_f32_e32 v75, v71, v39
	v_min_f32_e32 v39, v71, v39
	v_max_f32_e32 v71, v83, v101
	v_min_f32_e32 v101, v83, v101
	v_max_f32_e32 v103, v67, v87
	v_min_f32_e32 v67, v67, v87
	v_max_f32_e32 v87, v91, v79
	v_min_f32_e32 v79, v91, v79
	v_max_f32_e32 v91, v100, v75
	v_min_f32_e32 v75, v100, v75
	v_max_f32_e32 v100, v0, v51
	v_min_f32_e32 v0, v0, v51
	v_max_f32_e32 v51, v63, v47
	v_max_f32_e32 v105, v59, v43
	v_min_f32_e32 v43, v59, v43
	v_max_f32_e32 v59, v55, v39
	v_min_f32_e32 v107, v101, v79
	v_min_f32_e32 v108, v67, v75
	v_min_f32_e32 v110, v51, v59
	v_max_f32_e32 v79, v101, v79
	v_max_f32_e32 v67, v67, v75
	v_max_f32_e32 v101, v100, v105
	v_max_f32_e32 v51, v51, v59
	v_min_f32_e32 v75, v79, v67
	v_min_f32_e32 v59, v101, v51
	v_max_f32_e32 v79, v79, v67
	v_max_f32_e32 v67, v101, v51
	v_lshlrev_b32_e32 v101, 2, v102
	s_movk_i32 s8, 0xff80
	v_and_or_b32 v30, v30, s8, v101
	v_and_b32_e32 v27, 0xffffff80, v27
	s_movk_i32 s8, 0x41
	v_or3_b32 v27, v101, v27, s8
	v_and_b32_e32 v28, 0xffffff80, v28
	s_movk_i32 s8, 0x42
	v_or3_b32 v28, v101, v28, s8
	v_and_b32_e32 v29, 0xffffff80, v29
	s_movk_i32 s8, 0x43
	v_or3_b32 v29, v101, v29, s8
	v_and_b32_e32 v18, 0xffffff80, v18
	s_movk_i32 s8, 0x50
	v_or3_b32 v18, v101, v18, s8
	v_and_b32_e32 v19, 0xffffff80, v19
	s_movk_i32 s8, 0x51
	v_or3_b32 v19, v101, v19, s8
	v_and_b32_e32 v20, 0xffffff80, v20
	s_movk_i32 s8, 0x52
	v_or3_b32 v20, v101, v20, s8
	v_and_b32_e32 v21, 0xffffff80, v21
	s_movk_i32 s8, 0x53
	v_or3_b32 v21, v101, v21, s8
	v_and_b32_e32 v10, 0xffffff80, v10
	s_movk_i32 s8, 0x60
	v_or3_b32 v10, v101, v10, s8
	v_and_b32_e32 v11, 0xffffff80, v11
	s_movk_i32 s8, 0x61
	v_or3_b32 v11, v101, v11, s8
	v_and_b32_e32 v12, 0xffffff80, v12
	s_movk_i32 s8, 0x62
	v_or3_b32 v12, v101, v12, s8
	v_and_b32_e32 v13, 0xffffff80, v13
	s_movk_i32 s8, 0x63
	v_or3_b32 v13, v101, v13, s8
	v_and_b32_e32 v2, 0xffffff80, v2
	s_movk_i32 s8, 0x70
	v_and_b32_e32 v26, 0xffffff80, v26
	v_and_b32_e32 v31, 0xffffff80, v31
	v_or3_b32 v2, v101, v2, s8
	v_and_b32_e32 v3, 0xffffff80, v3
	s_movk_i32 s8, 0x71
	v_or3_b32 v26, v101, v26, 64
	v_or3_b32 v31, v101, v31, 1
	v_and_b32_e32 v32, 0xffffff80, v32
	v_and_b32_e32 v33, 0xffffff80, v33
	v_and_b32_e32 v22, 0xffffff80, v22
	v_and_b32_e32 v23, 0xffffff80, v23
	v_or3_b32 v3, v101, v3, s8
	v_and_b32_e32 v4, 0xffffff80, v4
	s_movk_i32 s8, 0x72
	v_min_f32_e32 v39, v55, v39
	v_min_f32_e32 v55, v71, v87
	v_min_f32_e32 v106, v103, v91
	v_min_f32_e32 v109, v100, v105
	v_max_f32_e32 v71, v71, v87
	v_max_f32_e32 v87, v103, v91
	v_or3_b32 v32, v101, v32, 2
	v_or3_b32 v33, v101, v33, 3
	v_or3_b32 v22, v101, v22, 16
	v_or3_b32 v23, v101, v23, 17
	v_and_b32_e32 v24, 0xffffff80, v24
	v_and_b32_e32 v25, 0xffffff80, v25
	v_and_b32_e32 v14, 0xffffff80, v14
	v_and_b32_e32 v15, 0xffffff80, v15
	v_and_b32_e32 v16, 0xffffff80, v16
	v_and_b32_e32 v17, 0xffffff80, v17
	v_and_b32_e32 v6, 0xffffff80, v6
	v_and_b32_e32 v7, 0xffffff80, v7
	v_and_b32_e32 v8, 0xffffff80, v8
	v_or3_b32 v4, v101, v4, s8
	v_and_b32_e32 v9, 0xffffff80, v9
	v_and_b32_e32 v5, 0xffffff80, v5
	s_movk_i32 s8, 0x73
	v_min_f32_e32 v104, v63, v47
	v_min_f32_e32 v83, v55, v106
	v_min_f32_e32 v47, v109, v110
	v_min_f32_e32 v91, v71, v87
	v_max_f32_e32 v100, v71, v87
	v_max_f32_e32 v87, v55, v106
	v_max_f32_e32 v55, v109, v110
	v_or3_b32 v24, v101, v24, 18
	v_or3_b32 v25, v101, v25, 19
	v_or3_b32 v14, v101, v14, 32
	v_or3_b32 v15, v101, v15, 33
	v_or3_b32 v16, v101, v16, 34
	v_or3_b32 v17, v101, v17, 35
	v_or3_b32 v6, v101, v6, 48
	v_or3_b32 v7, v101, v7, 49
	v_or3_b32 v8, v101, v8, 50
	v_or3_b32 v9, v101, v9, 51
	v_or3_b32 v5, v101, v5, s8
	v_max_f32_e32 v101, v30, v31
	v_min_f32_e32 v30, v30, v31
	v_max_f32_e32 v31, v32, v32
	v_max_f32_e32 v32, v33, v33
	v_max_f32_e32 v109, v26, v27
	v_min_f32_e32 v26, v26, v27
	v_max_f32_e32 v27, v28, v28
	v_max_f32_e32 v28, v29, v29
	v_max_f32_e32 v33, v32, v31
	v_min_f32_e32 v31, v32, v31
	v_max_f32_e32 v32, v22, v23
	v_min_f32_e32 v22, v22, v23
	v_max_f32_e32 v23, v24, v24
	v_max_f32_e32 v24, v25, v25
	v_max_f32_e32 v29, v28, v27
	v_min_f32_e32 v27, v28, v27
	v_max_f32_e32 v28, v18, v19
	v_min_f32_e32 v18, v18, v19
	v_max_f32_e32 v19, v20, v20
	v_max_f32_e32 v20, v21, v21
	v_max_f32_e32 v25, v24, v23
	v_min_f32_e32 v23, v24, v23
	v_max_f32_e32 v24, v14, v15
	v_min_f32_e32 v14, v14, v15
	v_max_f32_e32 v15, v16, v16
	v_max_f32_e32 v16, v17, v17
	v_max_f32_e32 v21, v20, v19
	v_min_f32_e32 v19, v20, v19
	v_max_f32_e32 v20, v10, v11
	v_min_f32_e32 v10, v10, v11
	v_max_f32_e32 v11, v12, v12
	v_max_f32_e32 v12, v13, v13
	v_max_f32_e32 v17, v16, v15
	v_min_f32_e32 v15, v16, v15
	v_max_f32_e32 v16, v6, v7
	v_min_f32_e32 v6, v6, v7
; DEV void ce(float& a, float& b) { float hi = fmaxf(a, b), lo = fminf(a, b); a = hi; b = lo; }
; DEV void sort16_desc(float (&a)[16]) {
; #pragma unroll
;   for (int k = 2; k <= 16; k <<= 1)
; #pragma unroll
;     for (int j = k >> 1; j > 0; j >>= 1)
; #pragma unroll
;       for (int i = 0; i < 16; i++) {
;         const int p = i ^ j;
;         if (p > i) { if ((i & k) == 0) ce(a[i], a[p]); else ce(a[p], a[i]); }
;       }
; }
; DEV void peer_top16(const bf16_t* __restrict__ pq, const bf16_t* sk  , float (&l)[16]) {
;     ...
;   float hi[16];
; #pragma unroll
;   for (int nt = 0; nt < 4; nt++)
; #pragma unroll
;     for (int r = 0; r < 4; r++) {
;       l[nt * 4 + r] = __uint_as_float((__float_as_uint(acc[nt][r]) & ~127u) | (unsigned)(nt * 16 + quad * 4 + r));
;       hi[nt * 4 + r] = __uint_as_float((__float_as_uint(acc[nt + 4][r]) & ~127u) | (unsigned)((nt + 4) * 16 + quad * 4 + r));
;     }
;   sort16_desc(l);
;   sort16_desc(hi);
	v_max_f32_e32 v7, v8, v8
	v_max_f32_e32 v8, v9, v9
	v_max_f32_e32 v13, v12, v11
	v_min_f32_e32 v11, v12, v11
	v_max_f32_e32 v12, v2, v3
	v_min_f32_e32 v2, v2, v3
	v_max_f32_e32 v3, v4, v4
	v_max_f32_e32 v4, v5, v5
	v_max_f32_e32 v9, v8, v7
	v_min_f32_e32 v7, v8, v7
	v_max_f32_e32 v5, v4, v3
	v_min_f32_e32 v3, v4, v3
	v_max_f32_e32 v8, v101, v31
	v_min_f32_e32 v31, v101, v31
	v_max_f32_e32 v101, v30, v33
	v_min_f32_e32 v30, v30, v33
	v_max_f32_e32 v33, v23, v32
	v_min_f32_e32 v23, v23, v32
	v_max_f32_e32 v32, v25, v22
	v_min_f32_e32 v22, v25, v22
	v_max_f32_e32 v25, v24, v15
	v_min_f32_e32 v15, v24, v15
	v_max_f32_e32 v24, v14, v17
	v_min_f32_e32 v14, v14, v17
	v_max_f32_e32 v17, v7, v16
	v_min_f32_e32 v7, v7, v16
	v_max_f32_e32 v16, v9, v6
	v_min_f32_e32 v6, v9, v6
	v_max_f32_e32 v4, v109, v27
	v_min_f32_e32 v27, v109, v27
	v_max_f32_e32 v109, v26, v29
	v_min_f32_e32 v26, v26, v29
	v_max_f32_e32 v29, v19, v28
	v_min_f32_e32 v19, v19, v28
	v_max_f32_e32 v28, v21, v18
	v_min_f32_e32 v18, v21, v18
	v_max_f32_e32 v21, v20, v11
	v_min_f32_e32 v11, v20, v11
	v_max_f32_e32 v20, v10, v13
	v_min_f32_e32 v10, v10, v13
	v_max_f32_e32 v13, v3, v12
	v_min_f32_e32 v3, v3, v12
	v_max_f32_e32 v12, v5, v2
	v_min_f32_e32 v2, v5, v2
	v_max_f32_e32 v9, v8, v101
	v_min_f32_e32 v8, v8, v101
	v_max_f32_e32 v101, v31, v30
	v_min_f32_e32 v30, v31, v30
	v_max_f32_e32 v31, v22, v23
	v_min_f32_e32 v22, v22, v23
	v_max_f32_e32 v23, v32, v33
	v_min_f32_e32 v32, v32, v33
	v_max_f32_e32 v33, v25, v24
	v_min_f32_e32 v24, v25, v24
	v_max_f32_e32 v25, v15, v14
	v_min_f32_e32 v14, v15, v14
	v_max_f32_e32 v15, v6, v7
	v_min_f32_e32 v6, v6, v7
	v_max_f32_e32 v7, v16, v17
	v_min_f32_e32 v16, v16, v17
	v_max_f32_e32 v5, v4, v109
	v_min_f32_e32 v4, v4, v109
	v_max_f32_e32 v109, v27, v26
	v_min_f32_e32 v26, v27, v26
	v_max_f32_e32 v27, v18, v19
	v_min_f32_e32 v18, v18, v19
	v_max_f32_e32 v19, v28, v29
	v_min_f32_e32 v28, v28, v29
	v_max_f32_e32 v29, v21, v20
	v_min_f32_e32 v20, v21, v20
	v_max_f32_e32 v21, v11, v10
	v_min_f32_e32 v10, v11, v10
	v_max_f32_e32 v11, v2, v3
	v_min_f32_e32 v2, v2, v3
	v_max_f32_e32 v3, v12, v13
	v_min_f32_e32 v12, v12, v13
	v_max_f32_e32 v17, v9, v22
	v_min_f32_e32 v9, v9, v22
	v_max_f32_e32 v22, v8, v31
	v_min_f32_e32 v8, v8, v31
	v_max_f32_e32 v31, v101, v32
	v_min_f32_e32 v32, v101, v32
	v_max_f32_e32 v101, v30, v23
	v_min_f32_e32 v23, v30, v23
	v_max_f32_e32 v30, v6, v33
	v_min_f32_e32 v6, v6, v33
	v_max_f32_e32 v33, v15, v24
	v_min_f32_e32 v15, v15, v24
	v_max_f32_e32 v24, v16, v25
	v_min_f32_e32 v16, v16, v25
	v_max_f32_e32 v25, v7, v14
	v_min_f32_e32 v7, v7, v14
	v_max_f32_e32 v13, v5, v18
	v_min_f32_e32 v5, v5, v18
	v_max_f32_e32 v18, v4, v27
	v_min_f32_e32 v4, v4, v27
	v_max_f32_e32 v27, v109, v28
	v_min_f32_e32 v28, v109, v28
	v_max_f32_e32 v109, v26, v19
	v_min_f32_e32 v19, v26, v19
	v_max_f32_e32 v26, v2, v29
	v_min_f32_e32 v2, v2, v29
	v_max_f32_e32 v29, v11, v20
	v_min_f32_e32 v11, v11, v20
	v_max_f32_e32 v20, v12, v21
	v_min_f32_e32 v12, v12, v21
	v_max_f32_e32 v21, v3, v10
	v_min_f32_e32 v3, v3, v10
	v_max_f32_e32 v14, v17, v31
	v_min_f32_e32 v17, v17, v31
	v_max_f32_e32 v31, v22, v101
	v_min_f32_e32 v22, v22, v101
	v_max_f32_e32 v101, v9, v32
	v_min_f32_e32 v9, v9, v32
	v_max_f32_e32 v32, v8, v23
	v_min_f32_e32 v8, v8, v23
	v_max_f32_e32 v23, v16, v6
	v_min_f32_e32 v6, v16, v6
	v_max_f32_e32 v16, v7, v15
	v_min_f32_e32 v7, v7, v15
	v_max_f32_e32 v15, v24, v30
	v_min_f32_e32 v24, v24, v30
	v_max_f32_e32 v30, v25, v33
	v_min_f32_e32 v25, v25, v33
	v_max_f32_e32 v10, v13, v27
	v_min_f32_e32 v13, v13, v27
	v_max_f32_e32 v27, v18, v109
	v_min_f32_e32 v18, v18, v109
	v_max_f32_e32 v109, v5, v28
	v_min_f32_e32 v5, v5, v28
	v_max_f32_e32 v28, v4, v19
	v_min_f32_e32 v4, v4, v19
	v_max_f32_e32 v19, v12, v2
	v_min_f32_e32 v2, v12, v2
	v_max_f32_e32 v12, v3, v11
	v_min_f32_e32 v3, v3, v11
	v_max_f32_e32 v11, v20, v26
	v_min_f32_e32 v20, v20, v26
	v_max_f32_e32 v26, v21, v29
	v_min_f32_e32 v21, v21, v29
	v_max_f32_e32 v33, v14, v31
	v_min_f32_e32 v14, v14, v31
	v_max_f32_e32 v31, v17, v22
	v_min_f32_e32 v17, v17, v22
	v_max_f32_e32 v22, v101, v32
	v_min_f32_e32 v32, v101, v32
	v_max_f32_e32 v101, v9, v8
	v_min_f32_e32 v8, v9, v8
	v_max_f32_e32 v9, v7, v6
	v_min_f32_e32 v6, v7, v6
	v_max_f32_e32 v7, v16, v23
	v_min_f32_e32 v16, v16, v23
	v_max_f32_e32 v23, v25, v24
	v_min_f32_e32 v24, v25, v24
	v_max_f32_e32 v25, v30, v15
	v_min_f32_e32 v15, v30, v15
	v_max_f32_e32 v29, v10, v27
	v_min_f32_e32 v10, v10, v27
	v_max_f32_e32 v27, v13, v18
	v_min_f32_e32 v13, v13, v18
	v_max_f32_e32 v18, v109, v28
	v_min_f32_e32 v28, v109, v28
	v_max_f32_e32 v109, v5, v4
	v_min_f32_e32 v4, v5, v4
	v_max_f32_e32 v5, v3, v2
	v_min_f32_e32 v2, v3, v2
	v_max_f32_e32 v3, v12, v19
	v_min_f32_e32 v12, v12, v19
	v_max_f32_e32 v19, v21, v20
	v_min_f32_e32 v20, v21, v20
	v_max_f32_e32 v21, v26, v11
	v_min_f32_e32 v11, v26, v11
	v_max_f32_e32 v30, v33, v6
	v_min_f32_e32 v6, v33, v6
	v_max_f32_e32 v33, v14, v9
	v_min_f32_e32 v9, v14, v9
	v_max_f32_e32 v14, v31, v16
	v_min_f32_e32 v16, v31, v16
	v_max_f32_e32 v31, v17, v7
	v_min_f32_e32 v7, v17, v7
	v_max_f32_e32 v17, v22, v24
	v_min_f32_e32 v22, v22, v24
	v_max_f32_e32 v24, v32, v23
	v_min_f32_e32 v23, v32, v23
	v_max_f32_e32 v32, v101, v15
	v_min_f32_e32 v15, v101, v15
	v_max_f32_e32 v101, v8, v25
	v_min_f32_e32 v8, v8, v25
	v_max_f32_e32 v26, v29, v2
	v_min_f32_e32 v2, v29, v2
	v_max_f32_e32 v29, v10, v5
	v_min_f32_e32 v5, v10, v5
	v_max_f32_e32 v10, v27, v12
	v_min_f32_e32 v12, v27, v12
	v_max_f32_e32 v27, v13, v3
	v_min_f32_e32 v3, v13, v3
	v_max_f32_e32 v13, v18, v20
	v_min_f32_e32 v18, v18, v20
	v_max_f32_e32 v20, v28, v19
; DEV void ce(float& a, float& b) { float hi = fmaxf(a, b), lo = fminf(a, b); a = hi; b = lo; }
; DEV void bitonic16(float (&l)[16]) {
; #pragma unroll
;   for (int s = 8; s > 0; s >>= 1)
; #pragma unroll
;     for (int i = 0; i < 16; i++)
;       if (!(i & s)) ce(l[i], l[i + s]);
; }
; DEV void sort16_desc(float (&a)[16]) {
; #pragma unroll
;   for (int k = 2; k <= 16; k <<= 1)
; #pragma unroll
;     for (int j = k >> 1; j > 0; j >>= 1)
; #pragma unroll
;       for (int i = 0; i < 16; i++) {
;         const int p = i ^ j;
;         if (p > i) { if ((i & k) == 0) ce(a[i], a[p]); else ce(a[p], a[i]); }
;       }
; }
; DEV void merge_xor(float (&l)[16], int mask) {
;   float t[16];
; #pragma unroll
;   for (int i = 0; i < 16; i++) t[i] = __shfl_xor(l[15 - i], mask);
; #pragma unroll
;   for (int i = 0; i < 16; i++) l[i] = fmaxf(l[i], t[i]);
;   bitonic16(l);
; DEV void peer_top16(const bf16_t* __restrict__ pq, const bf16_t* sk  , float (&l)[16]) {
;     ...
;   sort16_desc(l);
;   sort16_desc(hi);
; #pragma unroll
;   for (int i = 0; i < 16; i++) l[i] = fmaxf(l[i], hi[15 - i]);
;   bitonic16(l);
;   merge_xor(l, 16);
	v_min_f32_e32 v19, v28, v19
	v_max_f32_e32 v28, v109, v11
	v_min_f32_e32 v11, v109, v11
	v_max_f32_e32 v109, v4, v21
	v_min_f32_e32 v4, v4, v21
	v_max_f32_e32 v25, v30, v17
	v_min_f32_e32 v17, v30, v17
	v_max_f32_e32 v30, v33, v24
	v_min_f32_e32 v24, v33, v24
	v_max_f32_e32 v33, v14, v32
	v_min_f32_e32 v14, v14, v32
	v_max_f32_e32 v32, v31, v101
	v_min_f32_e32 v31, v31, v101
	v_max_f32_e32 v101, v6, v22
	v_min_f32_e32 v6, v6, v22
	v_max_f32_e32 v22, v9, v23
	v_min_f32_e32 v9, v9, v23
	v_max_f32_e32 v23, v16, v15
	v_min_f32_e32 v15, v16, v15
	v_max_f32_e32 v16, v7, v8
	v_min_f32_e32 v7, v7, v8
	v_max_f32_e32 v21, v26, v13
	v_min_f32_e32 v13, v26, v13
	v_max_f32_e32 v26, v29, v20
	v_min_f32_e32 v20, v29, v20
	v_max_f32_e32 v29, v10, v28
	v_min_f32_e32 v10, v10, v28
	v_max_f32_e32 v28, v27, v109
	v_min_f32_e32 v27, v27, v109
	v_max_f32_e32 v109, v2, v18
	v_min_f32_e32 v2, v2, v18
	v_max_f32_e32 v18, v5, v19
	v_min_f32_e32 v5, v5, v19
	v_max_f32_e32 v19, v12, v11
	v_min_f32_e32 v11, v12, v11
	v_max_f32_e32 v12, v3, v4
	v_min_f32_e32 v3, v3, v4
	v_max_f32_e32 v111, v0, v43
	v_min_f32_e32 v112, v104, v39
	v_max_f32_e32 v103, v104, v39
	v_min_f32_e32 v0, v0, v43
	v_max_f32_e32 v8, v25, v33
	v_min_f32_e32 v25, v25, v33
	v_max_f32_e32 v33, v30, v32
	v_min_f32_e32 v30, v30, v32
	v_max_f32_e32 v32, v17, v14
	v_min_f32_e32 v14, v17, v14
	v_max_f32_e32 v17, v24, v31
	v_min_f32_e32 v24, v24, v31
	v_max_f32_e32 v31, v101, v23
	v_min_f32_e32 v23, v101, v23
	v_max_f32_e32 v101, v22, v16
	v_min_f32_e32 v16, v22, v16
	v_max_f32_e32 v22, v6, v15
	v_min_f32_e32 v6, v6, v15
	v_max_f32_e32 v15, v9, v7
	v_min_f32_e32 v7, v9, v7
	v_max_f32_e32 v4, v21, v29
	v_min_f32_e32 v21, v21, v29
	v_max_f32_e32 v29, v26, v28
	v_min_f32_e32 v26, v26, v28
	v_max_f32_e32 v28, v13, v10
	v_min_f32_e32 v10, v13, v10
	v_max_f32_e32 v13, v20, v27
	v_min_f32_e32 v20, v20, v27
	v_max_f32_e32 v27, v109, v19
	v_min_f32_e32 v19, v109, v19
	v_max_f32_e32 v109, v18, v12
	v_min_f32_e32 v12, v18, v12
	v_max_f32_e32 v18, v2, v11
	v_min_f32_e32 v2, v2, v11
	v_max_f32_e32 v11, v5, v3
	v_min_f32_e32 v3, v5, v3
	v_min_f32_e32 v63, v107, v108
	v_min_f32_e32 v39, v111, v103
	v_max_f32_e32 v71, v107, v108
	v_max_f32_e32 v51, v111, v103
	v_max_f32_e32 v43, v0, v112
	v_min_f32_e32 v0, v0, v112
	v_min_f32_e32 v9, v8, v33
	v_min_f32_e32 v102, v25, v30
	v_min_f32_e32 v103, v32, v17
	v_min_f32_e32 v104, v14, v24
	v_min_f32_e32 v105, v31, v101
	v_min_f32_e32 v106, v23, v16
	v_min_f32_e32 v107, v22, v15
	v_min_f32_e32 v108, v6, v7
	v_min_f32_e32 v5, v4, v29
	v_min_f32_e32 v110, v21, v26
	v_min_f32_e32 v111, v28, v13
	v_min_f32_e32 v112, v10, v20
	v_min_f32_e32 v113, v27, v109
	v_min_f32_e32 v114, v19, v12
	v_min_f32_e32 v115, v18, v11
	v_min_f32_e32 v116, v2, v3
	v_max3_f32 v8, v8, v33, v116
	v_max3_f32 v2, v9, v2, v3
	v_max3_f32 v3, v25, v30, v115
	v_max3_f32 v9, v102, v18, v11
	v_max3_f32 v11, v32, v17, v114
	v_max3_f32 v12, v103, v19, v12
	v_max3_f32 v14, v14, v24, v113
	v_max3_f32 v17, v104, v27, v109
	v_max3_f32 v18, v31, v101, v112
	v_max3_f32 v10, v105, v10, v20
	v_max3_f32 v16, v23, v16, v111
	v_max3_f32 v13, v106, v28, v13
	v_max3_f32 v15, v22, v15, v110
	v_max3_f32 v19, v107, v21, v26
	v_max3_f32 v5, v6, v7, v5
	v_max3_f32 v4, v108, v4, v29
	v_max_f32_e32 v6, v8, v18
	v_min_f32_e32 v7, v8, v18
	v_max_f32_e32 v8, v2, v10
	v_min_f32_e32 v2, v2, v10
	v_max_f32_e32 v10, v3, v16
	v_min_f32_e32 v3, v3, v16
	v_max_f32_e32 v16, v9, v13
	v_min_f32_e32 v9, v9, v13
	v_max_f32_e32 v13, v11, v15
	v_min_f32_e32 v11, v11, v15
	v_max_f32_e32 v15, v12, v19
	v_min_f32_e32 v12, v12, v19
	v_max_f32_e32 v18, v14, v5
	v_min_f32_e32 v5, v14, v5
	v_max_f32_e32 v14, v17, v4
	v_min_f32_e32 v4, v17, v4
	v_max_f32_e32 v17, v6, v13
	v_min_f32_e32 v6, v6, v13
	v_max_f32_e32 v13, v8, v15
	v_min_f32_e32 v8, v8, v15
	v_max_f32_e32 v15, v10, v18
	v_min_f32_e32 v10, v10, v18
	v_max_f32_e32 v18, v16, v14
	v_min_f32_e32 v14, v16, v14
	v_max_f32_e32 v16, v7, v11
	v_min_f32_e32 v7, v7, v11
	v_max_f32_e32 v11, v2, v12
	v_min_f32_e32 v2, v2, v12
	v_max_f32_e32 v12, v3, v5
	v_min_f32_e32 v3, v3, v5
	v_max_f32_e32 v5, v9, v4
	v_min_f32_e32 v4, v9, v4
	v_max_f32_e32 v9, v17, v15
	v_min_f32_e32 v15, v17, v15
	v_max_f32_e32 v17, v13, v18
	v_min_f32_e32 v13, v13, v18
	v_max_f32_e32 v18, v6, v10
	v_min_f32_e32 v6, v6, v10
	v_max_f32_e32 v10, v8, v14
	v_min_f32_e32 v8, v8, v14
	v_max_f32_e32 v14, v16, v12
	v_min_f32_e32 v12, v16, v12
	v_max_f32_e32 v16, v11, v5
	v_min_f32_e32 v5, v11, v5
	v_max_f32_e32 v11, v7, v3
	v_min_f32_e32 v3, v7, v3
	v_max_f32_e32 v7, v2, v4
	v_min_f32_e32 v2, v2, v4
	v_max_f32_e32 v4, v9, v17
	v_min_f32_e32 v9, v9, v17
	v_max_f32_e32 v17, v15, v13
	v_min_f32_e32 v13, v15, v13
	v_max_f32_e32 v15, v18, v10
	v_min_f32_e32 v10, v18, v10
	v_max_f32_e32 v18, v6, v8
	v_min_f32_e32 v6, v6, v8
	v_max_f32_e32 v8, v14, v16
	v_min_f32_e32 v14, v14, v16
	v_max_f32_e32 v16, v12, v5
	v_min_f32_e32 v5, v12, v5
	v_max_f32_e32 v12, v11, v7
	v_min_f32_e32 v7, v11, v7
	v_max_f32_e32 v11, v3, v2
	v_min_f32_e32 v2, v3, v2
	ds_bpermute_b32 v3, v95, v2
	ds_bpermute_b32 v19, v95, v11
	ds_bpermute_b32 v20, v95, v7
	ds_bpermute_b32 v21, v95, v12
	ds_bpermute_b32 v22, v95, v5
	ds_bpermute_b32 v23, v95, v16
	s_waitcnt lgkmcnt(5)
	ds_bpermute_b32 v24, v95, v14
	ds_bpermute_b32 v33, v95, v4
	v_max_f32_e32 v3, v4, v3
	s_waitcnt lgkmcnt(6)
	ds_bpermute_b32 v25, v95, v8
	ds_bpermute_b32 v32, v95, v9
	v_max_f32_e32 v4, v9, v19
	s_waitcnt lgkmcnt(7)
	ds_bpermute_b32 v26, v95, v6
	ds_bpermute_b32 v31, v95, v17
	v_max_f32_e32 v9, v17, v20
	s_waitcnt lgkmcnt(8)
	ds_bpermute_b32 v27, v95, v18
	ds_bpermute_b32 v30, v95, v13
	v_max_f32_e32 v13, v13, v21
	s_waitcnt lgkmcnt(9)
; DEV void merge_xor(float (&l)[16], int mask) {
;   float t[16];
; #pragma unroll
;   for (int i = 0; i < 16; i++) t[i] = __shfl_xor(l[15 - i], mask);
; #pragma unroll
;   for (int i = 0; i < 16; i++) l[i] = fmaxf(l[i], t[i]);
;   bitonic16(l);
; }
; DEV void phase_peer_score(const Params& p, int layer, int M, char* smem) {
;     ...
;     unsigned char* tab = (unsigned char*)smem + 73728 + (w * 16 + l15) * 32;
; #pragma unroll
;     for (int i = 0; i < 16; i++) { tab[i] = (unsigned char)(__float_as_uint(L0[i]) & 127u); tab[16 + i] = (unsigned char)(__float_as_uint(L1[i]) & 127u); }
	ds_bpermute_b32 v28, v95, v10
	ds_bpermute_b32 v29, v95, v15
	v_max_f32_e32 v15, v15, v22
	s_waitcnt lgkmcnt(10)
	v_max_f32_e32 v10, v10, v23
	s_waitcnt lgkmcnt(9)
	v_max_f32_e32 v17, v18, v24
	s_waitcnt lgkmcnt(7)
	v_max_f32_e32 v6, v6, v25
	s_waitcnt lgkmcnt(5)
	v_max_f32_e32 v8, v8, v26
	s_waitcnt lgkmcnt(3)
	v_max_f32_e32 v14, v14, v27
	s_waitcnt lgkmcnt(1)
	v_max_f32_e32 v16, v16, v28
	s_waitcnt lgkmcnt(0)
	v_max_f32_e32 v5, v5, v29
	v_max_f32_e32 v12, v12, v30
	v_max_f32_e32 v7, v7, v31
	v_max_f32_e32 v11, v11, v32
	v_max_f32_e32 v2, v2, v33
	v_max_f32_e32 v18, v3, v8
	v_min_f32_e32 v3, v3, v8
	v_max_f32_e32 v8, v4, v14
	v_min_f32_e32 v4, v4, v14
	v_max_f32_e32 v14, v9, v16
	v_min_f32_e32 v9, v9, v16
	v_max_f32_e32 v16, v13, v5
	v_min_f32_e32 v5, v13, v5
	v_max_f32_e32 v13, v15, v12
	v_min_f32_e32 v12, v15, v12
	v_max_f32_e32 v15, v10, v7
	v_min_f32_e32 v7, v10, v7
	v_max_f32_e32 v10, v17, v11
	v_min_f32_e32 v11, v17, v11
	v_max_f32_e32 v17, v6, v2
	v_min_f32_e32 v2, v6, v2
	v_max_f32_e32 v6, v18, v13
	v_min_f32_e32 v13, v18, v13
	v_max_f32_e32 v18, v8, v15
	v_min_f32_e32 v8, v8, v15
	v_max_f32_e32 v15, v14, v10
	v_min_f32_e32 v10, v14, v10
	v_max_f32_e32 v14, v16, v17
	v_min_f32_e32 v16, v16, v17
	v_max_f32_e32 v17, v3, v12
	v_min_f32_e32 v3, v3, v12
	v_max_f32_e32 v12, v4, v7
	v_min_f32_e32 v4, v4, v7
	v_max_f32_e32 v7, v9, v11
	v_min_f32_e32 v9, v9, v11
	v_max_f32_e32 v11, v5, v2
	v_min_f32_e32 v2, v5, v2
	v_max_f32_e32 v5, v6, v15
	v_min_f32_e32 v6, v6, v15
	v_max_f32_e32 v15, v18, v14
	v_min_f32_e32 v14, v18, v14
	v_max_f32_e32 v18, v13, v10
	v_min_f32_e32 v10, v13, v10
	v_max_f32_e32 v13, v8, v16
	v_min_f32_e32 v8, v8, v16
	v_max_f32_e32 v16, v17, v7
	v_min_f32_e32 v7, v17, v7
	v_max_f32_e32 v17, v12, v11
	v_min_f32_e32 v11, v12, v11
	v_max_f32_e32 v12, v3, v9
	v_min_f32_e32 v3, v3, v9
	v_max_f32_e32 v9, v4, v2
	v_min_f32_e32 v2, v4, v2
	v_max_f32_e32 v4, v5, v15
	v_min_f32_e32 v5, v5, v15
	v_max_f32_e32 v15, v6, v14
	v_min_f32_e32 v6, v6, v14
	v_max_f32_e32 v14, v18, v13
	v_min_f32_e32 v13, v18, v13
	v_max_f32_e32 v18, v10, v8
	v_min_f32_e32 v8, v10, v8
	v_max_f32_e32 v10, v16, v17
	v_min_f32_e32 v16, v16, v17
	v_max_f32_e32 v17, v7, v11
	v_min_f32_e32 v7, v7, v11
	v_max_f32_e32 v11, v12, v9
	v_min_f32_e32 v9, v12, v9
	v_max_f32_e32 v12, v3, v2
	v_min_f32_e32 v2, v3, v2
	ds_bpermute_b32 v3, v99, v2
	ds_bpermute_b32 v19, v99, v12
	ds_bpermute_b32 v20, v99, v9
	ds_bpermute_b32 v21, v99, v11
	ds_bpermute_b32 v22, v99, v7
	ds_bpermute_b32 v23, v99, v17
	s_waitcnt lgkmcnt(5)
	ds_bpermute_b32 v24, v99, v16
	ds_bpermute_b32 v33, v99, v4
	v_max_f32_e32 v3, v4, v3
	s_waitcnt lgkmcnt(6)
	ds_bpermute_b32 v25, v99, v10
	ds_bpermute_b32 v32, v99, v5
	v_max_f32_e32 v4, v5, v19
	s_waitcnt lgkmcnt(7)
	ds_bpermute_b32 v26, v99, v8
	ds_bpermute_b32 v31, v99, v15
	v_max_f32_e32 v5, v15, v20
	s_waitcnt lgkmcnt(8)
	ds_bpermute_b32 v27, v99, v18
	ds_bpermute_b32 v30, v99, v6
	v_max_f32_e32 v6, v6, v21
	s_waitcnt lgkmcnt(9)
	ds_bpermute_b32 v28, v99, v13
	ds_bpermute_b32 v29, v99, v14
	v_max_f32_e32 v14, v14, v22
	s_waitcnt lgkmcnt(10)
	v_max_f32_e32 v13, v13, v23
	s_waitcnt lgkmcnt(9)
	v_max_f32_e32 v15, v18, v24
	s_waitcnt lgkmcnt(7)
	v_max_f32_e32 v8, v8, v25
	s_waitcnt lgkmcnt(5)
	v_max_f32_e32 v10, v10, v26
	s_waitcnt lgkmcnt(3)
	v_max_f32_e32 v16, v16, v27
	s_waitcnt lgkmcnt(1)
	v_max_f32_e32 v17, v17, v28
	s_waitcnt lgkmcnt(0)
	v_max_f32_e32 v7, v7, v29
	v_max_f32_e32 v11, v11, v30
	v_max_f32_e32 v9, v9, v31
	v_max_f32_e32 v12, v12, v32
	v_max_f32_e32 v2, v2, v33
	v_max_f32_e32 v18, v3, v10
	v_min_f32_e32 v3, v3, v10
	v_max_f32_e32 v10, v4, v16
	v_min_f32_e32 v4, v4, v16
	v_max_f32_e32 v16, v5, v17
	v_min_f32_e32 v5, v5, v17
	v_max_f32_e32 v17, v6, v7
	v_min_f32_e32 v6, v6, v7
	v_max_f32_e32 v7, v14, v11
	v_min_f32_e32 v11, v14, v11
	v_max_f32_e32 v14, v13, v9
	v_min_f32_e32 v9, v13, v9
	v_max_f32_e32 v13, v15, v12
	v_min_f32_e32 v12, v15, v12
	v_max_f32_e32 v15, v8, v2
	v_min_f32_e32 v2, v8, v2
	v_max_f32_e32 v8, v18, v7
	v_min_f32_e32 v7, v18, v7
	v_max_f32_e32 v18, v10, v14
	v_min_f32_e32 v10, v10, v14
	v_max_f32_e32 v14, v16, v13
	v_min_f32_e32 v13, v16, v13
	v_max_f32_e32 v16, v17, v15
	v_min_f32_e32 v15, v17, v15
	v_max_f32_e32 v17, v3, v11
	v_min_f32_e32 v3, v3, v11
	v_max_f32_e32 v11, v4, v9
	v_min_f32_e32 v4, v4, v9
	v_max_f32_e32 v9, v5, v12
	v_min_f32_e32 v5, v5, v12
	v_max_f32_e32 v12, v6, v2
	v_min_f32_e32 v2, v6, v2
	v_max_f32_e32 v6, v8, v14
	v_min_f32_e32 v8, v8, v14
	v_max_f32_e32 v14, v18, v16
	v_min_f32_e32 v16, v18, v16
	v_max_f32_e32 v18, v7, v13
	v_max_f32_e32 v19, v10, v15
	s_movk_i32 s8, 0x7f
	v_min_f32_e32 v13, v7, v13
	v_min_f32_e32 v10, v10, v15
	v_max_f32_e32 v15, v17, v9
	v_min_f32_e32 v21, v17, v9
	v_max_f32_e32 v17, v11, v12
	v_min_f32_e32 v22, v11, v12
	v_max_f32_e32 v23, v3, v5
	v_min_f32_e32 v3, v3, v5
	v_max_f32_e32 v5, v4, v2
	v_min_f32_e32 v24, v4, v2
	v_max_f32_e32 v9, v18, v19
	v_min_f32_e32 v12, v18, v19
	v_and_b32_sdwa v18, v63, s8 dst_sel:BYTE_1 dst_unused:UNUSED_PAD src0_sel:DWORD src1_sel:DWORD
	v_max_f32_e32 v2, v6, v14
	v_min_f32_e32 v4, v6, v14
	v_max_f32_e32 v11, v13, v10
	v_min_f32_e32 v10, v13, v10
	v_max_f32_e32 v14, v23, v5
	v_min_f32_e32 v13, v23, v5
	v_max_f32_e32 v6, v3, v24
	v_min_f32_e32 v5, v3, v24
	v_and_b32_sdwa v3, v75, s8 dst_sel:BYTE_1 dst_unused:UNUSED_PAD src0_sel:DWORD src1_sel:DWORD
	v_bitop3_b16 v18, v71, v18, s8 bitop3:0xec
	v_bitop3_b16 v3, v79, v3, s8 bitop3:0xec
	v_lshlrev_b32_e32 v18, 16, v18
	v_or_b32_sdwa v23, v3, v18 dst_sel:DWORD dst_unused:UNUSED_PAD src0_sel:WORD_0 src1_sel:DWORD
	v_and_b32_sdwa v18, v83, s8 dst_sel:BYTE_1 dst_unused:UNUSED_PAD src0_sel:DWORD src1_sel:DWORD
; DEV void ce(float& a, float& b) { float hi = fmaxf(a, b), lo = fminf(a, b); a = hi; b = lo; }
; DEV void phase_peer_score(const Params& p, int layer, int M, char* smem) {
;     ...
; #pragma unroll
;     for (int i = 0; i < 16; i++) R[i] = -3.0e38f;
; #pragma unroll
;     for (int i = 0; i < 16; i++)
; #pragma unroll
;       for (int j = 0; j < 16; j++)
;         if ((i + 1) * (j + 1) <= 16) {
;           float v = L0[i] + L1[j];
;           v = __uint_as_float((__float_as_uint(v) & ~255u) | (unsigned)(i * 16 + j));
; #pragma unroll
;           for (int t = 0; t < 16; t++)
;             if (t >= (i + 1) * (j + 1) - 1) ce(R[t], v);
;         }
;     unsigned char* tab = (unsigned char*)smem + 73728 + (w * 16 + l15) * 32;
; #pragma unroll
;     for (int i = 0; i < 16; i++) { tab[i] = (unsigned char)(__float_as_uint(L0[i]) & 127u); tab[16 + i] = (unsigned char)(__float_as_uint(L1[i]) & 127u); }
	v_and_b32_sdwa v3, v91, s8 dst_sel:BYTE_1 dst_unused:UNUSED_PAD src0_sel:DWORD src1_sel:DWORD
	v_bitop3_b16 v18, v87, v18, s8 bitop3:0xec
	v_bitop3_b16 v3, v100, v3, s8 bitop3:0xec
	v_lshlrev_b32_e32 v18, 16, v18
	v_max_f32_e32 v7, v8, v16
	v_min_f32_e32 v8, v8, v16
	v_max_f32_e32 v20, v15, v17
	v_min_f32_e32 v17, v15, v17
	v_max_f32_e32 v16, v21, v22
	v_min_f32_e32 v15, v21, v22
	v_or_b32_sdwa v22, v3, v18 dst_sel:DWORD dst_unused:UNUSED_PAD src0_sel:WORD_0 src1_sel:DWORD
	v_and_b32_sdwa v18, v10, s8 dst_sel:BYTE_1 dst_unused:UNUSED_PAD src0_sel:DWORD src1_sel:DWORD
	v_and_b32_sdwa v3, v12, s8 dst_sel:BYTE_1 dst_unused:UNUSED_PAD src0_sel:DWORD src1_sel:DWORD
	v_bitop3_b16 v18, v11, v18, s8 bitop3:0xec
	v_bitop3_b16 v3, v9, v3, s8 bitop3:0xec
	v_lshlrev_b32_e32 v18, 16, v18
	v_or_b32_sdwa v27, v3, v18 dst_sel:DWORD dst_unused:UNUSED_PAD src0_sel:WORD_0 src1_sel:DWORD
	v_and_b32_sdwa v18, v8, s8 dst_sel:BYTE_1 dst_unused:UNUSED_PAD src0_sel:DWORD src1_sel:DWORD
	v_and_b32_sdwa v3, v4, s8 dst_sel:BYTE_1 dst_unused:UNUSED_PAD src0_sel:DWORD src1_sel:DWORD
	v_bitop3_b16 v18, v7, v18, s8 bitop3:0xec
	v_bitop3_b16 v3, v2, v3, s8 bitop3:0xec
	v_lshlrev_b32_e32 v18, 16, v18
	v_or_b32_sdwa v26, v3, v18 dst_sel:DWORD dst_unused:UNUSED_PAD src0_sel:WORD_0 src1_sel:DWORD
	v_and_b32_sdwa v18, v0, s8 dst_sel:BYTE_1 dst_unused:UNUSED_PAD src0_sel:DWORD src1_sel:DWORD
	v_and_b32_sdwa v3, v39, s8 dst_sel:BYTE_1 dst_unused:UNUSED_PAD src0_sel:DWORD src1_sel:DWORD
	v_bitop3_b16 v18, v43, v18, s8 bitop3:0xec
	v_bitop3_b16 v3, v51, v3, s8 bitop3:0xec
	v_lshlrev_b32_e32 v18, 16, v18
	v_or_b32_sdwa v25, v3, v18 dst_sel:DWORD dst_unused:UNUSED_PAD src0_sel:WORD_0 src1_sel:DWORD
	v_and_b32_sdwa v18, v47, s8 dst_sel:BYTE_1 dst_unused:UNUSED_PAD src0_sel:DWORD src1_sel:DWORD
	v_and_b32_sdwa v3, v59, s8 dst_sel:BYTE_1 dst_unused:UNUSED_PAD src0_sel:DWORD src1_sel:DWORD
	v_bitop3_b16 v18, v55, v18, s8 bitop3:0xec
	v_bitop3_b16 v3, v67, v3, s8 bitop3:0xec
	v_lshlrev_b32_e32 v18, 16, v18
	v_or_b32_sdwa v24, v3, v18 dst_sel:DWORD dst_unused:UNUSED_PAD src0_sel:WORD_0 src1_sel:DWORD
	v_and_b32_sdwa v18, v5, s8 dst_sel:BYTE_1 dst_unused:UNUSED_PAD src0_sel:DWORD src1_sel:DWORD
	v_and_b32_sdwa v3, v13, s8 dst_sel:BYTE_1 dst_unused:UNUSED_PAD src0_sel:DWORD src1_sel:DWORD
	v_bitop3_b16 v18, v6, v18, s8 bitop3:0xec
	v_bitop3_b16 v3, v14, v3, s8 bitop3:0xec
	v_lshlrev_b32_e32 v18, 16, v18
	v_or_b32_sdwa v29, v3, v18 dst_sel:DWORD dst_unused:UNUSED_PAD src0_sel:WORD_0 src1_sel:DWORD
	v_and_b32_sdwa v18, v15, s8 dst_sel:BYTE_1 dst_unused:UNUSED_PAD src0_sel:DWORD src1_sel:DWORD
	v_and_b32_sdwa v3, v17, s8 dst_sel:BYTE_1 dst_unused:UNUSED_PAD src0_sel:DWORD src1_sel:DWORD
	v_bitop3_b16 v18, v16, v18, s8 bitop3:0xec
	v_bitop3_b16 v3, v20, v3, s8 bitop3:0xec
	v_lshlrev_b32_e32 v18, 16, v18
	v_or_b32_sdwa v28, v3, v18 dst_sel:DWORD dst_unused:UNUSED_PAD src0_sel:WORD_0 src1_sel:DWORD
	ds_write_b128 v138, v[22:25]
	ds_write_b128 v138, v[26:29] offset:16
	s_and_saveexec_b64 s[8:9], s[38:39]
	s_cbranch_execz .LBB0_627
	s_movk_i32 s18, 0xff00
	v_add_f32_e32 v164, v100, v2
	v_and_or_b32 v164, v164, s18, 0
	v_max_f32_e32 v148, 0xff61b1e6, v164
	v_add_f32_e32 v164, v100, v4
	v_and_or_b32 v164, v164, s18, 1
	v_max_f32_e32 v149, 0xff61b1e6, v164
	v_add_f32_e32 v164, v100, v7
	v_and_or_b32 v164, v164, s18, 2
	v_max_f32_e32 v150, 0xff61b1e6, v164
	v_add_f32_e32 v164, v100, v8
	v_and_or_b32 v164, v164, s18, 3
	v_max_f32_e32 v151, 0xff61b1e6, v164
	v_add_f32_e32 v164, v100, v9
	v_and_or_b32 v164, v164, s18, 4
	v_max_f32_e32 v152, 0xff61b1e6, v164
	v_add_f32_e32 v164, v100, v12
	v_and_or_b32 v164, v164, s18, 5
	v_max_f32_e32 v153, 0xff61b1e6, v164
	v_add_f32_e32 v164, v100, v11
	v_and_or_b32 v164, v164, s18, 6
	v_max_f32_e32 v154, 0xff61b1e6, v164
	v_add_f32_e32 v164, v100, v10
	v_and_or_b32 v164, v164, s18, 7
	v_max_f32_e32 v155, 0xff61b1e6, v164
	v_add_f32_e32 v164, v100, v20
	v_and_or_b32 v164, v164, s18, 8
	v_max_f32_e32 v156, 0xff61b1e6, v164
	v_add_f32_e32 v164, v100, v17
	v_and_or_b32 v164, v164, s18, 9
	v_max_f32_e32 v157, 0xff61b1e6, v164
	v_add_f32_e32 v164, v100, v16
	v_and_or_b32 v164, v164, s18, 10
	v_max_f32_e32 v158, 0xff61b1e6, v164
	v_add_f32_e32 v164, v100, v15
	v_and_or_b32 v164, v164, s18, 11
	v_max_f32_e32 v159, 0xff61b1e6, v164
	v_add_f32_e32 v164, v100, v14
	v_and_or_b32 v164, v164, s18, 12
	v_max_f32_e32 v160, 0xff61b1e6, v164
	v_add_f32_e32 v164, v100, v13
	v_and_or_b32 v164, v164, s18, 13
	v_max_f32_e32 v161, 0xff61b1e6, v164
	v_add_f32_e32 v164, v100, v6
	v_and_or_b32 v164, v164, s18, 14
	v_max_f32_e32 v162, 0xff61b1e6, v164
	v_add_f32_e32 v164, v100, v5
	v_and_or_b32 v164, v164, s18, 15
	v_max_f32_e32 v163, 0xff61b1e6, v164
	v_add_f32_e32 v164, v91, v2
	v_and_or_b32 v164, v164, s18, 16
	v_med3_f32 v163, v162, v163, v164
	v_med3_f32 v162, v161, v162, v164
	v_med3_f32 v161, v160, v161, v164
	v_med3_f32 v160, v159, v160, v164
	v_med3_f32 v159, v158, v159, v164
	v_med3_f32 v158, v157, v158, v164
	v_med3_f32 v157, v156, v157, v164
	v_med3_f32 v156, v155, v156, v164
	v_med3_f32 v155, v154, v155, v164
	v_med3_f32 v154, v153, v154, v164
	v_med3_f32 v153, v152, v153, v164
	v_med3_f32 v152, v151, v152, v164
	v_med3_f32 v151, v150, v151, v164
	v_med3_f32 v150, v149, v150, v164
	v_max_f32_e32 v149, v149, v164
	v_add_f32_e32 v164, v91, v4
	v_and_or_b32 v164, v164, s18, 17
	v_med3_f32 v163, v162, v163, v164
	v_med3_f32 v162, v161, v162, v164
	v_med3_f32 v161, v160, v161, v164
	v_med3_f32 v160, v159, v160, v164
	v_med3_f32 v159, v158, v159, v164
	v_med3_f32 v158, v157, v158, v164
	v_med3_f32 v157, v156, v157, v164
	v_med3_f32 v156, v155, v156, v164
	v_med3_f32 v155, v154, v155, v164
; DEV void ce(float& a, float& b) { float hi = fmaxf(a, b), lo = fminf(a, b); a = hi; b = lo; }
; DEV void phase_peer_score(const Params& p, int layer, int M, char* smem) {
;     ...
; #pragma unroll
;     for (int i = 0; i < 16; i++)
; #pragma unroll
;       for (int j = 0; j < 16; j++)
;         if ((i + 1) * (j + 1) <= 16) {
;           float v = L0[i] + L1[j];
;           v = __uint_as_float((__float_as_uint(v) & ~255u) | (unsigned)(i * 16 + j));
; #pragma unroll
;           for (int t = 0; t < 16; t++)
;             if (t >= (i + 1) * (j + 1) - 1) ce(R[t], v);
;         }
	v_med3_f32 v154, v153, v154, v164
	v_med3_f32 v153, v152, v153, v164
	v_med3_f32 v152, v151, v152, v164
	v_max_f32_e32 v151, v151, v164
	v_add_f32_e32 v164, v91, v7
	v_and_or_b32 v164, v164, s18, 18
	v_med3_f32 v163, v162, v163, v164
	v_med3_f32 v162, v161, v162, v164
	v_med3_f32 v161, v160, v161, v164
	v_med3_f32 v160, v159, v160, v164
	v_med3_f32 v159, v158, v159, v164
	v_med3_f32 v158, v157, v158, v164
	v_med3_f32 v157, v156, v157, v164
	v_med3_f32 v156, v155, v156, v164
	v_med3_f32 v155, v154, v155, v164
	v_med3_f32 v154, v153, v154, v164
	v_max_f32_e32 v153, v153, v164
	v_add_f32_e32 v164, v91, v8
	v_and_or_b32 v164, v164, s18, 19
	v_med3_f32 v163, v162, v163, v164
	v_med3_f32 v162, v161, v162, v164
	v_med3_f32 v161, v160, v161, v164
	v_med3_f32 v160, v159, v160, v164
	v_med3_f32 v159, v158, v159, v164
	v_med3_f32 v158, v157, v158, v164
	v_med3_f32 v157, v156, v157, v164
	v_med3_f32 v156, v155, v156, v164
	v_max_f32_e32 v155, v155, v164
	v_add_f32_e32 v164, v91, v9
	v_and_or_b32 v164, v164, s18, 20
	v_med3_f32 v163, v162, v163, v164
	v_med3_f32 v162, v161, v162, v164
	v_med3_f32 v161, v160, v161, v164
	v_med3_f32 v160, v159, v160, v164
	v_med3_f32 v159, v158, v159, v164
	v_med3_f32 v158, v157, v158, v164
	v_max_f32_e32 v157, v157, v164
	v_add_f32_e32 v164, v91, v12
	v_and_or_b32 v164, v164, s18, 21
	v_med3_f32 v163, v162, v163, v164
	v_med3_f32 v162, v161, v162, v164
	v_med3_f32 v161, v160, v161, v164
	v_med3_f32 v160, v159, v160, v164
	v_max_f32_e32 v159, v159, v164
	v_add_f32_e32 v164, v91, v11
	v_and_or_b32 v164, v164, s18, 22
	v_med3_f32 v163, v162, v163, v164
	v_med3_f32 v162, v161, v162, v164
	v_max_f32_e32 v161, v161, v164
	v_add_f32_e32 v164, v91, v10
	v_and_or_b32 v164, v164, s18, 23
	v_max_f32_e32 v163, v163, v164
	v_add_f32_e32 v164, v87, v2
	v_and_or_b32 v164, v164, s18, 32
	v_med3_f32 v163, v162, v163, v164
	v_med3_f32 v162, v161, v162, v164
	v_med3_f32 v161, v160, v161, v164
	v_med3_f32 v160, v159, v160, v164
	v_med3_f32 v159, v158, v159, v164
	v_med3_f32 v158, v157, v158, v164
	v_med3_f32 v157, v156, v157, v164
	v_med3_f32 v156, v155, v156, v164
	v_med3_f32 v155, v154, v155, v164
	v_med3_f32 v154, v153, v154, v164
	v_med3_f32 v153, v152, v153, v164
	v_med3_f32 v152, v151, v152, v164
	v_med3_f32 v151, v150, v151, v164
	v_max_f32_e32 v150, v150, v164
	v_add_f32_e32 v164, v87, v4
	v_and_or_b32 v164, v164, s18, 33
	v_med3_f32 v163, v162, v163, v164
	v_med3_f32 v162, v161, v162, v164
	v_med3_f32 v161, v160, v161, v164
	v_med3_f32 v160, v159, v160, v164
	v_med3_f32 v159, v158, v159, v164
	v_med3_f32 v158, v157, v158, v164
	v_med3_f32 v157, v156, v157, v164
	v_med3_f32 v156, v155, v156, v164
	v_med3_f32 v155, v154, v155, v164
	v_med3_f32 v154, v153, v154, v164
	v_max_f32_e32 v153, v153, v164
	v_add_f32_e32 v164, v87, v7
	v_and_or_b32 v164, v164, s18, 34
	v_med3_f32 v163, v162, v163, v164
	v_med3_f32 v162, v161, v162, v164
	v_med3_f32 v161, v160, v161, v164
	v_med3_f32 v160, v159, v160, v164
	v_med3_f32 v159, v158, v159, v164
	v_med3_f32 v158, v157, v158, v164
	v_med3_f32 v157, v156, v157, v164
	v_max_f32_e32 v156, v156, v164
	v_add_f32_e32 v164, v87, v8
	v_and_or_b32 v164, v164, s18, 35
	v_med3_f32 v163, v162, v163, v164
	v_med3_f32 v162, v161, v162, v164
	v_med3_f32 v161, v160, v161, v164
	v_med3_f32 v160, v159, v160, v164
	v_max_f32_e32 v159, v159, v164
	v_add_f32_e32 v164, v87, v9
	v_and_or_b32 v164, v164, s18, 36
	v_med3_f32 v163, v162, v163, v164
	v_max_f32_e32 v162, v162, v164
	v_add_f32_e32 v164, v83, v2
	v_and_or_b32 v164, v164, s18, 48
	v_med3_f32 v163, v162, v163, v164
	v_med3_f32 v162, v161, v162, v164
	v_med3_f32 v161, v160, v161, v164
	v_med3_f32 v160, v159, v160, v164
	v_med3_f32 v159, v158, v159, v164
	v_med3_f32 v158, v157, v158, v164
	v_med3_f32 v157, v156, v157, v164
	v_med3_f32 v156, v155, v156, v164
	v_med3_f32 v155, v154, v155, v164
	v_med3_f32 v154, v153, v154, v164
	v_med3_f32 v153, v152, v153, v164
	v_med3_f32 v152, v151, v152, v164
	v_max_f32_e32 v151, v151, v164
	v_add_f32_e32 v164, v83, v4
	v_and_or_b32 v164, v164, s18, 49
	v_med3_f32 v163, v162, v163, v164
	v_med3_f32 v162, v161, v162, v164
	v_med3_f32 v161, v160, v161, v164
	v_med3_f32 v160, v159, v160, v164
	v_med3_f32 v159, v158, v159, v164
	v_med3_f32 v158, v157, v158, v164
	v_med3_f32 v157, v156, v157, v164
	v_med3_f32 v156, v155, v156, v164
	v_max_f32_e32 v155, v155, v164
	v_add_f32_e32 v164, v83, v7
	v_and_or_b32 v164, v164, s18, 50
	v_med3_f32 v163, v162, v163, v164
	v_med3_f32 v162, v161, v162, v164
	v_med3_f32 v161, v160, v161, v164
	v_med3_f32 v160, v159, v160, v164
	v_max_f32_e32 v159, v159, v164
	v_add_f32_e32 v164, v83, v8
	v_and_or_b32 v164, v164, s18, 51
	v_max_f32_e32 v163, v163, v164
	v_add_f32_e32 v164, v79, v2
	v_and_or_b32 v164, v164, s18, 64
	v_med3_f32 v163, v162, v163, v164
	v_med3_f32 v162, v161, v162, v164
	v_med3_f32 v161, v160, v161, v164
	v_med3_f32 v160, v159, v160, v164
	v_med3_f32 v159, v158, v159, v164
	v_med3_f32 v158, v157, v158, v164
	v_med3_f32 v157, v156, v157, v164
	v_med3_f32 v156, v155, v156, v164
	v_med3_f32 v155, v154, v155, v164
	v_med3_f32 v154, v153, v154, v164
	v_med3_f32 v153, v152, v153, v164
	v_max_f32_e32 v152, v152, v164
	v_add_f32_e32 v164, v79, v4
	v_and_b32_e32 v164, 0xffffff00, v164
	v_or_b32_e32 v164, 0x41, v164
	v_med3_f32 v163, v162, v163, v164
	v_med3_f32 v162, v161, v162, v164
	v_med3_f32 v161, v160, v161, v164
	v_med3_f32 v160, v159, v160, v164
	v_med3_f32 v159, v158, v159, v164
	v_med3_f32 v158, v157, v158, v164
	v_max_f32_e32 v157, v157, v164
	v_add_f32_e32 v164, v79, v7
	v_and_b32_e32 v164, 0xffffff00, v164
	v_or_b32_e32 v164, 0x42, v164
	v_med3_f32 v163, v162, v163, v164
; DEV void ce(float& a, float& b) { float hi = fmaxf(a, b), lo = fminf(a, b); a = hi; b = lo; }
; DEV void phase_peer_score(const Params& p, int layer, int M, char* smem) {
;     ...
; #pragma unroll
;     for (int i = 0; i < 16; i++)
; #pragma unroll
;       for (int j = 0; j < 16; j++)
;         if ((i + 1) * (j + 1) <= 16) {
;           float v = L0[i] + L1[j];
;           v = __uint_as_float((__float_as_uint(v) & ~255u) | (unsigned)(i * 16 + j));
; #pragma unroll
;           for (int t = 0; t < 16; t++)
;             if (t >= (i + 1) * (j + 1) - 1) ce(R[t], v);
;         }
	v_max_f32_e32 v162, v162, v164
	v_add_f32_e32 v164, v75, v2
	v_and_b32_e32 v164, 0xffffff00, v164
	v_or_b32_e32 v164, 0x50, v164
	v_med3_f32 v163, v162, v163, v164
	v_med3_f32 v162, v161, v162, v164
	v_med3_f32 v161, v160, v161, v164
	v_med3_f32 v160, v159, v160, v164
	v_med3_f32 v159, v158, v159, v164
	v_med3_f32 v158, v157, v158, v164
	v_med3_f32 v157, v156, v157, v164
	v_med3_f32 v156, v155, v156, v164
	v_med3_f32 v155, v154, v155, v164
	v_med3_f32 v154, v153, v154, v164
	v_max_f32_e32 v153, v153, v164
	v_add_f32_e32 v164, v75, v4
	v_and_b32_e32 v164, 0xffffff00, v164
	v_or_b32_e32 v164, 0x51, v164
	v_med3_f32 v163, v162, v163, v164
	v_med3_f32 v162, v161, v162, v164
	v_med3_f32 v161, v160, v161, v164
	v_med3_f32 v160, v159, v160, v164
	v_max_f32_e32 v159, v159, v164
	v_add_f32_e32 v164, v71, v2
	v_and_b32_e32 v164, 0xffffff00, v164
	v_or_b32_e32 v164, 0x60, v164
	v_med3_f32 v163, v162, v163, v164
	v_med3_f32 v162, v161, v162, v164
	v_med3_f32 v161, v160, v161, v164
	v_med3_f32 v160, v159, v160, v164
	v_med3_f32 v159, v158, v159, v164
	v_med3_f32 v158, v157, v158, v164
	v_med3_f32 v157, v156, v157, v164
	v_med3_f32 v156, v155, v156, v164
	v_med3_f32 v155, v154, v155, v164
	v_max_f32_e32 v154, v154, v164
	v_add_f32_e32 v164, v71, v4
	v_and_b32_e32 v164, 0xffffff00, v164
	v_or_b32_e32 v164, 0x61, v164
	v_med3_f32 v163, v162, v163, v164
	v_med3_f32 v162, v161, v162, v164
	v_max_f32_e32 v161, v161, v164
	v_add_f32_e32 v164, v63, v2
	v_and_b32_e32 v164, 0xffffff00, v164
	v_or_b32_e32 v164, 0x70, v164
	v_med3_f32 v163, v162, v163, v164
	v_med3_f32 v162, v161, v162, v164
	v_med3_f32 v161, v160, v161, v164
	v_med3_f32 v160, v159, v160, v164
	v_med3_f32 v159, v158, v159, v164
	v_med3_f32 v158, v157, v158, v164
	v_med3_f32 v157, v156, v157, v164
	v_med3_f32 v156, v155, v156, v164
	v_max_f32_e32 v155, v155, v164
	v_add_f32_e32 v164, v63, v4
	v_and_b32_e32 v164, 0xffffff00, v164
	v_or_b32_e32 v164, 0x71, v164
	v_max_f32_e32 v163, v163, v164
	v_add_f32_e32 v164, v67, v2
	v_and_b32_e32 v164, 0xffffff00, v164
	v_or_b32_e32 v164, 0x80, v164
	v_med3_f32 v163, v162, v163, v164
	v_med3_f32 v162, v161, v162, v164
	v_med3_f32 v161, v160, v161, v164
	v_med3_f32 v160, v159, v160, v164
	v_med3_f32 v159, v158, v159, v164
	v_med3_f32 v158, v157, v158, v164
	v_med3_f32 v157, v156, v157, v164
	v_max_f32_e32 v156, v156, v164
	v_add_f32_e32 v164, v59, v2
	v_and_b32_e32 v164, 0xffffff00, v164
	v_or_b32_e32 v164, 0x90, v164
	v_med3_f32 v163, v162, v163, v164
	v_med3_f32 v162, v161, v162, v164
	v_med3_f32 v161, v160, v161, v164
	v_med3_f32 v160, v159, v160, v164
	v_med3_f32 v159, v158, v159, v164
	v_med3_f32 v158, v157, v158, v164
	v_max_f32_e32 v157, v157, v164
	v_add_f32_e32 v164, v55, v2
	v_and_b32_e32 v164, 0xffffff00, v164
	v_or_b32_e32 v164, 0xa0, v164
	v_med3_f32 v163, v162, v163, v164
	v_med3_f32 v162, v161, v162, v164
	v_med3_f32 v161, v160, v161, v164
	v_med3_f32 v160, v159, v160, v164
	v_med3_f32 v159, v158, v159, v164
	v_max_f32_e32 v158, v158, v164
	v_add_f32_e32 v164, v47, v2
	v_and_b32_e32 v164, 0xffffff00, v164
	v_or_b32_e32 v164, 0xb0, v164
	v_med3_f32 v163, v162, v163, v164
	v_med3_f32 v162, v161, v162, v164
	v_med3_f32 v161, v160, v161, v164
	v_med3_f32 v160, v159, v160, v164
	v_max_f32_e32 v159, v159, v164
	v_add_f32_e32 v164, v51, v2
	v_and_b32_e32 v164, 0xffffff00, v164
	v_or_b32_e32 v164, 0xc0, v164
	v_med3_f32 v163, v162, v163, v164
	v_med3_f32 v162, v161, v162, v164
	v_med3_f32 v161, v160, v161, v164
	v_max_f32_e32 v160, v160, v164
	v_add_f32_e32 v164, v39, v2
	v_and_b32_e32 v164, 0xffffff00, v164
	v_or_b32_e32 v164, 0xd0, v164
	v_med3_f32 v163, v162, v163, v164
	v_med3_f32 v162, v161, v162, v164
	v_max_f32_e32 v161, v161, v164
	v_add_f32_e32 v164, v43, v2
	v_and_b32_e32 v164, 0xffffff00, v164
	v_or_b32_e32 v164, 0xe0, v164
	v_med3_f32 v163, v162, v163, v164
	v_max_f32_e32 v162, v162, v164
	v_add_f32_e32 v164, v0, v2
	v_and_b32_e32 v164, 0xffffff00, v164
	v_or_b32_e32 v164, 0xf0, v164
	v_max_f32_e32 v163, v163, v164
	v_cmp_le_f32_e64 s[40:41], v148, v149
	v_cmp_le_f32_e32 vcc, v149, v150
	s_or_b64 s[40:41], s[40:41], vcc
	v_cmp_le_f32_e32 vcc, v150, v151
	s_or_b64 s[40:41], s[40:41], vcc
	v_cmp_le_f32_e32 vcc, v151, v152
	s_or_b64 s[40:41], s[40:41], vcc
	v_cmp_le_f32_e32 vcc, v152, v153
	s_or_b64 s[40:41], s[40:41], vcc
	v_cmp_le_f32_e32 vcc, v153, v154
	s_or_b64 s[40:41], s[40:41], vcc
	v_cmp_le_f32_e32 vcc, v154, v155
	s_or_b64 s[40:41], s[40:41], vcc
	v_cmp_le_f32_e32 vcc, v155, v156
	s_or_b64 s[40:41], s[40:41], vcc
	v_cmp_le_f32_e32 vcc, v156, v157
	s_or_b64 s[40:41], s[40:41], vcc
	v_cmp_le_f32_e32 vcc, v157, v158
	s_or_b64 s[40:41], s[40:41], vcc
	v_cmp_le_f32_e32 vcc, v158, v159
	s_or_b64 s[40:41], s[40:41], vcc
	v_cmp_le_f32_e32 vcc, v159, v160
	s_or_b64 s[40:41], s[40:41], vcc
	v_cmp_le_f32_e32 vcc, v160, v161
	s_or_b64 s[40:41], s[40:41], vcc
	v_cmp_le_f32_e32 vcc, v161, v162
	s_or_b64 s[40:41], s[40:41], vcc
	v_cmp_le_f32_e32 vcc, v162, v163
	s_or_b64 s[40:41], s[40:41], vcc
	s_and_b64 s[40:41], s[40:41], exec
	s_cbranch_scc0 .Lmed3_ok_bb_637
; DEV void ce(float& a, float& b) { float hi = fmaxf(a, b), lo = fminf(a, b); a = hi; b = lo; }
; DEV void phase_peer_score(const Params& p, int layer, int M, char* smem) {
;     ...
; #pragma unroll
;     for (int i = 0; i < 16; i++) R[i] = -3.0e38f;
; #pragma unroll
;     for (int i = 0; i < 16; i++)
; #pragma unroll
;       for (int j = 0; j < 16; j++)
;         if ((i + 1) * (j + 1) <= 16) {
;           float v = L0[i] + L1[j];
;           v = __uint_as_float((__float_as_uint(v) & ~255u) | (unsigned)(i * 16 + j));
; #pragma unroll
;           for (int t = 0; t < 16; t++)
;             if (t >= (i + 1) * (j + 1) - 1) ce(R[t], v);
;         }
	v_mov_b32_e32 v148, 0xff61b1e6
	v_mov_b32_e32 v149, 0xff61b1e6
	v_mov_b32_e32 v150, 0xff61b1e6
	v_mov_b32_e32 v151, 0xff61b1e6
	v_mov_b32_e32 v152, 0xff61b1e6
	v_mov_b32_e32 v153, 0xff61b1e6
	v_mov_b32_e32 v154, 0xff61b1e6
	v_mov_b32_e32 v155, 0xff61b1e6
	v_mov_b32_e32 v156, 0xff61b1e6
	v_mov_b32_e32 v157, 0xff61b1e6
	v_mov_b32_e32 v158, 0xff61b1e6
	v_mov_b32_e32 v159, 0xff61b1e6
	v_mov_b32_e32 v160, 0xff61b1e6
	v_mov_b32_e32 v161, 0xff61b1e6
	v_mov_b32_e32 v162, 0xff61b1e6
	v_mov_b32_e32 v163, 0xff61b1e6
	v_add_f32_e32 v164, v100, v2
	v_and_or_b32 v164, v164, s18, 0
	v_min_f32_e32 v165, v148, v164
	v_max_f32_e32 v148, v148, v164
	v_min_f32_e32 v164, v149, v165
	v_max_f32_e32 v149, v149, v165
	v_min_f32_e32 v165, v150, v164
	v_max_f32_e32 v150, v150, v164
	v_min_f32_e32 v164, v151, v165
	v_max_f32_e32 v151, v151, v165
	v_min_f32_e32 v165, v152, v164
	v_max_f32_e32 v152, v152, v164
	v_min_f32_e32 v164, v153, v165
	v_max_f32_e32 v153, v153, v165
	v_min_f32_e32 v165, v154, v164
	v_max_f32_e32 v154, v154, v164
	v_min_f32_e32 v164, v155, v165
	v_max_f32_e32 v155, v155, v165
	v_min_f32_e32 v165, v156, v164
	v_max_f32_e32 v156, v156, v164
	v_min_f32_e32 v164, v157, v165
	v_max_f32_e32 v157, v157, v165
	v_min_f32_e32 v165, v158, v164
	v_max_f32_e32 v158, v158, v164
	v_min_f32_e32 v164, v159, v165
	v_max_f32_e32 v159, v159, v165
	v_min_f32_e32 v165, v160, v164
	v_max_f32_e32 v160, v160, v164
	v_min_f32_e32 v164, v161, v165
	v_max_f32_e32 v161, v161, v165
	v_min_f32_e32 v165, v162, v164
	v_max_f32_e32 v162, v162, v164
	v_max_f32_e32 v163, v163, v165
	v_add_f32_e32 v164, v100, v4
	v_and_or_b32 v164, v164, s18, 1
	v_min_f32_e32 v165, v149, v164
	v_max_f32_e32 v149, v149, v164
	v_min_f32_e32 v164, v150, v165
	v_max_f32_e32 v150, v150, v165
	v_min_f32_e32 v165, v151, v164
	v_max_f32_e32 v151, v151, v164
	v_min_f32_e32 v164, v152, v165
	v_max_f32_e32 v152, v152, v165
	v_min_f32_e32 v165, v153, v164
	v_max_f32_e32 v153, v153, v164
	v_min_f32_e32 v164, v154, v165
	v_max_f32_e32 v154, v154, v165
	v_min_f32_e32 v165, v155, v164
	v_max_f32_e32 v155, v155, v164
	v_min_f32_e32 v164, v156, v165
	v_max_f32_e32 v156, v156, v165
	v_min_f32_e32 v165, v157, v164
	v_max_f32_e32 v157, v157, v164
	v_min_f32_e32 v164, v158, v165
	v_max_f32_e32 v158, v158, v165
	v_min_f32_e32 v165, v159, v164
	v_max_f32_e32 v159, v159, v164
	v_min_f32_e32 v164, v160, v165
	v_max_f32_e32 v160, v160, v165
	v_min_f32_e32 v165, v161, v164
	v_max_f32_e32 v161, v161, v164
	v_min_f32_e32 v164, v162, v165
	v_max_f32_e32 v162, v162, v165
	v_max_f32_e32 v163, v163, v164
	v_add_f32_e32 v164, v100, v7
	v_and_or_b32 v164, v164, s18, 2
	v_min_f32_e32 v165, v150, v164
	v_max_f32_e32 v150, v150, v164
	v_min_f32_e32 v164, v151, v165
	v_max_f32_e32 v151, v151, v165
	v_min_f32_e32 v165, v152, v164
	v_max_f32_e32 v152, v152, v164
	v_min_f32_e32 v164, v153, v165
	v_max_f32_e32 v153, v153, v165
	v_min_f32_e32 v165, v154, v164
	v_max_f32_e32 v154, v154, v164
	v_min_f32_e32 v164, v155, v165
	v_max_f32_e32 v155, v155, v165
	v_min_f32_e32 v165, v156, v164
	v_max_f32_e32 v156, v156, v164
	v_min_f32_e32 v164, v157, v165
	v_max_f32_e32 v157, v157, v165
	v_min_f32_e32 v165, v158, v164
	v_max_f32_e32 v158, v158, v164
	v_min_f32_e32 v164, v159, v165
	v_max_f32_e32 v159, v159, v165
	v_min_f32_e32 v165, v160, v164
	v_max_f32_e32 v160, v160, v164
	v_min_f32_e32 v164, v161, v165
	v_max_f32_e32 v161, v161, v165
	v_min_f32_e32 v165, v162, v164
	v_max_f32_e32 v162, v162, v164
	v_max_f32_e32 v163, v163, v165
	v_add_f32_e32 v164, v100, v8
	v_and_or_b32 v164, v164, s18, 3
	v_min_f32_e32 v165, v151, v164
	v_max_f32_e32 v151, v151, v164
	v_min_f32_e32 v164, v152, v165
	v_max_f32_e32 v152, v152, v165
	v_min_f32_e32 v165, v153, v164
	v_max_f32_e32 v153, v153, v164
	v_min_f32_e32 v164, v154, v165
	v_max_f32_e32 v154, v154, v165
	v_min_f32_e32 v165, v155, v164
	v_max_f32_e32 v155, v155, v164
	v_min_f32_e32 v164, v156, v165
	v_max_f32_e32 v156, v156, v165
	v_min_f32_e32 v165, v157, v164
	v_max_f32_e32 v157, v157, v164
	v_min_f32_e32 v164, v158, v165
	v_max_f32_e32 v158, v158, v165
	v_min_f32_e32 v165, v159, v164
	v_max_f32_e32 v159, v159, v164
	v_min_f32_e32 v164, v160, v165
	v_max_f32_e32 v160, v160, v165
	v_min_f32_e32 v165, v161, v164
	v_max_f32_e32 v161, v161, v164
	v_min_f32_e32 v164, v162, v165
	v_max_f32_e32 v162, v162, v165
	v_max_f32_e32 v163, v163, v164
	v_add_f32_e32 v164, v100, v9
	v_and_or_b32 v164, v164, s18, 4
	v_min_f32_e32 v165, v152, v164
	v_max_f32_e32 v152, v152, v164
	v_min_f32_e32 v164, v153, v165
	v_max_f32_e32 v153, v153, v165
	v_min_f32_e32 v165, v154, v164
	v_max_f32_e32 v154, v154, v164
	v_min_f32_e32 v164, v155, v165
	v_max_f32_e32 v155, v155, v165
	v_min_f32_e32 v165, v156, v164
	v_max_f32_e32 v156, v156, v164
	v_min_f32_e32 v164, v157, v165
	v_max_f32_e32 v157, v157, v165
	v_min_f32_e32 v165, v158, v164
	v_max_f32_e32 v158, v158, v164
	v_min_f32_e32 v164, v159, v165
	v_max_f32_e32 v159, v159, v165
	v_min_f32_e32 v165, v160, v164
	v_max_f32_e32 v160, v160, v164
	v_min_f32_e32 v164, v161, v165
	v_max_f32_e32 v161, v161, v165
	v_min_f32_e32 v165, v162, v164
	v_max_f32_e32 v162, v162, v164
	v_max_f32_e32 v163, v163, v165
	v_add_f32_e32 v164, v100, v12
	v_and_or_b32 v164, v164, s18, 5
	v_min_f32_e32 v165, v153, v164
	v_max_f32_e32 v153, v153, v164
	v_min_f32_e32 v164, v154, v165
	v_max_f32_e32 v154, v154, v165
	v_min_f32_e32 v165, v155, v164
	v_max_f32_e32 v155, v155, v164
	v_min_f32_e32 v164, v156, v165
	v_max_f32_e32 v156, v156, v165
	v_min_f32_e32 v165, v157, v164
	v_max_f32_e32 v157, v157, v164
	v_min_f32_e32 v164, v158, v165
	v_max_f32_e32 v158, v158, v165
	v_min_f32_e32 v165, v159, v164
; DEV void ce(float& a, float& b) { float hi = fmaxf(a, b), lo = fminf(a, b); a = hi; b = lo; }
; DEV void phase_peer_score(const Params& p, int layer, int M, char* smem) {
;     ...
; #pragma unroll
;     for (int i = 0; i < 16; i++)
; #pragma unroll
;       for (int j = 0; j < 16; j++)
;         if ((i + 1) * (j + 1) <= 16) {
;           float v = L0[i] + L1[j];
;           v = __uint_as_float((__float_as_uint(v) & ~255u) | (unsigned)(i * 16 + j));
; #pragma unroll
;           for (int t = 0; t < 16; t++)
;             if (t >= (i + 1) * (j + 1) - 1) ce(R[t], v);
;         }
	v_max_f32_e32 v159, v159, v164
	v_min_f32_e32 v164, v160, v165
	v_max_f32_e32 v160, v160, v165
	v_min_f32_e32 v165, v161, v164
	v_max_f32_e32 v161, v161, v164
	v_min_f32_e32 v164, v162, v165
	v_max_f32_e32 v162, v162, v165
	v_max_f32_e32 v163, v163, v164
	v_add_f32_e32 v164, v100, v11
	v_and_or_b32 v164, v164, s18, 6
	v_min_f32_e32 v165, v154, v164
	v_max_f32_e32 v154, v154, v164
	v_min_f32_e32 v164, v155, v165
	v_max_f32_e32 v155, v155, v165
	v_min_f32_e32 v165, v156, v164
	v_max_f32_e32 v156, v156, v164
	v_min_f32_e32 v164, v157, v165
	v_max_f32_e32 v157, v157, v165
	v_min_f32_e32 v165, v158, v164
	v_max_f32_e32 v158, v158, v164
	v_min_f32_e32 v164, v159, v165
	v_max_f32_e32 v159, v159, v165
	v_min_f32_e32 v165, v160, v164
	v_max_f32_e32 v160, v160, v164
	v_min_f32_e32 v164, v161, v165
	v_max_f32_e32 v161, v161, v165
	v_min_f32_e32 v165, v162, v164
	v_max_f32_e32 v162, v162, v164
	v_max_f32_e32 v163, v163, v165
	v_add_f32_e32 v164, v100, v10
	v_and_or_b32 v164, v164, s18, 7
	v_min_f32_e32 v165, v155, v164
	v_max_f32_e32 v155, v155, v164
	v_min_f32_e32 v164, v156, v165
	v_max_f32_e32 v156, v156, v165
	v_min_f32_e32 v165, v157, v164
	v_max_f32_e32 v157, v157, v164
	v_min_f32_e32 v164, v158, v165
	v_max_f32_e32 v158, v158, v165
	v_min_f32_e32 v165, v159, v164
	v_max_f32_e32 v159, v159, v164
	v_min_f32_e32 v164, v160, v165
	v_max_f32_e32 v160, v160, v165
	v_min_f32_e32 v165, v161, v164
	v_max_f32_e32 v161, v161, v164
	v_min_f32_e32 v164, v162, v165
	v_max_f32_e32 v162, v162, v165
	v_max_f32_e32 v163, v163, v164
	v_add_f32_e32 v164, v100, v20
	v_and_or_b32 v164, v164, s18, 8
	v_min_f32_e32 v165, v156, v164
	v_max_f32_e32 v156, v156, v164
	v_min_f32_e32 v164, v157, v165
	v_max_f32_e32 v157, v157, v165
	v_min_f32_e32 v165, v158, v164
	v_max_f32_e32 v158, v158, v164
	v_min_f32_e32 v164, v159, v165
	v_max_f32_e32 v159, v159, v165
	v_min_f32_e32 v165, v160, v164
	v_max_f32_e32 v160, v160, v164
	v_min_f32_e32 v164, v161, v165
	v_max_f32_e32 v161, v161, v165
	v_min_f32_e32 v165, v162, v164
	v_max_f32_e32 v162, v162, v164
	v_max_f32_e32 v163, v163, v165
	v_add_f32_e32 v164, v100, v17
	v_and_or_b32 v164, v164, s18, 9
	v_min_f32_e32 v165, v157, v164
	v_max_f32_e32 v157, v157, v164
	v_min_f32_e32 v164, v158, v165
	v_max_f32_e32 v158, v158, v165
	v_min_f32_e32 v165, v159, v164
	v_max_f32_e32 v159, v159, v164
	v_min_f32_e32 v164, v160, v165
	v_max_f32_e32 v160, v160, v165
	v_min_f32_e32 v165, v161, v164
	v_max_f32_e32 v161, v161, v164
	v_min_f32_e32 v164, v162, v165
	v_max_f32_e32 v162, v162, v165
	v_max_f32_e32 v163, v163, v164
	v_add_f32_e32 v164, v100, v16
	v_and_or_b32 v164, v164, s18, 10
	v_min_f32_e32 v165, v158, v164
	v_max_f32_e32 v158, v158, v164
	v_min_f32_e32 v164, v159, v165
	v_max_f32_e32 v159, v159, v165
	v_min_f32_e32 v165, v160, v164
	v_max_f32_e32 v160, v160, v164
	v_min_f32_e32 v164, v161, v165
	v_max_f32_e32 v161, v161, v165
	v_min_f32_e32 v165, v162, v164
	v_max_f32_e32 v162, v162, v164
	v_max_f32_e32 v163, v163, v165
	v_add_f32_e32 v164, v100, v15
	v_and_or_b32 v164, v164, s18, 11
	v_min_f32_e32 v165, v159, v164
	v_max_f32_e32 v159, v159, v164
	v_min_f32_e32 v164, v160, v165
	v_max_f32_e32 v160, v160, v165
	v_min_f32_e32 v165, v161, v164
	v_max_f32_e32 v161, v161, v164
	v_min_f32_e32 v164, v162, v165
	v_max_f32_e32 v162, v162, v165
	v_max_f32_e32 v163, v163, v164
	v_add_f32_e32 v164, v100, v14
	v_and_or_b32 v164, v164, s18, 12
	v_min_f32_e32 v165, v160, v164
	v_max_f32_e32 v160, v160, v164
	v_min_f32_e32 v164, v161, v165
	v_max_f32_e32 v161, v161, v165
	v_min_f32_e32 v165, v162, v164
	v_max_f32_e32 v162, v162, v164
	v_max_f32_e32 v163, v163, v165
	v_add_f32_e32 v164, v100, v13
	v_and_or_b32 v164, v164, s18, 13
	v_min_f32_e32 v165, v161, v164
	v_max_f32_e32 v161, v161, v164
	v_min_f32_e32 v164, v162, v165
	v_max_f32_e32 v162, v162, v165
	v_max_f32_e32 v163, v163, v164
	v_add_f32_e32 v164, v100, v6
	v_and_or_b32 v164, v164, s18, 14
	v_min_f32_e32 v165, v162, v164
	v_max_f32_e32 v162, v162, v164
	v_max_f32_e32 v163, v163, v165
	v_add_f32_e32 v164, v100, v5
	v_and_or_b32 v164, v164, s18, 15
	v_max_f32_e32 v163, v163, v164
	v_add_f32_e32 v164, v91, v2
	v_and_or_b32 v164, v164, s18, 16
	v_min_f32_e32 v165, v149, v164
	v_max_f32_e32 v149, v149, v164
	v_min_f32_e32 v164, v150, v165
	v_max_f32_e32 v150, v150, v165
	v_min_f32_e32 v165, v151, v164
	v_max_f32_e32 v151, v151, v164
	v_min_f32_e32 v164, v152, v165
	v_max_f32_e32 v152, v152, v165
	v_min_f32_e32 v165, v153, v164
	v_max_f32_e32 v153, v153, v164
	v_min_f32_e32 v164, v154, v165
	v_max_f32_e32 v154, v154, v165
	v_min_f32_e32 v165, v155, v164
	v_max_f32_e32 v155, v155, v164
	v_min_f32_e32 v164, v156, v165
	v_max_f32_e32 v156, v156, v165
	v_min_f32_e32 v165, v157, v164
	v_max_f32_e32 v157, v157, v164
	v_min_f32_e32 v164, v158, v165
	v_max_f32_e32 v158, v158, v165
	v_min_f32_e32 v165, v159, v164
	v_max_f32_e32 v159, v159, v164
	v_min_f32_e32 v164, v160, v165
	v_max_f32_e32 v160, v160, v165
	v_min_f32_e32 v165, v161, v164
	v_max_f32_e32 v161, v161, v164
	v_min_f32_e32 v164, v162, v165
	v_max_f32_e32 v162, v162, v165
	v_max_f32_e32 v163, v163, v164
	v_add_f32_e32 v164, v91, v4
	v_and_or_b32 v164, v164, s18, 17
	v_min_f32_e32 v165, v151, v164
	v_max_f32_e32 v151, v151, v164
	v_min_f32_e32 v164, v152, v165
	v_max_f32_e32 v152, v152, v165
	v_min_f32_e32 v165, v153, v164
	v_max_f32_e32 v153, v153, v164
	v_min_f32_e32 v164, v154, v165
	v_max_f32_e32 v154, v154, v165
	v_min_f32_e32 v165, v155, v164
	v_max_f32_e32 v155, v155, v164
	v_min_f32_e32 v164, v156, v165
	v_max_f32_e32 v156, v156, v165
	v_min_f32_e32 v165, v157, v164
	v_max_f32_e32 v157, v157, v164
	v_min_f32_e32 v164, v158, v165
; DEV void ce(float& a, float& b) { float hi = fmaxf(a, b), lo = fminf(a, b); a = hi; b = lo; }
; DEV void phase_peer_score(const Params& p, int layer, int M, char* smem) {
;     ...
; #pragma unroll
;     for (int i = 0; i < 16; i++)
; #pragma unroll
;       for (int j = 0; j < 16; j++)
;         if ((i + 1) * (j + 1) <= 16) {
;           float v = L0[i] + L1[j];
;           v = __uint_as_float((__float_as_uint(v) & ~255u) | (unsigned)(i * 16 + j));
; #pragma unroll
;           for (int t = 0; t < 16; t++)
;             if (t >= (i + 1) * (j + 1) - 1) ce(R[t], v);
;         }
	v_max_f32_e32 v158, v158, v165
	v_min_f32_e32 v165, v159, v164
	v_max_f32_e32 v159, v159, v164
	v_min_f32_e32 v164, v160, v165
	v_max_f32_e32 v160, v160, v165
	v_min_f32_e32 v165, v161, v164
	v_max_f32_e32 v161, v161, v164
	v_min_f32_e32 v164, v162, v165
	v_max_f32_e32 v162, v162, v165
	v_max_f32_e32 v163, v163, v164
	v_add_f32_e32 v164, v91, v7
	v_and_or_b32 v164, v164, s18, 18
	v_min_f32_e32 v165, v153, v164
	v_max_f32_e32 v153, v153, v164
	v_min_f32_e32 v164, v154, v165
	v_max_f32_e32 v154, v154, v165
	v_min_f32_e32 v165, v155, v164
	v_max_f32_e32 v155, v155, v164
	v_min_f32_e32 v164, v156, v165
	v_max_f32_e32 v156, v156, v165
	v_min_f32_e32 v165, v157, v164
	v_max_f32_e32 v157, v157, v164
	v_min_f32_e32 v164, v158, v165
	v_max_f32_e32 v158, v158, v165
	v_min_f32_e32 v165, v159, v164
	v_max_f32_e32 v159, v159, v164
	v_min_f32_e32 v164, v160, v165
	v_max_f32_e32 v160, v160, v165
	v_min_f32_e32 v165, v161, v164
	v_max_f32_e32 v161, v161, v164
	v_min_f32_e32 v164, v162, v165
	v_max_f32_e32 v162, v162, v165
	v_max_f32_e32 v163, v163, v164
	v_add_f32_e32 v164, v91, v8
	v_and_or_b32 v164, v164, s18, 19
	v_min_f32_e32 v165, v155, v164
	v_max_f32_e32 v155, v155, v164
	v_min_f32_e32 v164, v156, v165
	v_max_f32_e32 v156, v156, v165
	v_min_f32_e32 v165, v157, v164
	v_max_f32_e32 v157, v157, v164
	v_min_f32_e32 v164, v158, v165
	v_max_f32_e32 v158, v158, v165
	v_min_f32_e32 v165, v159, v164
	v_max_f32_e32 v159, v159, v164
	v_min_f32_e32 v164, v160, v165
	v_max_f32_e32 v160, v160, v165
	v_min_f32_e32 v165, v161, v164
	v_max_f32_e32 v161, v161, v164
	v_min_f32_e32 v164, v162, v165
	v_max_f32_e32 v162, v162, v165
	v_max_f32_e32 v163, v163, v164
	v_add_f32_e32 v164, v91, v9
	v_and_or_b32 v164, v164, s18, 20
	v_min_f32_e32 v165, v157, v164
	v_max_f32_e32 v157, v157, v164
	v_min_f32_e32 v164, v158, v165
	v_max_f32_e32 v158, v158, v165
	v_min_f32_e32 v165, v159, v164
	v_max_f32_e32 v159, v159, v164
	v_min_f32_e32 v164, v160, v165
	v_max_f32_e32 v160, v160, v165
	v_min_f32_e32 v165, v161, v164
	v_max_f32_e32 v161, v161, v164
	v_min_f32_e32 v164, v162, v165
	v_max_f32_e32 v162, v162, v165
	v_max_f32_e32 v163, v163, v164
	v_add_f32_e32 v164, v91, v12
	v_and_or_b32 v164, v164, s18, 21
	v_min_f32_e32 v165, v159, v164
	v_max_f32_e32 v159, v159, v164
	v_min_f32_e32 v164, v160, v165
	v_max_f32_e32 v160, v160, v165
	v_min_f32_e32 v165, v161, v164
	v_max_f32_e32 v161, v161, v164
	v_min_f32_e32 v164, v162, v165
	v_max_f32_e32 v162, v162, v165
	v_max_f32_e32 v163, v163, v164
	v_add_f32_e32 v164, v91, v11
	v_and_or_b32 v164, v164, s18, 22
	v_min_f32_e32 v165, v161, v164
	v_max_f32_e32 v161, v161, v164
	v_min_f32_e32 v164, v162, v165
	v_max_f32_e32 v162, v162, v165
	v_max_f32_e32 v163, v163, v164
	v_add_f32_e32 v164, v91, v10
	v_and_or_b32 v164, v164, s18, 23
	v_max_f32_e32 v163, v163, v164
	v_add_f32_e32 v164, v87, v2
	v_and_or_b32 v164, v164, s18, 32
	v_min_f32_e32 v165, v150, v164
	v_max_f32_e32 v150, v150, v164
	v_min_f32_e32 v164, v151, v165
	v_max_f32_e32 v151, v151, v165
	v_min_f32_e32 v165, v152, v164
	v_max_f32_e32 v152, v152, v164
	v_min_f32_e32 v164, v153, v165
	v_max_f32_e32 v153, v153, v165
	v_min_f32_e32 v165, v154, v164
	v_max_f32_e32 v154, v154, v164
	v_min_f32_e32 v164, v155, v165
	v_max_f32_e32 v155, v155, v165
	v_min_f32_e32 v165, v156, v164
	v_max_f32_e32 v156, v156, v164
	v_min_f32_e32 v164, v157, v165
	v_max_f32_e32 v157, v157, v165
	v_min_f32_e32 v165, v158, v164
	v_max_f32_e32 v158, v158, v164
	v_min_f32_e32 v164, v159, v165
	v_max_f32_e32 v159, v159, v165
	v_min_f32_e32 v165, v160, v164
	v_max_f32_e32 v160, v160, v164
	v_min_f32_e32 v164, v161, v165
	v_max_f32_e32 v161, v161, v165
	v_min_f32_e32 v165, v162, v164
	v_max_f32_e32 v162, v162, v164
	v_max_f32_e32 v163, v163, v165
	v_add_f32_e32 v164, v87, v4
	v_and_or_b32 v164, v164, s18, 33
	v_min_f32_e32 v165, v153, v164
	v_max_f32_e32 v153, v153, v164
	v_min_f32_e32 v164, v154, v165
	v_max_f32_e32 v154, v154, v165
	v_min_f32_e32 v165, v155, v164
	v_max_f32_e32 v155, v155, v164
	v_min_f32_e32 v164, v156, v165
	v_max_f32_e32 v156, v156, v165
	v_min_f32_e32 v165, v157, v164
	v_max_f32_e32 v157, v157, v164
	v_min_f32_e32 v164, v158, v165
	v_max_f32_e32 v158, v158, v165
	v_min_f32_e32 v165, v159, v164
	v_max_f32_e32 v159, v159, v164
	v_min_f32_e32 v164, v160, v165
	v_max_f32_e32 v160, v160, v165
	v_min_f32_e32 v165, v161, v164
	v_max_f32_e32 v161, v161, v164
	v_min_f32_e32 v164, v162, v165
	v_max_f32_e32 v162, v162, v165
	v_max_f32_e32 v163, v163, v164
	v_add_f32_e32 v164, v87, v7
	v_and_or_b32 v164, v164, s18, 34
	v_min_f32_e32 v165, v156, v164
	v_max_f32_e32 v156, v156, v164
	v_min_f32_e32 v164, v157, v165
	v_max_f32_e32 v157, v157, v165
	v_min_f32_e32 v165, v158, v164
	v_max_f32_e32 v158, v158, v164
	v_min_f32_e32 v164, v159, v165
	v_max_f32_e32 v159, v159, v165
	v_min_f32_e32 v165, v160, v164
	v_max_f32_e32 v160, v160, v164
	v_min_f32_e32 v164, v161, v165
	v_max_f32_e32 v161, v161, v165
	v_min_f32_e32 v165, v162, v164
	v_max_f32_e32 v162, v162, v164
	v_max_f32_e32 v163, v163, v165
	v_add_f32_e32 v164, v87, v8
	v_and_or_b32 v164, v164, s18, 35
	v_min_f32_e32 v165, v159, v164
	v_max_f32_e32 v159, v159, v164
	v_min_f32_e32 v164, v160, v165
	v_max_f32_e32 v160, v160, v165
	v_min_f32_e32 v165, v161, v164
	v_max_f32_e32 v161, v161, v164
	v_min_f32_e32 v164, v162, v165
	v_max_f32_e32 v162, v162, v165
	v_max_f32_e32 v163, v163, v164
	v_add_f32_e32 v164, v87, v9
	v_and_or_b32 v164, v164, s18, 36
	v_min_f32_e32 v165, v162, v164
	v_max_f32_e32 v162, v162, v164
	v_max_f32_e32 v163, v163, v165
	v_add_f32_e32 v164, v83, v2
	v_and_or_b32 v164, v164, s18, 48
	v_min_f32_e32 v165, v151, v164
	v_max_f32_e32 v151, v151, v164
; DEV void ce(float& a, float& b) { float hi = fmaxf(a, b), lo = fminf(a, b); a = hi; b = lo; }
; DEV void phase_peer_score(const Params& p, int layer, int M, char* smem) {
;     ...
; #pragma unroll
;     for (int i = 0; i < 16; i++)
; #pragma unroll
;       for (int j = 0; j < 16; j++)
;         if ((i + 1) * (j + 1) <= 16) {
;           float v = L0[i] + L1[j];
;           v = __uint_as_float((__float_as_uint(v) & ~255u) | (unsigned)(i * 16 + j));
; #pragma unroll
;           for (int t = 0; t < 16; t++)
;             if (t >= (i + 1) * (j + 1) - 1) ce(R[t], v);
;         }
	v_min_f32_e32 v164, v152, v165
	v_max_f32_e32 v152, v152, v165
	v_min_f32_e32 v165, v153, v164
	v_max_f32_e32 v153, v153, v164
	v_min_f32_e32 v164, v154, v165
	v_max_f32_e32 v154, v154, v165
	v_min_f32_e32 v165, v155, v164
	v_max_f32_e32 v155, v155, v164
	v_min_f32_e32 v164, v156, v165
	v_max_f32_e32 v156, v156, v165
	v_min_f32_e32 v165, v157, v164
	v_max_f32_e32 v157, v157, v164
	v_min_f32_e32 v164, v158, v165
	v_max_f32_e32 v158, v158, v165
	v_min_f32_e32 v165, v159, v164
	v_max_f32_e32 v159, v159, v164
	v_min_f32_e32 v164, v160, v165
	v_max_f32_e32 v160, v160, v165
	v_min_f32_e32 v165, v161, v164
	v_max_f32_e32 v161, v161, v164
	v_min_f32_e32 v164, v162, v165
	v_max_f32_e32 v162, v162, v165
	v_max_f32_e32 v163, v163, v164
	v_add_f32_e32 v164, v83, v4
	v_and_or_b32 v164, v164, s18, 49
	v_min_f32_e32 v165, v155, v164
	v_max_f32_e32 v155, v155, v164
	v_min_f32_e32 v164, v156, v165
	v_max_f32_e32 v156, v156, v165
	v_min_f32_e32 v165, v157, v164
	v_max_f32_e32 v157, v157, v164
	v_min_f32_e32 v164, v158, v165
	v_max_f32_e32 v158, v158, v165
	v_min_f32_e32 v165, v159, v164
	v_max_f32_e32 v159, v159, v164
	v_min_f32_e32 v164, v160, v165
	v_max_f32_e32 v160, v160, v165
	v_min_f32_e32 v165, v161, v164
	v_max_f32_e32 v161, v161, v164
	v_min_f32_e32 v164, v162, v165
	v_max_f32_e32 v162, v162, v165
	v_max_f32_e32 v163, v163, v164
	v_add_f32_e32 v164, v83, v7
	v_and_or_b32 v164, v164, s18, 50
	v_min_f32_e32 v165, v159, v164
	v_max_f32_e32 v159, v159, v164
	v_min_f32_e32 v164, v160, v165
	v_max_f32_e32 v160, v160, v165
	v_min_f32_e32 v165, v161, v164
	v_max_f32_e32 v161, v161, v164
	v_min_f32_e32 v164, v162, v165
	v_max_f32_e32 v162, v162, v165
	v_max_f32_e32 v163, v163, v164
	v_add_f32_e32 v164, v83, v8
	v_and_or_b32 v164, v164, s18, 51
	v_max_f32_e32 v163, v163, v164
	v_add_f32_e32 v164, v79, v2
	v_and_or_b32 v164, v164, s18, 64
	v_min_f32_e32 v165, v152, v164
	v_max_f32_e32 v152, v152, v164
	v_min_f32_e32 v164, v153, v165
	v_max_f32_e32 v153, v153, v165
	v_min_f32_e32 v165, v154, v164
	v_max_f32_e32 v154, v154, v164
	v_min_f32_e32 v164, v155, v165
	v_max_f32_e32 v155, v155, v165
	v_min_f32_e32 v165, v156, v164
	v_max_f32_e32 v156, v156, v164
	v_min_f32_e32 v164, v157, v165
	v_max_f32_e32 v157, v157, v165
	v_min_f32_e32 v165, v158, v164
	v_max_f32_e32 v158, v158, v164
	v_min_f32_e32 v164, v159, v165
	v_max_f32_e32 v159, v159, v165
	v_min_f32_e32 v165, v160, v164
	v_max_f32_e32 v160, v160, v164
	v_min_f32_e32 v164, v161, v165
	v_max_f32_e32 v161, v161, v165
	v_min_f32_e32 v165, v162, v164
	v_max_f32_e32 v162, v162, v164
	v_max_f32_e32 v163, v163, v165
	v_add_f32_e32 v164, v79, v4
	v_and_b32_e32 v164, 0xffffff00, v164
	v_or_b32_e32 v164, 0x41, v164
	v_min_f32_e32 v165, v157, v164
	v_max_f32_e32 v157, v157, v164
	v_min_f32_e32 v164, v158, v165
	v_max_f32_e32 v158, v158, v165
	v_min_f32_e32 v165, v159, v164
	v_max_f32_e32 v159, v159, v164
	v_min_f32_e32 v164, v160, v165
	v_max_f32_e32 v160, v160, v165
	v_min_f32_e32 v165, v161, v164
	v_max_f32_e32 v161, v161, v164
	v_min_f32_e32 v164, v162, v165
	v_max_f32_e32 v162, v162, v165
	v_max_f32_e32 v163, v163, v164
	v_add_f32_e32 v164, v79, v7
	v_and_b32_e32 v164, 0xffffff00, v164
	v_or_b32_e32 v164, 0x42, v164
	v_min_f32_e32 v165, v162, v164
	v_max_f32_e32 v162, v162, v164
	v_max_f32_e32 v163, v163, v165
	v_add_f32_e32 v164, v75, v2
	v_and_b32_e32 v164, 0xffffff00, v164
	v_or_b32_e32 v164, 0x50, v164
	v_min_f32_e32 v165, v153, v164
	v_max_f32_e32 v153, v153, v164
	v_min_f32_e32 v164, v154, v165
	v_max_f32_e32 v154, v154, v165
	v_min_f32_e32 v165, v155, v164
	v_max_f32_e32 v155, v155, v164
	v_min_f32_e32 v164, v156, v165
	v_max_f32_e32 v156, v156, v165
	v_min_f32_e32 v165, v157, v164
	v_max_f32_e32 v157, v157, v164
	v_min_f32_e32 v164, v158, v165
	v_max_f32_e32 v158, v158, v165
	v_min_f32_e32 v165, v159, v164
	v_max_f32_e32 v159, v159, v164
	v_min_f32_e32 v164, v160, v165
	v_max_f32_e32 v160, v160, v165
	v_min_f32_e32 v165, v161, v164
	v_max_f32_e32 v161, v161, v164
	v_min_f32_e32 v164, v162, v165
	v_max_f32_e32 v162, v162, v165
	v_max_f32_e32 v163, v163, v164
	v_add_f32_e32 v164, v75, v4
	v_and_b32_e32 v164, 0xffffff00, v164
	v_or_b32_e32 v164, 0x51, v164
	v_min_f32_e32 v165, v159, v164
	v_max_f32_e32 v159, v159, v164
	v_min_f32_e32 v164, v160, v165
	v_max_f32_e32 v160, v160, v165
	v_min_f32_e32 v165, v161, v164
	v_max_f32_e32 v161, v161, v164
	v_min_f32_e32 v164, v162, v165
	v_max_f32_e32 v162, v162, v165
	v_max_f32_e32 v163, v163, v164
	v_add_f32_e32 v164, v71, v2
	v_and_b32_e32 v164, 0xffffff00, v164
	v_or_b32_e32 v164, 0x60, v164
	v_min_f32_e32 v165, v154, v164
	v_max_f32_e32 v154, v154, v164
	v_min_f32_e32 v164, v155, v165
	v_max_f32_e32 v155, v155, v165
	v_min_f32_e32 v165, v156, v164
	v_max_f32_e32 v156, v156, v164
	v_min_f32_e32 v164, v157, v165
	v_max_f32_e32 v157, v157, v165
	v_min_f32_e32 v165, v158, v164
	v_max_f32_e32 v158, v158, v164
	v_min_f32_e32 v164, v159, v165
	v_max_f32_e32 v159, v159, v165
	v_min_f32_e32 v165, v160, v164
	v_max_f32_e32 v160, v160, v164
	v_min_f32_e32 v164, v161, v165
	v_max_f32_e32 v161, v161, v165
	v_min_f32_e32 v165, v162, v164
	v_max_f32_e32 v162, v162, v164
	v_max_f32_e32 v163, v163, v165
	v_add_f32_e32 v164, v71, v4
	v_and_b32_e32 v164, 0xffffff00, v164
	v_or_b32_e32 v164, 0x61, v164
	v_min_f32_e32 v165, v161, v164
	v_max_f32_e32 v161, v161, v164
	v_min_f32_e32 v164, v162, v165
	v_max_f32_e32 v162, v162, v165
	v_max_f32_e32 v163, v163, v164
	v_add_f32_e32 v164, v63, v2
	v_and_b32_e32 v164, 0xffffff00, v164
	v_or_b32_e32 v164, 0x70, v164
	v_min_f32_e32 v165, v155, v164
	v_max_f32_e32 v155, v155, v164
	v_min_f32_e32 v164, v156, v165
	v_max_f32_e32 v156, v156, v165
; DEV void ce(float& a, float& b) { float hi = fmaxf(a, b), lo = fminf(a, b); a = hi; b = lo; }
; DEV void phase_peer_score(const Params& p, int layer, int M, char* smem) {
;     ...
;     for (int i = 0; i < 16; i++)
; #pragma unroll
;       for (int j = 0; j < 16; j++)
;         if ((i + 1) * (j + 1) <= 16) {
;           float v = L0[i] + L1[j];
;           v = __uint_as_float((__float_as_uint(v) & ~255u) | (unsigned)(i * 16 + j));
; #pragma unroll
;           for (int t = 0; t < 16; t++)
;             if (t >= (i + 1) * (j + 1) - 1) ce(R[t], v);
;         }
;     unsigned char* tab = (unsigned char*)smem + 73728 + (w * 16 + l15) * 32;
; #pragma unroll
;     for (int i = 0; i < 16; i++) { tab[i] = (unsigned char)(__float_as_uint(L0[i]) & 127u); tab[16 + i] = (unsigned char)(__float_as_uint(L1[i]) & 127u); }
;     float ev[16]; float sum = 0.f;
; #pragma unroll
;     for (int t = 0; t < 16; t++) { ev[t] = __expf(R[t] - R[0]); sum += ev[t]; }
;     const float inv = 1.f / sum;
;     int eid[16];
; #pragma unroll
;     for (int t = 0; t < 16; t++) {
;       unsigned code = __float_as_uint(R[t]) & 255u;
;       eid[t] = (int)tab[code >> 4] * 128 + (int)tab[16 + (code & 15u)];
	v_min_f32_e32 v165, v157, v164
	v_max_f32_e32 v157, v157, v164
	v_min_f32_e32 v164, v158, v165
	v_max_f32_e32 v158, v158, v165
	v_min_f32_e32 v165, v159, v164
	v_max_f32_e32 v159, v159, v164
	v_min_f32_e32 v164, v160, v165
	v_max_f32_e32 v160, v160, v165
	v_min_f32_e32 v165, v161, v164
	v_max_f32_e32 v161, v161, v164
	v_min_f32_e32 v164, v162, v165
	v_max_f32_e32 v162, v162, v165
	v_max_f32_e32 v163, v163, v164
	v_add_f32_e32 v164, v63, v4
	v_and_b32_e32 v164, 0xffffff00, v164
	v_or_b32_e32 v164, 0x71, v164
	v_max_f32_e32 v163, v163, v164
	v_add_f32_e32 v164, v67, v2
	v_and_b32_e32 v164, 0xffffff00, v164
	v_or_b32_e32 v164, 0x80, v164
	v_min_f32_e32 v165, v156, v164
	v_max_f32_e32 v156, v156, v164
	v_min_f32_e32 v164, v157, v165
	v_max_f32_e32 v157, v157, v165
	v_min_f32_e32 v165, v158, v164
	v_max_f32_e32 v158, v158, v164
	v_min_f32_e32 v164, v159, v165
	v_max_f32_e32 v159, v159, v165
	v_min_f32_e32 v165, v160, v164
	v_max_f32_e32 v160, v160, v164
	v_min_f32_e32 v164, v161, v165
	v_max_f32_e32 v161, v161, v165
	v_min_f32_e32 v165, v162, v164
	v_max_f32_e32 v162, v162, v164
	v_max_f32_e32 v163, v163, v165
	v_add_f32_e32 v164, v59, v2
	v_and_b32_e32 v164, 0xffffff00, v164
	v_or_b32_e32 v164, 0x90, v164
	v_min_f32_e32 v165, v157, v164
	v_max_f32_e32 v157, v157, v164
	v_min_f32_e32 v164, v158, v165
	v_max_f32_e32 v158, v158, v165
	v_min_f32_e32 v165, v159, v164
	v_max_f32_e32 v159, v159, v164
	v_min_f32_e32 v164, v160, v165
	v_max_f32_e32 v160, v160, v165
	v_min_f32_e32 v165, v161, v164
	v_max_f32_e32 v161, v161, v164
	v_min_f32_e32 v164, v162, v165
	v_max_f32_e32 v162, v162, v165
	v_max_f32_e32 v163, v163, v164
	v_add_f32_e32 v164, v55, v2
	v_and_b32_e32 v164, 0xffffff00, v164
	v_or_b32_e32 v164, 0xa0, v164
	v_min_f32_e32 v165, v158, v164
	v_max_f32_e32 v158, v158, v164
	v_min_f32_e32 v164, v159, v165
	v_max_f32_e32 v159, v159, v165
	v_min_f32_e32 v165, v160, v164
	v_max_f32_e32 v160, v160, v164
	v_min_f32_e32 v164, v161, v165
	v_max_f32_e32 v161, v161, v165
	v_min_f32_e32 v165, v162, v164
	v_max_f32_e32 v162, v162, v164
	v_max_f32_e32 v163, v163, v165
	v_add_f32_e32 v164, v47, v2
	v_and_b32_e32 v164, 0xffffff00, v164
	v_or_b32_e32 v164, 0xb0, v164
	v_min_f32_e32 v165, v159, v164
	v_max_f32_e32 v159, v159, v164
	v_min_f32_e32 v164, v160, v165
	v_max_f32_e32 v160, v160, v165
	v_min_f32_e32 v165, v161, v164
	v_max_f32_e32 v161, v161, v164
	v_min_f32_e32 v164, v162, v165
	v_max_f32_e32 v162, v162, v165
	v_max_f32_e32 v163, v163, v164
	v_add_f32_e32 v164, v51, v2
	v_and_b32_e32 v164, 0xffffff00, v164
	v_or_b32_e32 v164, 0xc0, v164
	v_min_f32_e32 v165, v160, v164
	v_max_f32_e32 v160, v160, v164
	v_min_f32_e32 v164, v161, v165
	v_max_f32_e32 v161, v161, v165
	v_min_f32_e32 v165, v162, v164
	v_max_f32_e32 v162, v162, v164
	v_max_f32_e32 v163, v163, v165
	v_add_f32_e32 v164, v39, v2
	v_and_b32_e32 v164, 0xffffff00, v164
	v_or_b32_e32 v164, 0xd0, v164
	v_min_f32_e32 v165, v161, v164
	v_max_f32_e32 v161, v161, v164
	v_min_f32_e32 v164, v162, v165
	v_max_f32_e32 v162, v162, v165
	v_max_f32_e32 v163, v163, v164
	v_add_f32_e32 v164, v43, v2
	v_and_b32_e32 v164, 0xffffff00, v164
	v_or_b32_e32 v164, 0xe0, v164
	v_min_f32_e32 v165, v162, v164
	v_max_f32_e32 v162, v162, v164
	v_max_f32_e32 v163, v163, v165
	v_add_f32_e32 v164, v0, v2
	v_and_b32_e32 v164, 0xffffff00, v164
	v_or_b32_e32 v164, 0xf0, v164
	v_max_f32_e32 v163, v163, v164
.Lmed3_ok_bb_637:
	s_lshl_b32 s18, s16, 3
	s_andn2_b32 s18, s18, 63
	v_add_u32_e32 v18, s18, v117
	s_movk_i32 s18, 0xff00
	v_sub_f32_e32 v5, v149, v148
	v_mul_f32_e32 v5, 0x3fb8aa3b, v5
	v_exp_f32_e32 v101, v5
	v_sub_f32_e32 v5, v150, v148
	v_mul_f32_e32 v5, 0x3fb8aa3b, v5
	v_exp_f32_e32 v104, v5
	v_sub_f32_e32 v5, v151, v148
	v_mul_f32_e32 v5, 0x3fb8aa3b, v5
	v_exp_f32_e32 v105, v5
	v_sub_f32_e32 v5, v152, v148
	v_mul_f32_e32 v5, 0x3fb8aa3b, v5
	v_exp_f32_e32 v102, v5
	v_sub_f32_e32 v5, v153, v148
	v_mul_f32_e32 v5, 0x3fb8aa3b, v5
	v_exp_f32_e32 v103, v5
	v_sub_f32_e32 v5, v154, v148
	v_mul_f32_e32 v5, 0x3fb8aa3b, v5
	v_exp_f32_e32 v110, v5
	v_sub_f32_e32 v5, v155, v148
	v_sub_f32_e32 v3, v148, v148
	v_mul_f32_e32 v5, 0x3fb8aa3b, v5
	v_mul_f32_e32 v3, 0x3fb8aa3b, v3
	v_exp_f32_e32 v111, v5
	v_sub_f32_e32 v5, v156, v148
	v_exp_f32_e32 v100, v3
	v_mul_f32_e32 v5, 0x3fb8aa3b, v5
	v_exp_f32_e32 v112, v5
	v_sub_f32_e32 v5, v157, v148
	v_mul_f32_e32 v5, 0x3fb8aa3b, v5
	v_exp_f32_e32 v113, v5
	v_sub_f32_e32 v5, v158, v148
	v_add_f32_e32 v3, 0, v100
	v_mul_f32_e32 v5, 0x3fb8aa3b, v5
	v_add_f32_e32 v3, v3, v101
	v_exp_f32_e32 v114, v5
	v_sub_f32_e32 v5, v159, v148
	v_add_f32_e32 v3, v3, v104
	v_mul_f32_e32 v5, 0x3fb8aa3b, v5
	v_add_f32_e32 v3, v3, v105
	v_exp_f32_e32 v115, v5
	v_sub_f32_e32 v5, v160, v148
	v_add_f32_e32 v3, v3, v102
	v_mul_f32_e32 v5, 0x3fb8aa3b, v5
	v_add_f32_e32 v3, v3, v103
	v_exp_f32_e32 v106, v5
	v_sub_f32_e32 v5, v161, v148
	v_add_f32_e32 v3, v3, v110
	v_mul_f32_e32 v5, 0x3fb8aa3b, v5
	v_add_f32_e32 v3, v3, v111
	v_exp_f32_e32 v107, v5
	v_sub_f32_e32 v5, v162, v148
	v_add_f32_e32 v3, v3, v112
	v_mul_f32_e32 v5, 0x3fb8aa3b, v5
	v_add_f32_e32 v3, v3, v113
	v_exp_f32_e32 v108, v5
	v_sub_f32_e32 v5, v163, v148
	v_add_f32_e32 v3, v3, v114
	v_mul_f32_e32 v5, 0x3fb8aa3b, v5
	v_add_f32_e32 v3, v3, v115
	v_exp_f32_e32 v109, v5
	v_add_f32_e32 v3, v3, v106
	v_add_f32_e32 v3, v3, v107
	v_add_f32_e32 v3, v3, v108
	v_add_f32_e32 v3, v3, v109
	v_div_scale_f32 v5, s[18:19], v3, v3, 1.0
	v_rcp_f32_e32 v6, v5
	v_ashrrev_i32_e32 v19, 31, v18
	s_lshl_b32 s52, s17, 6
	s_mov_b32 s17, 0x10000
	v_fma_f32 v17, -v5, v6, 1.0
	v_fmac_f32_e32 v6, v17, v6
	v_div_scale_f32 v17, vcc, 1.0, v3, 1.0
	v_mul_f32_e32 v20, v17, v6
	v_fma_f32 v21, -v5, v20, v17
	v_fmac_f32_e32 v20, v21, v6
	v_fma_f32 v5, -v5, v20, v17
	v_div_fmas_f32 v5, v5, v6, v20
	v_div_fixup_f32 v116, v5, v3, 1.0
	v_bfe_u32 v3, v163, 4, 4
	v_and_b32_e32 v2, 15, v163
	v_and_b32_e32 v17, 15, v155
	v_add_u32_e32 v3, v138, v3
	v_add_u32_e32 v2, v138, v2
	v_add_u32_e32 v17, v138, v17
	ds_read_u8 v3, v3
	ds_read_u8 v17, v17 offset:16
	ds_read_u8 v2, v2 offset:16
	v_and_b32_e32 v6, 15, v160
	v_add_u32_e32 v6, v138, v6
	ds_read_u8 v6, v6 offset:16
	v_lshlrev_b64 v[120:121], 9, v[18:19]
	s_waitcnt lgkmcnt(1)
; DEV void phase_peer_score(const Params& p, int layer, int M, char* smem) {
;     ...
;     int eid[16];
; #pragma unroll
;     for (int t = 0; t < 16; t++) {
;       unsigned code = __float_as_uint(R[t]) & 255u;
;       eid[t] = (int)tab[code >> 4] * 128 + (int)tab[16 + (code & 15u)];
;     }
	v_lshl_add_u32 v5, v3, 7, v2
	v_bfe_u32 v2, v162, 4, 4
	v_and_b32_e32 v3, 15, v162
	v_add_u32_e32 v2, v138, v2
	v_add_u32_e32 v3, v138, v3
	ds_read_u8 v2, v2
	ds_read_u8 v3, v3 offset:16
	v_lshl_add_u64 v[18:19], s[2:3], 0, v[120:121]
	v_lshl_add_u64 v[118:119], v[18:19], 0, s[52:53]
	v_lshl_add_u64 v[120:121], s[0:1], 0, v[120:121]
	v_lshl_add_u64 v[120:121], v[120:121], 0, s[52:53]
	s_waitcnt lgkmcnt(0)
	v_lshl_add_u32 v4, v2, 7, v3
	v_bfe_u32 v2, v161, 4, 4
	v_and_b32_e32 v3, 15, v161
	v_add_u32_e32 v2, v138, v2
	v_add_u32_e32 v3, v138, v3
	ds_read_u8 v2, v2
	ds_read_u8 v3, v3 offset:16
	v_and_b32_e32 v7, 15, v159
	v_add_u32_e32 v7, v138, v7
	ds_read_u8 v7, v7 offset:16
	s_waitcnt lgkmcnt(1)
	v_lshl_add_u32 v3, v2, 7, v3
	v_bfe_u32 v2, v160, 4, 4
	v_add_u32_e32 v2, v138, v2
	ds_read_u8 v2, v2
	s_waitcnt lgkmcnt(0)
	v_lshl_add_u32 v2, v2, 7, v6
	v_bfe_u32 v6, v159, 4, 4
	v_add_u32_e32 v6, v138, v6
	ds_read_u8 v6, v6
	s_waitcnt lgkmcnt(0)
	v_lshl_add_u32 v9, v6, 7, v7
	v_bfe_u32 v6, v158, 4, 4
	v_and_b32_e32 v7, 15, v158
	v_add_u32_e32 v6, v138, v6
	v_add_u32_e32 v7, v138, v7
	ds_read_u8 v6, v6
	ds_read_u8 v7, v7 offset:16
	s_waitcnt lgkmcnt(0)
	v_lshl_add_u32 v8, v6, 7, v7
	v_bfe_u32 v6, v157, 4, 4
	v_and_b32_e32 v7, 15, v157
	v_add_u32_e32 v6, v138, v6
	v_add_u32_e32 v7, v138, v7
	ds_read_u8 v6, v6
	ds_read_u8 v7, v7 offset:16
	s_waitcnt lgkmcnt(0)
	v_lshl_add_u32 v7, v6, 7, v7
	v_bfe_u32 v6, v156, 4, 4
	v_and_b32_e32 v13, 15, v156
	v_add_u32_e32 v6, v138, v6
	v_add_u32_e32 v13, v138, v13
	ds_read_u8 v6, v6
	ds_read_u8 v13, v13 offset:16
	s_waitcnt lgkmcnt(0)
	v_lshl_add_u32 v6, v6, 7, v13
	v_bfe_u32 v13, v155, 4, 4
	v_add_u32_e32 v13, v138, v13
	ds_read_u8 v13, v13
	s_waitcnt lgkmcnt(0)
	v_lshl_add_u32 v13, v13, 7, v17
	v_bfe_u32 v17, v154, 4, 4
	v_and_b32_e32 v12, 15, v154
	v_add_u32_e32 v17, v138, v17
	v_add_u32_e32 v12, v138, v12
	ds_read_u8 v17, v17
	ds_read_u8 v12, v12 offset:16
	s_waitcnt lgkmcnt(0)
	v_lshl_add_u32 v12, v17, 7, v12
	v_bfe_u32 v17, v153, 4, 4
	v_and_b32_e32 v11, 15, v153
	v_add_u32_e32 v17, v138, v17
	v_add_u32_e32 v11, v138, v11
	ds_read_u8 v17, v17
	ds_read_u8 v11, v11 offset:16
	s_waitcnt lgkmcnt(0)
	v_lshl_add_u32 v11, v17, 7, v11
	v_bfe_u32 v17, v152, 4, 4
	v_and_b32_e32 v10, 15, v152
	v_add_u32_e32 v17, v138, v17
	v_add_u32_e32 v10, v138, v10
	ds_read_u8 v17, v17
	ds_read_u8 v10, v10 offset:16
	s_waitcnt lgkmcnt(0)
	v_lshl_add_u32 v10, v17, 7, v10
	v_bfe_u32 v17, v151, 4, 4
	v_and_b32_e32 v16, 15, v151
	v_add_u32_e32 v17, v138, v17
	v_add_u32_e32 v16, v138, v16
	ds_read_u8 v17, v17
	ds_read_u8 v16, v16 offset:16
	s_waitcnt lgkmcnt(0)
	v_lshl_add_u32 v17, v17, 7, v16
	v_bfe_u32 v16, v150, 4, 4
	v_and_b32_e32 v15, 15, v150
	v_add_u32_e32 v16, v138, v16
	v_add_u32_e32 v15, v138, v15
	ds_read_u8 v16, v16
	ds_read_u8 v15, v15 offset:16
	s_waitcnt lgkmcnt(0)
	v_lshl_add_u32 v16, v16, 7, v15
	v_bfe_u32 v15, v149, 4, 4
	v_and_b32_e32 v14, 15, v149
	v_add_u32_e32 v15, v138, v15
	v_add_u32_e32 v14, v138, v14
	ds_read_u8 v15, v15
	ds_read_u8 v14, v14 offset:16
	s_waitcnt lgkmcnt(0)
	v_lshl_add_u32 v15, v15, 7, v14
	v_bfe_u32 v14, v148, 4, 4
	v_and_b32_e32 v0, 15, v148
	v_add_u32_e32 v14, v138, v14
	v_add_u32_e32 v0, v138, v0
	ds_read_u8 v14, v14
	ds_read_u8 v0, v0 offset:16
	s_waitcnt lgkmcnt(0)
; DEV void phase_peer_score(const Params& p, int layer, int M, char* smem) {
;     ...
;     if (quad == 0) {
;       int* eo = EIDX + (size_t)m * 128 + h * 16;
;       float* go = GATE + (size_t)m * 128 + h * 16;
;       float* uo = go + (size_t)MT * 128;
;       float us[16], vs[16];
; #pragma unroll
;       for (int t = 0; t < 16; t++) { us[t] = USC[eid[t]]; vs[t] = USC[16384 + eid[t]]; }
; #pragma unroll
;       for (int t = 0; t < 16; t += 4) {
;         *(int4*)(eo + t) = make_int4(eid[t], eid[t + 1], eid[t + 2], eid[t + 3]);
;         *(float4*)(go + t) = make_float4(ev[t] * inv * vs[t], ev[t + 1] * inv * vs[t + 1], ev[t + 2] * inv * vs[t + 2], ev[t + 3] * inv * vs[t + 3]);
;         *(float4*)(uo + t) = make_float4(us[t], us[t + 1], us[t + 2], us[t + 3]);
;       }
;     }
	v_lshl_add_u32 v14, v14, 7, v0
	v_lshlrev_b32_e32 v0, 2, v14
	v_lshl_add_u64 v[20:21], s[6:7], 0, v[0:1]
	v_add_co_u32_e32 v20, vcc, s17, v20
	global_load_dword v18, v0, s[6:7]
	s_nop 0
	v_addc_co_u32_e32 v21, vcc, 0, v21, vcc
	global_load_dword v122, v[20:21], off
	v_lshlrev_b32_e32 v0, 2, v15
	v_lshl_add_u64 v[20:21], s[6:7], 0, v[0:1]
	v_add_co_u32_e32 v20, vcc, s17, v20
	global_load_dword v19, v0, s[6:7]
	s_nop 0
	v_addc_co_u32_e32 v21, vcc, 0, v21, vcc
	global_load_dword v123, v[20:21], off
	v_lshlrev_b32_e32 v0, 2, v16
	v_lshl_add_u64 v[22:23], s[6:7], 0, v[0:1]
	v_add_co_u32_e32 v22, vcc, s17, v22
	global_load_dword v20, v0, s[6:7]
	s_nop 0
	v_addc_co_u32_e32 v23, vcc, 0, v23, vcc
	global_load_dword v126, v[22:23], off
	v_lshlrev_b32_e32 v0, 2, v17
	v_lshl_add_u64 v[22:23], s[6:7], 0, v[0:1]
	v_add_co_u32_e32 v22, vcc, s17, v22
	global_load_dword v21, v0, s[6:7]
	s_nop 0
	v_addc_co_u32_e32 v23, vcc, 0, v23, vcc
	global_load_dword v127, v[22:23], off
	v_lshlrev_b32_e32 v0, 2, v10
	v_lshl_add_u64 v[24:25], s[6:7], 0, v[0:1]
	v_add_co_u32_e32 v24, vcc, s17, v24
	global_load_dword v22, v0, s[6:7]
	s_nop 0
	v_addc_co_u32_e32 v25, vcc, 0, v25, vcc
	global_load_dword v124, v[24:25], off
	v_lshlrev_b32_e32 v0, 2, v11
	v_lshl_add_u64 v[24:25], s[6:7], 0, v[0:1]
	v_add_co_u32_e32 v24, vcc, s17, v24
	global_load_dword v23, v0, s[6:7]
	s_nop 0
	v_addc_co_u32_e32 v25, vcc, 0, v25, vcc
	global_load_dword v125, v[24:25], off
	v_lshlrev_b32_e32 v0, 2, v12
	v_lshl_add_u64 v[26:27], s[6:7], 0, v[0:1]
	v_add_co_u32_e32 v26, vcc, s17, v26
	global_load_dword v24, v0, s[6:7]
	s_nop 0
	v_addc_co_u32_e32 v27, vcc, 0, v27, vcc
	global_load_dword v128, v[26:27], off
	v_lshlrev_b32_e32 v0, 2, v13
	v_lshl_add_u64 v[26:27], s[6:7], 0, v[0:1]
	v_add_co_u32_e32 v26, vcc, s17, v26
	global_load_dword v25, v0, s[6:7]
	s_nop 0
	v_addc_co_u32_e32 v27, vcc, 0, v27, vcc
	global_load_dword v129, v[26:27], off
	v_lshlrev_b32_e32 v0, 2, v6
	v_lshl_add_u64 v[28:29], s[6:7], 0, v[0:1]
	v_add_co_u32_e32 v28, vcc, s17, v28
	global_load_dword v26, v0, s[6:7]
	s_nop 0
	v_addc_co_u32_e32 v29, vcc, 0, v29, vcc
	global_load_dword v130, v[28:29], off
	v_lshlrev_b32_e32 v0, 2, v7
	v_lshl_add_u64 v[28:29], s[6:7], 0, v[0:1]
	v_add_co_u32_e32 v28, vcc, s17, v28
	global_load_dword v27, v0, s[6:7]
	s_nop 0
	v_addc_co_u32_e32 v29, vcc, 0, v29, vcc
	global_load_dword v131, v[28:29], off
	v_lshlrev_b32_e32 v0, 2, v8
	v_lshl_add_u64 v[30:31], s[6:7], 0, v[0:1]
	v_add_co_u32_e32 v30, vcc, s17, v30
	global_load_dword v28, v0, s[6:7]
	s_nop 0
	v_addc_co_u32_e32 v31, vcc, 0, v31, vcc
	global_load_dword v132, v[30:31], off
	v_lshlrev_b32_e32 v0, 2, v9
	v_lshl_add_u64 v[30:31], s[6:7], 0, v[0:1]
	v_add_co_u32_e32 v30, vcc, s17, v30
	global_load_dword v29, v0, s[6:7]
	s_nop 0
	v_addc_co_u32_e32 v31, vcc, 0, v31, vcc
	global_load_dword v133, v[30:31], off
	v_lshlrev_b32_e32 v0, 2, v2
	v_lshl_add_u64 v[32:33], s[6:7], 0, v[0:1]
	v_add_co_u32_e32 v32, vcc, s17, v32
	global_load_dword v30, v0, s[6:7]
	s_nop 0
	v_addc_co_u32_e32 v33, vcc, 0, v33, vcc
	global_load_dword v134, v[32:33], off
	v_lshlrev_b32_e32 v0, 2, v3
	v_lshl_add_u64 v[32:33], s[6:7], 0, v[0:1]
	v_add_co_u32_e32 v32, vcc, s17, v32
	global_load_dword v31, v0, s[6:7]
	s_nop 0
	v_addc_co_u32_e32 v33, vcc, 0, v33, vcc
	global_load_dword v135, v[32:33], off
	v_lshlrev_b32_e32 v0, 2, v4
	v_lshl_add_u64 v[136:137], s[6:7], 0, v[0:1]
	v_add_co_u32_e32 v136, vcc, s17, v136
	global_load_dword v32, v0, s[6:7]
	s_nop 0
	v_addc_co_u32_e32 v137, vcc, 0, v137, vcc
	global_load_dword v136, v[136:137], off
	v_lshlrev_b32_e32 v0, 2, v5
	v_lshl_add_u64 v[140:141], s[6:7], 0, v[0:1]
	v_add_co_u32_e32 v140, vcc, s17, v140
	global_load_dword v33, v0, s[6:7]
	s_nop 0
	v_addc_co_u32_e32 v141, vcc, 0, v141, vcc
	global_load_dword v137, v[140:141], off
	s_mov_b32 s17, 0x840000
	global_store_dwordx4 v[120:121], v[14:17], off
	s_nop 1
	v_pk_mul_f32 v[14:15], v[100:101], v[116:117] op_sel_hi:[1,0]
	v_pk_mul_f32 v[16:17], v[104:105], v[116:117] op_sel_hi:[1,0]
	s_waitcnt vmcnt(29)
	v_pk_mul_f32 v[14:15], v[14:15], v[122:123]
	s_waitcnt vmcnt(25)
	v_pk_mul_f32 v[16:17], v[16:17], v[126:127]
	global_store_dwordx4 v[118:119], v[14:17], off
	s_nop 1
	v_add_co_u32_e32 v14, vcc, s17, v118
	s_nop 1
	v_addc_co_u32_e32 v15, vcc, 0, v119, vcc
	global_store_dwordx4 v[14:15], v[18:21], off
	global_store_dwordx4 v[120:121], v[10:13], off offset:16
	s_nop 1
	v_pk_mul_f32 v[10:11], v[102:103], v[116:117] op_sel_hi:[1,0]
	v_pk_mul_f32 v[12:13], v[110:111], v[116:117] op_sel_hi:[1,0]
	s_waitcnt vmcnt(24)
	v_pk_mul_f32 v[10:11], v[10:11], v[124:125]
	s_waitcnt vmcnt(20)
	v_pk_mul_f32 v[12:13], v[12:13], v[128:129]
	global_store_dwordx4 v[118:119], v[10:13], off offset:16
	global_store_dwordx4 v[14:15], v[22:25], off offset:16
	global_store_dwordx4 v[120:121], v[6:9], off offset:32
	s_nop 1
	v_pk_mul_f32 v[6:7], v[112:113], v[116:117] op_sel_hi:[1,0]
	v_pk_mul_f32 v[8:9], v[114:115], v[116:117] op_sel_hi:[1,0]
	s_waitcnt vmcnt(19)
	v_pk_mul_f32 v[6:7], v[6:7], v[130:131]
	s_waitcnt vmcnt(15)
	v_pk_mul_f32 v[8:9], v[8:9], v[132:133]
	global_store_dwordx4 v[118:119], v[6:9], off offset:32
	global_store_dwordx4 v[14:15], v[26:29], off offset:32
	global_store_dwordx4 v[120:121], v[2:5], off offset:48
	s_nop 1
	v_pk_mul_f32 v[2:3], v[106:107], v[116:117] op_sel_hi:[1,0]
	v_pk_mul_f32 v[4:5], v[108:109], v[116:117] op_sel_hi:[1,0]
	s_waitcnt vmcnt(14)
	v_pk_mul_f32 v[2:3], v[2:3], v[134:135]
	s_waitcnt vmcnt(10)
	v_pk_mul_f32 v[4:5], v[4:5], v[136:137]
	global_store_dwordx4 v[118:119], v[2:5], off offset:48
	global_store_dwordx4 v[14:15], v[30:33], off offset:48
	s_branch .LBB0_627
